# plus prologue transpose loads batched and automatic load hoisting in ATT/RB/RA code
# speedup vs baseline: 1.0347x; 1.0149x over previous
.LBB0_43:
	s_andn2_b64 vcc, exec, s[18:19]
	s_cbranch_vccnz .LBB0_9
	s_lshr_b32 s4, s36, 7
	v_cvt_f32_u32_e32 v2, s4
	s_sub_i32 s15, 0, s4
	s_sub_i32 s5, s23, s42
	s_abs_i32 s14, s5
	v_rcp_iflag_f32_e32 v2, v2
	s_ashr_i32 s6, s5, 31
	v_mov_b32_e32 v13, v9
	v_mul_f32_e32 v2, 0x4f7ffffe, v2
	v_cvt_u32_f32_e32 v2, v2
	s_nop 0
	v_readfirstlane_b32 s16, v2
	s_mul_i32 s15, s15, s16
	s_mul_hi_u32 s15, s16, s15
	s_add_i32 s16, s16, s15
	s_mul_hi_u32 s15, s14, s16
	s_mul_i32 s16, s15, s4
	s_sub_i32 s14, s14, s16
	s_add_i32 s17, s15, 1
	s_sub_i32 s16, s14, s4
	s_cmp_ge_u32 s14, s4
	s_cselect_b32 s15, s17, s15
	s_cselect_b32 s14, s16, s14
	s_add_i32 s16, s15, 1
	s_cmp_ge_u32 s14, s4
	s_cselect_b32 s14, s16, s15
	s_xor_b32 s14, s14, s6
	s_sub_i32 s6, s14, s6
	s_mul_i32 s4, s6, s4
	s_sub_i32 s4, s5, s4
	s_lshl_b32 s16, s4, 7
	s_ashr_i32 s17, s16, 31
	s_lshl_b32 s14, s6, 7
	s_lshl_b64 s[4:5], s[16:17], 2
	s_add_u32 s4, s8, s4
	v_add_u32_e32 v16, s14, v7
	s_addc_u32 s5, s9, s5
	v_lshl_add_u64 v[14:15], s[4:5], 0, v[12:13]
	v_mad_u64_u32 v[2:3], s[4:5], v16, s36, 0
	v_ashrrev_i32_e32 v17, 31, v16
	v_mov_b32_e32 v4, v3
	v_mad_u64_u32 v[4:5], s[4:5], v17, s36, v[4:5]
	v_mov_b32_e32 v3, v4
	v_lshl_add_u64 v[2:3], v[2:3], 2, v[14:15]
	s_lshl_b32 s4, s36, 6
	s_mov_b32 s5, 0
	global_load_dwordx4 v[28:31], v[2:3], off
	v_lshl_add_u64 v[2:3], v[2:3], 0, s[4:5]
	global_load_dwordx4 v[32:35], v[2:3], off
	v_lshl_add_u64 v[2:3], v[2:3], 0, s[4:5]
	global_load_dwordx4 v[36:39], v[2:3], off
	v_lshl_add_u64 v[2:3], v[2:3], 0, s[4:5]
	global_load_dwordx4 v[40:43], v[2:3], off
	v_lshl_add_u64 v[2:3], v[2:3], 0, s[4:5]
	global_load_dwordx4 v[44:47], v[2:3], off
	v_lshl_add_u64 v[2:3], v[2:3], 0, s[4:5]
	global_load_dwordx4 v[48:51], v[2:3], off
	v_lshl_add_u64 v[2:3], v[2:3], 0, s[4:5]
	global_load_dwordx4 v[52:55], v[2:3], off
	v_lshl_add_u64 v[2:3], v[2:3], 0, s[4:5]
	global_load_dwordx4 v[56:59], v[2:3], off
	v_lshl_add_u64 v[18:19], v[16:17], 2, s[12:13]
	s_cmp_eq_u64 s[12:13], 0
	s_cbranch_scc1 .Ltr_nogain
	global_load_dword v60, v[18:19], off
	global_load_dword v61, v[18:19], off offset:64
	global_load_dword v62, v[18:19], off offset:128
	global_load_dword v63, v[18:19], off offset:192
	global_load_dword v64, v[18:19], off offset:256
	global_load_dword v65, v[18:19], off offset:320
	global_load_dword v66, v[18:19], off offset:384
	global_load_dword v67, v[18:19], off offset:448
	s_branch .Ltr_gain_done
.Ltr_nogain:
	v_mov_b32_e32 v60, 1.0
	v_mov_b32_e32 v61, 1.0
	v_mov_b32_e32 v62, 1.0
	v_mov_b32_e32 v63, 1.0
	v_mov_b32_e32 v64, 1.0
	v_mov_b32_e32 v65, 1.0
	v_mov_b32_e32 v66, 1.0
	v_mov_b32_e32 v67, 1.0
.Ltr_gain_done:
	s_waitcnt vmcnt(7)
	v_mul_f32_e32 v28, v28, v60
	v_mul_f32_e32 v29, v29, v60
	v_mul_f32_e32 v30, v30, v60
	v_mul_f32_e32 v31, v31, v60
	ds_write2_b32 v21, v28, v29 offset1:1
	ds_write2_b32 v21, v30, v31 offset0:2 offset1:3
	s_waitcnt vmcnt(6)
	v_mul_f32_e32 v32, v32, v61
	v_mul_f32_e32 v33, v33, v61
	v_mul_f32_e32 v34, v34, v61
	v_mul_f32_e32 v35, v35, v61
	v_add_u32_e32 v8, 0x2040, v21
	ds_write2_b32 v8, v32, v33 offset1:1
	ds_write2_b32 v8, v34, v35 offset0:2 offset1:3
	s_waitcnt vmcnt(5)
	v_mul_f32_e32 v36, v36, v62
	v_mul_f32_e32 v37, v37, v62
	v_mul_f32_e32 v38, v38, v62
	v_mul_f32_e32 v39, v39, v62
	v_add_u32_e32 v8, 0x4080, v21
	ds_write2_b32 v8, v36, v37 offset1:1
	ds_write2_b32 v8, v38, v39 offset0:2 offset1:3
	s_waitcnt vmcnt(4)
	v_mul_f32_e32 v40, v40, v63
	v_mul_f32_e32 v41, v41, v63
	v_mul_f32_e32 v42, v42, v63
	v_mul_f32_e32 v43, v43, v63
	v_add_u32_e32 v8, 0x60c0, v21
	ds_write2_b32 v8, v40, v41 offset1:1
	ds_write2_b32 v8, v42, v43 offset0:2 offset1:3
	s_waitcnt vmcnt(3)
	v_mul_f32_e32 v44, v44, v64
	v_mul_f32_e32 v45, v45, v64
	v_mul_f32_e32 v46, v46, v64
	v_mul_f32_e32 v47, v47, v64
	v_add_u32_e32 v8, 0x8100, v21
	ds_write2_b32 v8, v44, v45 offset1:1
	ds_write2_b32 v8, v46, v47 offset0:2 offset1:3
	s_waitcnt vmcnt(2)
	v_mul_f32_e32 v48, v48, v65
	v_mul_f32_e32 v49, v49, v65
	v_mul_f32_e32 v50, v50, v65
	v_mul_f32_e32 v51, v51, v65
	v_add_u32_e32 v8, 0xa140, v21
	ds_write2_b32 v8, v48, v49 offset1:1
	ds_write2_b32 v8, v50, v51 offset0:2 offset1:3
	s_waitcnt vmcnt(1)
	v_mul_f32_e32 v52, v52, v66
	v_mul_f32_e32 v53, v53, v66
	v_mul_f32_e32 v54, v54, v66
	v_mul_f32_e32 v55, v55, v66
	v_add_u32_e32 v8, 0xc180, v21
	ds_write2_b32 v8, v52, v53 offset1:1
	ds_write2_b32 v8, v54, v55 offset0:2 offset1:3
	s_waitcnt vmcnt(0)
	v_mul_f32_e32 v56, v56, v67
	v_mul_f32_e32 v57, v57, v67
	v_mul_f32_e32 v58, v58, v67
	v_mul_f32_e32 v59, v59, v67
	v_add_u32_e32 v8, 0xe1c0, v21
	ds_write2_b32 v8, v56, v57 offset1:1
	ds_write2_b32 v8, v58, v59 offset0:2 offset1:3
	v_add_u32_e32 v13, 0x400, v20
	v_add_u32_e32 v19, 0x800, v20
	v_add_u32_e32 v22, 0xc00, v20
	s_waitcnt lgkmcnt(0)
	s_barrier
	ds_read2_b32 v[16:17], v20 offset1:129
	ds_read2_b32 v[14:15], v13 offset0:2 offset1:131
	ds_read2_b32 v[4:5], v19 offset0:4 offset1:133
	ds_read2_b32 v[2:3], v22 offset0:6 offset1:135
	v_add_u32_e32 v18, s16, v11
	s_cmp_lg_u32 s43, 0
	s_cselect_b64 s[16:17], -1, 0
	s_cmp_eq_u32 s43, 0
	v_mov_b32_e32 v8, v18
	s_cbranch_scc1 .LBB0_62
	v_mul_hi_i32 v8, v18, s37
	v_lshrrev_b32_e32 v23, 31, v8
	v_ashrrev_i32_e32 v8, 9, v8
	v_add_u32_e32 v8, v8, v23
	v_mul_i32_i24_e32 v23, 0xc00, v8
	v_sub_u32_e32 v23, v18, v23
	v_lshlrev_b32_e32 v24, 1, v23
	v_and_b32_e32 v24, 0xffffff00, v24
	v_lshl_add_u32 v8, v8, 7, v24
	v_and_or_b32 v8, v23, s38, v8

.LBB0_399:
	s_or_b64 exec, exec, s[4:5]
	s_and_b32 s2, s12, -2
	s_cmp_eq_u32 s13, 0
	s_cselect_b64 vcc, -1, 0
	s_lshl_b32 s4, s2, 4
	v_or_b32_e32 v47, s14, v75
	v_lshl_add_u32 v46, v79, 4, 0
	v_or_b32_e32 v48, s4, v75
	v_mad_u64_u32 v[100:101], s[6:7], v48, s88, v[46:47]
	s_or_b32 s6, s4, 16
	s_add_i32 s3, s2, 2
	v_or_b32_e32 v48, s6, v75
	s_lshl_b32 s12, s3, 4
	v_mad_u64_u32 v[98:99], s[8:9], v48, s88, v[46:47]
	v_or_b32_e32 v48, s12, v75
	s_add_i32 s20, s4, 48
	s_add_i32 s49, s2, 4
	v_mad_u64_u32 v[96:97], s[8:9], v48, s88, v[46:47]
	v_or_b32_e32 v48, s20, v75
	s_lshl_b32 s28, s49, 4
	v_mad_u64_u32 v[94:95], s[8:9], v48, s88, v[46:47]
	v_or_b32_e32 v48, s28, v75
	s_add_i32 s38, s4, 0x50
	v_mad_u64_u32 v[92:93], s[8:9], v48, s88, v[46:47]
	v_or_b32_e32 v48, s38, v75
	v_mad_u64_u32 v[90:91], s[8:9], v48, s88, v[46:47]
	s_add_i32 s88, s2, 6
	s_lshl_b32 s54, s88, 4
	s_movk_i32 s5, 0x90
	v_or_b32_e32 v48, s54, v75
	s_add_i32 s62, s4, 0x70
	s_add_i32 s89, s2, 8
	v_mad_u64_u32 v[88:89], s[8:9], v48, s5, v[46:47]
	v_or_b32_e32 v48, s62, v75
	s_lshl_b32 s70, s89, 4
	v_mad_u64_u32 v[86:87], s[8:9], v48, s5, v[46:47]
	v_or_b32_e32 v48, s70, v75
	s_add_i32 s78, s4, 0x90
	v_mad_u64_u32 v[84:85], s[8:9], v48, s5, v[46:47]
	v_or_b32_e32 v48, s78, v75
	v_mad_u64_u32 v[82:83], s[8:9], v48, s5, v[46:47]
	v_max_i32_e32 v46, 0x80, v47
	v_lshlrev_b32_e32 v48, 2, v79
	v_cndmask_b32_e32 v46, v47, v46, vcc
	v_add_u32_e32 v47, 0x80, v47
	v_or_b32_e32 v49, s4, v48
	v_cmp_lt_i32_e32 vcc, v49, v46
	v_cmp_gt_i32_e64 s[4:5], v49, v47
	v_or_b32_e32 v50, 1, v49
	s_or_b64 s[40:41], vcc, s[4:5]
	v_cmp_lt_i32_e32 vcc, v50, v46
	v_cmp_ge_i32_e64 s[4:5], v49, v47
	v_or_b32_e32 v50, 2, v49
	v_writelane_b32 v255, s40, 0
	s_or_b64 s[42:43], vcc, s[4:5]
	v_cmp_lt_i32_e32 vcc, v50, v46
	v_cmp_gt_i32_e64 s[4:5], v50, v47
	v_writelane_b32 v255, s41, 1
	s_or_b64 s[4:5], vcc, s[4:5]
	v_writelane_b32 v255, s4, 2
	v_or_b32_e32 v49, 3, v49
	v_cmp_lt_i32_e32 vcc, v49, v46
	v_writelane_b32 v255, s5, 3
	v_cmp_gt_i32_e64 s[4:5], v49, v47
	s_or_b64 s[4:5], vcc, s[4:5]
	v_or_b32_e32 v49, s6, v48
	v_writelane_b32 v255, s4, 4
	v_cmp_lt_i32_e32 vcc, v49, v46
	v_or_b32_e32 v50, 1, v49
	v_writelane_b32 v255, s5, 5
	v_cmp_gt_i32_e64 s[4:5], v49, v47
	s_or_b64 s[4:5], vcc, s[4:5]
	v_cmp_lt_i32_e32 vcc, v50, v46
	v_writelane_b32 v255, s4, 6
	v_cmp_ge_i32_e64 s[6:7], v49, v47
	v_or_b32_e32 v50, 2, v49
	v_writelane_b32 v255, s5, 7
	s_or_b64 s[6:7], vcc, s[6:7]
	v_cmp_lt_i32_e32 vcc, v50, v46
	v_cmp_gt_i32_e64 s[8:9], v50, v47
	v_or_b32_e32 v49, 3, v49
	v_writelane_b32 v255, s6, 8
	s_or_b64 s[4:5], vcc, s[8:9]
	v_cmp_lt_i32_e32 vcc, v49, v46
	v_cmp_gt_i32_e64 s[10:11], v49, v47
	v_or_b32_e32 v49, s12, v48
	v_writelane_b32 v255, s7, 9
	s_or_b64 s[44:45], vcc, s[10:11]
	v_cmp_lt_i32_e32 vcc, v49, v46
	v_cmp_gt_i32_e64 s[12:13], v49, v47
	v_or_b32_e32 v50, 1, v49
	v_writelane_b32 v255, s4, 10
	s_or_b64 s[8:9], vcc, s[12:13]
	v_cmp_lt_i32_e32 vcc, v50, v46
	v_cmp_ge_i32_e64 s[14:15], v49, v47
	v_or_b32_e32 v50, 2, v49
	v_writelane_b32 v255, s5, 11
	s_or_b64 s[12:13], vcc, s[14:15]
	v_cmp_lt_i32_e32 vcc, v50, v46
	v_cmp_gt_i32_e64 s[16:17], v50, v47
	v_or_b32_e32 v49, 3, v49
	v_writelane_b32 v255, s8, 12
	s_or_b64 s[10:11], vcc, s[16:17]
	v_cmp_lt_i32_e32 vcc, v49, v46
	v_cmp_gt_i32_e64 s[18:19], v49, v47
	v_or_b32_e32 v49, s20, v48
	v_writelane_b32 v255, s9, 13
	s_or_b64 s[8:9], vcc, s[18:19]
	v_cmp_lt_i32_e32 vcc, v49, v46
	v_cmp_gt_i32_e64 s[20:21], v49, v47
	v_or_b32_e32 v50, 1, v49
	s_or_b64 s[20:21], vcc, s[20:21]
	v_cmp_lt_i32_e32 vcc, v50, v46
	v_cmp_ge_i32_e64 s[22:23], v49, v47
	v_or_b32_e32 v50, 2, v49
	s_or_b64 s[18:19], vcc, s[22:23]
	v_cmp_lt_i32_e32 vcc, v50, v46
	v_cmp_gt_i32_e64 s[24:25], v50, v47
	v_or_b32_e32 v49, 3, v49
	s_or_b64 s[16:17], vcc, s[24:25]
	v_cmp_lt_i32_e32 vcc, v49, v46
	v_cmp_gt_i32_e64 s[26:27], v49, v47
	v_or_b32_e32 v49, s28, v48
	s_or_b64 s[14:15], vcc, s[26:27]
	v_cmp_lt_i32_e32 vcc, v49, v46
	v_cmp_gt_i32_e64 s[28:29], v49, v47
	v_or_b32_e32 v50, 1, v49
	s_or_b64 s[28:29], vcc, s[28:29]
	v_cmp_lt_i32_e32 vcc, v50, v46
	v_cmp_ge_i32_e64 s[30:31], v49, v47
	v_or_b32_e32 v50, 2, v49
	s_or_b64 s[24:25], vcc, s[30:31]
	v_cmp_lt_i32_e32 vcc, v50, v46
	v_cmp_gt_i32_e64 s[34:35], v50, v47
	v_or_b32_e32 v49, 3, v49
	s_or_b64 s[22:23], vcc, s[34:35]
	v_cmp_lt_i32_e32 vcc, v49, v46
	v_cmp_gt_i32_e64 s[36:37], v49, v47
	v_or_b32_e32 v49, s38, v48
	s_or_b64 s[26:27], vcc, s[36:37]
	v_cmp_lt_i32_e32 vcc, v49, v46
	v_cmp_gt_i32_e64 s[38:39], v49, v47
	v_or_b32_e32 v50, 1, v49
	s_or_b64 s[38:39], vcc, s[38:39]
	v_cmp_lt_i32_e32 vcc, v50, v46
	v_cmp_ge_i32_e64 s[46:47], v49, v47
	v_or_b32_e32 v50, 2, v49
	s_or_b64 s[30:31], vcc, s[46:47]
	v_cmp_lt_i32_e32 vcc, v50, v46
	v_cmp_gt_i32_e64 s[50:51], v50, v47
	v_or_b32_e32 v49, 3, v49
	s_or_b64 s[34:35], vcc, s[50:51]
	v_cmp_lt_i32_e32 vcc, v49, v46
	v_cmp_gt_i32_e64 s[52:53], v49, v47
	v_or_b32_e32 v49, s54, v48
	s_or_b64 s[36:37], vcc, s[52:53]
	v_cmp_lt_i32_e32 vcc, v49, v46
	v_cmp_gt_i32_e64 s[54:55], v49, v47
	v_or_b32_e32 v50, 1, v49
	s_or_b64 s[54:55], vcc, s[54:55]
	v_cmp_lt_i32_e32 vcc, v50, v46
	v_cmp_ge_i32_e64 s[56:57], v49, v47
	v_or_b32_e32 v50, 2, v49
	s_or_b64 s[46:47], vcc, s[56:57]
	v_cmp_lt_i32_e32 vcc, v50, v46
	v_cmp_gt_i32_e64 s[58:59], v50, v47
	v_or_b32_e32 v49, 3, v49
	s_or_b64 s[50:51], vcc, s[58:59]
	v_cmp_lt_i32_e32 vcc, v49, v46
	v_cmp_gt_i32_e64 s[60:61], v49, v47
	v_or_b32_e32 v49, s62, v48
	s_or_b64 s[52:53], vcc, s[60:61]
	v_cmp_lt_i32_e32 vcc, v49, v46
	v_cmp_gt_i32_e64 s[62:63], v49, v47
	v_or_b32_e32 v50, 1, v49
	s_or_b64 s[62:63], vcc, s[62:63]
	v_cmp_lt_i32_e32 vcc, v50, v46
	v_cmp_ge_i32_e64 s[64:65], v49, v47
	v_or_b32_e32 v50, 2, v49
	s_or_b64 s[56:57], vcc, s[64:65]
	v_cmp_lt_i32_e32 vcc, v50, v46
	v_cmp_gt_i32_e64 s[66:67], v50, v47
	v_or_b32_e32 v49, 3, v49
	s_or_b64 s[58:59], vcc, s[66:67]
	v_cmp_lt_i32_e32 vcc, v49, v46
	v_cmp_gt_i32_e64 s[68:69], v49, v47
	v_or_b32_e32 v49, s70, v48
	s_or_b64 s[60:61], vcc, s[68:69]
	v_cmp_lt_i32_e32 vcc, v49, v46
	v_cmp_gt_i32_e64 s[70:71], v49, v47
	v_or_b32_e32 v50, 1, v49
	v_ashrrev_i32_e32 v3, 31, v2
	s_or_b64 s[70:71], vcc, s[70:71]
	v_cmp_lt_i32_e32 vcc, v50, v46
	v_cmp_ge_i32_e64 s[72:73], v49, v47
	v_or_b32_e32 v50, 2, v49
	s_or_b64 s[64:65], vcc, s[72:73]
	v_cmp_lt_i32_e32 vcc, v50, v46
	v_cmp_gt_i32_e64 s[74:75], v50, v47
	v_or_b32_e32 v49, 3, v49
	v_lshlrev_b64 v[2:3], 11, v[2:3]
	v_lshlrev_b32_e32 v0, 3, v79
	s_or_b64 s[66:67], vcc, s[74:75]
	v_cmp_lt_i32_e32 vcc, v49, v46
	v_cmp_gt_i32_e64 s[76:77], v49, v47
	v_or_b32_e32 v48, s78, v48
	v_lshl_add_u64 v[2:3], s[0:1], 0, v[2:3]
	s_or_b64 s[68:69], vcc, s[76:77]
	v_cmp_lt_i32_e32 vcc, v48, v46
	v_cmp_gt_i32_e64 s[78:79], v48, v47
	v_or_b32_e32 v49, 1, v48
	v_lshl_add_u64 v[2:3], v[2:3], 0, v[0:1]
	s_mov_b64 s[0:1], 0xa000000
	s_or_b64 s[78:79], vcc, s[78:79]
	v_cmp_lt_i32_e32 vcc, v49, v46
	v_cmp_ge_i32_e64 s[80:81], v48, v47
	v_or_b32_e32 v49, 2, v48
	v_lshl_add_u64 v[80:81], v[2:3], 0, s[0:1]
	v_readlane_b32 s0, v254, 14
	s_or_b64 s[76:77], vcc, s[80:81]
	v_cmp_lt_i32_e32 vcc, v49, v46
	v_cmp_gt_i32_e64 s[82:83], v49, v47
	v_or_b32_e32 v48, 3, v48
	v_mov_b32_e32 v79, s0
	s_waitcnt lgkmcnt(0)
	s_barrier
	s_or_b64 s[72:73], vcc, s[82:83]
	v_cmp_lt_i32_e32 vcc, v48, v46
	v_cmp_gt_i32_e64 s[84:85], v48, v47
	v_add_u32_e32 v46, 0, v0
	v_mul_u32_u24_e32 v47, 0x210, v75
	s_lshl_b32 s2, s2, 5
	v_lshlrev_b32_e32 v64, 16, v38
	v_and_b32_e32 v66, 0xffff0000, v38
	v_lshlrev_b32_e32 v65, 16, v39
	v_and_b32_e32 v67, 0xffff0000, v39
	v_lshlrev_b32_e32 v68, 16, v40
	v_and_b32_e32 v70, 0xffff0000, v40
	v_lshlrev_b32_e32 v69, 16, v41
	v_and_b32_e32 v71, 0xffff0000, v41
	ds_read2_b64 v[38:41], v79 offset1:1
	v_add3_u32 v91, v46, s2, v47
	s_lshl_b32 s2, s3, 5
	v_add3_u32 v89, v46, s2, v47
	s_lshl_b32 s2, s49, 5
	v_add3_u32 v87, v46, s2, v47
	s_lshl_b32 s2, s88, 5
	v_readlane_b32 s0, v254, 51
	v_add3_u32 v85, v46, s2, v47
	s_lshl_b32 s2, s89, 5
	v_readlane_b32 s1, v254, 52
	s_or_b64 s[74:75], vcc, s[84:85]
	v_add3_u32 v83, v46, s2, v47
	s_waitcnt lgkmcnt(0)
	v_readfirstlane_b32 s2, v38
	s_lshl_b64 s[0:1], s[0:1], 2
	v_readfirstlane_b32 s3, v39
	s_add_u32 s2, s2, s0
	v_lshlrev_b32_e32 v3, 16, v43
	v_and_b32_e32 v59, 0xffff0000, v43
	v_lshlrev_b32_e32 v60, 16, v44
	v_and_b32_e32 v62, 0xffff0000, v44
	v_lshlrev_b32_e32 v61, 16, v45
	v_and_b32_e32 v63, 0xffff0000, v45
	s_addc_u32 s3, s3, s1
	v_lshlrev_b32_e32 v0, 2, v0
	v_mov_b32_e32 v44, v67
	v_mov_b32_e32 v45, v65
	v_lshlrev_b32_e32 v2, 16, v42
	v_and_b32_e32 v58, 0xffff0000, v42
	v_lshl_add_u64 v[38:39], s[2:3], 0, v[0:1]
	v_mov_b32_e32 v42, v59
	v_mov_b32_e32 v43, v3
	v_pk_mul_f32 v[44:45], v[44:45], v[44:45]
	flat_load_dwordx4 v[46:49], v[38:39] offset:128
	v_pk_fma_f32 v[72:73], v[42:43], v[42:43], v[44:45]
	flat_load_dwordx4 v[42:45], v[38:39]
	flat_load_dwordx4 v[50:53], v[38:39] offset:16
	flat_load_dwordx4 v[54:57], v[38:39] offset:144
	v_mul_f32_e32 v38, v58, v58
	v_mul_f32_e32 v39, v2, v2
	v_fmac_f32_e32 v38, v66, v66
	v_fmac_f32_e32 v39, v64, v64
	v_mov_b32_e32 v104, v18
	v_mov_b32_e32 v105, v20
	v_mov_b32_e32 v20, v19
	v_mov_b32_e32 v18, v70
	v_mov_b32_e32 v19, v68
	v_add_f32_e32 v38, v39, v38
	v_mov_b32_e32 v102, v10
	v_mov_b32_e32 v103, v12
	v_mov_b32_e32 v12, v11
	v_mov_b32_e32 v10, v62
	v_mov_b32_e32 v11, v60
	v_pk_mul_f32 v[18:19], v[18:19], v[18:19]
	v_add_f32_e32 v38, v73, v38
	v_pk_fma_f32 v[10:11], v[10:11], v[10:11], v[18:19]
	v_add_f32_e32 v38, v72, v38
	v_mov_b32_e32 v18, v63
	v_mov_b32_e32 v19, v61
	v_add_f32_e32 v11, v11, v38
	v_add_f32_e32 v10, v10, v11
	s_mov_b32 s2, 0xf800000
	v_readfirstlane_b32 s49, v40
	v_writelane_b32 v255, s12, 14
	s_mov_b32 s94, 0xf149f2ca
	s_mov_b64 s[84:85], s[8:9]
	v_writelane_b32 v255, s13, 15
	v_writelane_b32 v255, s18, 16
	s_mov_b64 s[82:83], s[10:11]
	s_waitcnt vmcnt(0) lgkmcnt(0)
	v_mov_b32_e32 v76, v46
	v_mov_b32_e32 v77, v48
	v_mov_b32_e32 v74, v42
	v_mov_b32_e32 v75, v44
	v_mov_b32_e32 v44, v43
	v_mov_b32_e32 v42, v71
	v_mov_b32_e32 v43, v69
	v_pk_mul_f32 v[42:43], v[42:43], v[42:43]
	v_mov_b32_e32 v48, v47
	v_pk_fma_f32 v[18:19], v[18:19], v[18:19], v[42:43]
	v_writelane_b32 v255, s19, 17
	v_add_f32_e32 v10, v19, v10
	v_add_f32_e32 v10, v18, v10
	ds_bpermute_b32 v11, v109, v10
	v_writelane_b32 v255, s16, 18
	s_waitcnt lgkmcnt(0)
	v_add_f32_e32 v10, v10, v11
	ds_bpermute_b32 v11, v110, v10
	v_writelane_b32 v255, s17, 19
	v_writelane_b32 v255, s70, 20
	s_waitcnt lgkmcnt(0)
	v_add_f32_e32 v10, v10, v11
	v_fmamk_f32 v10, v10, 0x3c800000, v219
	v_cmp_gt_f32_e32 vcc, s2, v10
	v_mul_f32_e32 v11, 0x4f800000, v10
	v_writelane_b32 v255, s71, 21
	v_cndmask_b32_e32 v10, v10, v11, vcc
	v_sqrt_f32_e32 v11, v10
	s_nop 0
	v_add_u32_e32 v18, -1, v11
	v_fma_f32 v19, -v18, v11, v10
	v_cmp_ge_f32_e64 s[88:89], 0, v19
	v_add_u32_e32 v19, 1, v11
	s_nop 0
	v_cndmask_b32_e64 v18, v11, v18, s[88:89]
	v_fma_f32 v11, -v19, v11, v10
	v_cmp_lt_f32_e64 s[88:89], 0, v11
	s_nop 1
	v_cndmask_b32_e64 v11, v18, v19, s[88:89]
	v_mul_f32_e32 v18, 0x37800000, v11
	v_cndmask_b32_e32 v11, v11, v18, vcc
	v_cmp_class_f32_e32 vcc, v10, v221
	v_readfirstlane_b32 s88, v41
	s_nop 0
	v_cndmask_b32_e32 v10, v11, v10, vcc
	v_div_scale_f32 v11, s[2:3], v10, v10, 1.0
	v_rcp_f32_e32 v18, v11
	s_add_i32 s2, s48, s93
	s_ashr_i32 s3, s2, 31
	s_lshl_b64 s[2:3], s[2:3], 2
	v_fma_f32 v19, -v11, v18, 1.0
	v_fmac_f32_e32 v18, v19, v18
	v_div_scale_f32 v19, vcc, 1.0, v10, 1.0
	v_mul_f32_e32 v38, v19, v18
	v_fma_f32 v39, -v11, v38, v19
	v_fmac_f32_e32 v38, v39, v18
	v_fma_f32 v11, -v11, v38, v19
	v_div_fmas_f32 v11, v11, v18, v38
	v_div_fixup_f32 v10, v11, v10, 1.0
	v_pk_mul_f32 v[18:19], v[10:11], v[64:65] op_sel_hi:[0,1]
	v_pk_mul_f32 v[38:39], v[76:77], v[18:19]
	v_pk_mul_f32 v[18:19], v[10:11], v[58:59] op_sel_hi:[0,1]
	v_pk_mul_f32 v[2:3], v[10:11], v[2:3] op_sel_hi:[0,1]
	v_pk_mul_f32 v[42:43], v[18:19], v[44:45]
	v_pk_mul_f32 v[18:19], v[10:11], v[66:67] op_sel_hi:[0,1]
	v_pk_mul_f32 v[2:3], v[74:75], v[2:3]
	v_pk_mul_f32 v[44:45], v[18:19], v[48:49]
	v_pk_mul_f32 v[18:19], v[102:103], v[38:39]
	v_mov_b32_e32 v58, v50
	v_pk_fma_f32 v[18:19], v[104:105], v[2:3], v[18:19]
	v_mov_b32_e32 v59, v52
	v_pk_mul_f32 v[46:47], v[18:19], s[86:87] op_sel_hi:[1,0]
	v_pk_mul_f32 v[18:19], v[12:13], v[44:45]
	v_mov_b32_e32 v52, v51
	v_pk_fma_f32 v[18:19], v[20:21], v[42:43], v[18:19]
	s_add_u32 s48, s49, s2
	v_pk_mul_f32 v[48:49], v[18:19], s[86:87] op_sel_hi:[1,0]
	v_pk_mul_f32 v[18:19], v[10:11], v[60:61] op_sel_hi:[0,1]
	v_pk_mul_f32 v[58:59], v[18:19], v[58:59]
	v_pk_mul_f32 v[18:19], v[10:11], v[68:69] op_sel_hi:[0,1]
	v_mov_b32_e32 v60, v54
	v_mov_b32_e32 v61, v56
	v_pk_mul_f32 v[60:61], v[18:19], v[60:61]
	v_pk_mul_f32 v[18:19], v[10:11], v[62:63] op_sel_hi:[0,1]
	v_pk_mul_f32 v[50:51], v[18:19], v[52:53]
	v_pk_mul_f32 v[10:11], v[10:11], v[70:71] op_sel_hi:[0,1]
	v_mov_b32_e32 v56, v55
	v_mov_b32_e32 v18, v14
	v_mov_b32_e32 v19, v16
	v_mov_b32_e32 v16, v15
	v_pk_mul_f32 v[14:15], v[104:105], v[38:39]
	v_pk_mul_f32 v[52:53], v[10:11], v[56:57]
	v_pk_fma_f32 v[2:3], v[102:103], v[2:3], v[14:15] neg_lo:[0,0,1] neg_hi:[0,0,1]
	v_pk_mul_f32 v[14:15], v[20:21], v[44:45]
	v_mov_b32_e32 v10, v6
	v_mov_b32_e32 v11, v8
	v_mov_b32_e32 v8, v7
	v_pk_fma_f32 v[14:15], v[12:13], v[42:43], v[14:15] neg_lo:[0,0,1] neg_hi:[0,0,1]
	v_pk_mul_f32 v[38:39], v[18:19], v[60:61]
	v_pk_mul_f32 v[42:43], v[16:17], v[52:53]
	v_pk_mul_f32 v[6:7], v[8:9], v[52:53]
	v_pk_mul_f32 v[14:15], v[14:15], s[86:87] op_sel_hi:[1,0]
	v_pk_fma_f32 v[38:39], v[10:11], v[58:59], v[38:39] neg_lo:[0,0,1] neg_hi:[0,0,1]
	v_pk_fma_f32 v[42:43], v[8:9], v[50:51], v[42:43] neg_lo:[0,0,1] neg_hi:[0,0,1]
	v_pk_fma_f32 v[6:7], v[16:17], v[50:51], v[6:7]
	v_pk_mul_f32 v[38:39], v[38:39], s[86:87] op_sel_hi:[1,0]
	v_pk_mul_f32 v[42:43], v[42:43], s[86:87] op_sel_hi:[1,0]
	v_bfe_u32 v50, v15, 16, 1
	v_bfe_u32 v51, v14, 16, 1
	v_pk_mul_f32 v[54:55], v[10:11], v[60:61]
	v_pk_mul_f32 v[2:3], v[2:3], s[86:87] op_sel_hi:[1,0]
	v_bfe_u32 v44, v43, 16, 1
	v_bfe_u32 v45, v42, 16, 1
	v_add3_u32 v14, v14, v51, s91
	v_add3_u32 v15, v15, v50, s91
	v_bfe_u32 v50, v38, 16, 1
	v_bfe_u32 v51, v39, 16, 1
	v_pk_fma_f32 v[54:55], v[18:19], v[58:59], v[54:55]
	v_add3_u32 v42, v42, v45, s91
	v_add3_u32 v43, v43, v44, s91
	v_bfe_u32 v44, v2, 16, 1
	v_bfe_u32 v45, v3, 16, 1
	v_add3_u32 v39, v39, v51, s91
	v_add3_u32 v38, v38, v50, s91
	v_pk_mul_f32 v[54:55], v[54:55], s[86:87] op_sel_hi:[1,0]
	v_add3_u32 v3, v3, v45, s91
	v_add3_u32 v2, v2, v44, s91
	v_lshrrev_b32_e32 v38, 16, v38
	v_lshrrev_b32_e32 v39, 16, v39
	v_pk_mul_f32 v[6:7], v[6:7], s[86:87] op_sel_hi:[1,0]
	v_lshrrev_b32_e32 v2, 16, v2
	v_lshrrev_b32_e32 v3, 16, v3
	v_and_or_b32 v115, v43, s33, v39
	v_and_or_b32 v114, v42, s33, v38
	v_bfe_u32 v38, v54, 16, 1
	v_bfe_u32 v39, v55, 16, 1
	v_and_or_b32 v113, v15, s33, v3
	v_and_or_b32 v112, v14, s33, v2
	v_bfe_u32 v2, v7, 16, 1
	v_bfe_u32 v3, v6, 16, 1
	v_add3_u32 v39, v55, v39, s91
	v_add3_u32 v38, v54, v38, s91
	v_add3_u32 v3, v6, v3, s91
	v_add3_u32 v2, v7, v2, s91
	v_lshrrev_b32_e32 v38, 16, v38
	v_lshrrev_b32_e32 v39, 16, v39
	v_and_or_b32 v119, v2, s33, v39
	v_and_or_b32 v118, v3, s33, v38
	ds_read_b128 v[38:41], v100
	ds_read_b128 v[42:45], v100 offset:64
	v_bfe_u32 v6, v46, 16, 1
	v_bfe_u32 v7, v47, 16, 1
	s_waitcnt lgkmcnt(1)
	v_mfma_f32_16x16x32_bf16 v[38:41], v[38:41], v[112:115], 0
	v_bfe_u32 v14, v49, 16, 1
	v_bfe_u32 v15, v48, 16, 1
	v_add3_u32 v7, v47, v7, s91
	v_add3_u32 v6, v46, v6, s91
	v_add3_u32 v15, v48, v15, s91
	v_add3_u32 v14, v49, v14, s91
	v_lshrrev_b32_e32 v6, 16, v6
	v_lshrrev_b32_e32 v7, 16, v7
	v_and_or_b32 v117, v14, s33, v7
	v_and_or_b32 v116, v15, s33, v6
	s_addc_u32 s49, s88, s3
	s_nop 1
	v_mov_b64_e32 v[132:133], s[48:49]
	global_load_dword v134, v[132:133], off
	v_mov_b64_e32 v[2:3], s[48:49]
	s_waitcnt lgkmcnt(0)
	v_mfma_f32_16x16x32_bf16 v[74:77], v[42:45], v[116:119], v[38:41]
	ds_read_b128 v[42:45], v98 offset:64
	s_waitcnt vmcnt(0)
	s_nop 0
	v_mov_b32_e32 v3, v134
	s_nop 1
	v_mov_b32_e32 v2, s94
	ds_read_b128 v[38:41], v98
	s_waitcnt lgkmcnt(0)
	v_mfma_f32_16x16x32_bf16 v[38:41], v[38:41], v[112:115], 0
	s_nop 1
	v_cndmask_b32_e64 v15, v74, v2, s[40:41]
	s_mov_b64 s[40:41], s[42:43]
	v_mfma_f32_16x16x32_bf16 v[70:73], v[42:45], v[116:119], v[38:41]
	ds_read_b128 v[42:45], v96 offset:64
	v_writelane_b32 v255, s40, 22
	v_cndmask_b32_e64 v14, v75, v227, s[42:43]
	ds_read_b128 v[38:41], v96
	s_waitcnt lgkmcnt(0)
	v_mfma_f32_16x16x32_bf16 v[38:41], v[38:41], v[112:115], 0
	v_writelane_b32 v255, s41, 23
	v_max3_f32 v2, v15, s94, v14
	v_readlane_b32 s80, v255, 2
	v_mfma_f32_16x16x32_bf16 v[66:69], v[42:45], v[116:119], v[38:41]
	ds_read_b128 v[42:45], v94 offset:64
	v_readlane_b32 s42, v255, 4
	v_readlane_b32 s81, v255, 3
	s_nop 0
	ds_read_b128 v[38:41], v94
	s_waitcnt lgkmcnt(0)
	v_mfma_f32_16x16x32_bf16 v[38:41], v[38:41], v[112:115], 0
	v_readlane_b32 s43, v255, 5
	v_cndmask_b32_e64 v7, v76, v227, s[80:81]
	v_mfma_f32_16x16x32_bf16 v[62:65], v[42:45], v[116:119], v[38:41]
	ds_read_b128 v[42:45], v92 offset:64
	v_cndmask_b32_e64 v6, v77, v227, s[42:43]
	v_readlane_b32 s48, v255, 6
	s_nop 1
	ds_read_b128 v[38:41], v92
	s_waitcnt lgkmcnt(0)
	v_mfma_f32_16x16x32_bf16 v[38:41], v[38:41], v[112:115], 0
	v_max3_f32 v76, v2, v7, v6
	v_mov_b32_e32 v2, s94
	v_readlane_b32 s49, v255, 7
	v_mfma_f32_16x16x32_bf16 v[58:61], v[42:45], v[116:119], v[38:41]
	ds_read_b128 v[42:45], v90 offset:64
	v_cndmask_b32_e64 v75, v70, v2, s[48:49]
	v_cndmask_b32_e64 v74, v71, v227, s[6:7]
	s_nop 0
	ds_read_b128 v[38:41], v90
	s_waitcnt lgkmcnt(0)
	v_mfma_f32_16x16x32_bf16 v[38:41], v[38:41], v[112:115], 0
	v_max3_f32 v2, v76, v75, v74
	v_cndmask_b32_e64 v71, v72, v227, s[4:5]
	v_mfma_f32_16x16x32_bf16 v[54:57], v[42:45], v[116:119], v[38:41]
	ds_read_b128 v[42:45], v88 offset:64
	v_cndmask_b32_e64 v70, v73, v227, s[44:45]
	v_readlane_b32 s4, v255, 12
	s_nop 1
	ds_read_b128 v[38:41], v88
	s_waitcnt lgkmcnt(0)
	v_mfma_f32_16x16x32_bf16 v[38:41], v[38:41], v[112:115], 0
	v_max3_f32 v76, v2, v71, v70
	v_mov_b32_e32 v2, s94
	v_readlane_b32 s5, v255, 13
	v_mfma_f32_16x16x32_bf16 v[50:53], v[42:45], v[116:119], v[38:41]
	ds_read_b128 v[42:45], v86 offset:64
	v_cndmask_b32_e64 v73, v66, v2, s[4:5]
	v_cndmask_b32_e64 v72, v67, v227, s[12:13]
	s_nop 0
	ds_read_b128 v[38:41], v86
	s_waitcnt lgkmcnt(0)
	v_mfma_f32_16x16x32_bf16 v[38:41], v[38:41], v[112:115], 0
	v_max3_f32 v2, v76, v73, v72
	v_cndmask_b32_e64 v67, v68, v227, s[10:11]
	v_mfma_f32_16x16x32_bf16 v[46:49], v[42:45], v[116:119], v[38:41]
	ds_read_b128 v[42:45], v84 offset:64
	v_cndmask_b32_e64 v66, v69, v227, s[8:9]
	v_max3_f32 v76, v2, v67, v66
	s_nop 1
	ds_read_b128 v[38:41], v84
	s_waitcnt lgkmcnt(0)
	v_mfma_f32_16x16x32_bf16 v[38:41], v[38:41], v[112:115], 0
	v_mov_b32_e32 v2, s94
	v_cndmask_b32_e64 v69, v62, v2, s[20:21]
	v_cndmask_b32_e64 v68, v63, v227, s[18:19]
	v_mfma_f32_16x16x32_bf16 v[42:45], v[42:45], v[116:119], v[38:41]
	v_max3_f32 v2, v76, v69, v68
	v_cndmask_b32_e64 v63, v64, v227, s[16:17]
	v_cndmask_b32_e64 v62, v65, v227, s[14:15]
	s_nop 0
	ds_read_b128 v[38:41], v82
	v_max3_f32 v76, v2, v63, v62
	v_mov_b32_e32 v2, s94
	v_cndmask_b32_e64 v65, v58, v2, s[28:29]
	v_cndmask_b32_e64 v64, v59, v227, s[24:25]
	v_max3_f32 v2, v76, v65, v64
	v_cndmask_b32_e64 v59, v60, v227, s[22:23]
	v_cndmask_b32_e64 v58, v61, v227, s[26:27]
	s_waitcnt lgkmcnt(0)
	v_mfma_f32_16x16x32_bf16 v[38:41], v[38:41], v[112:115], 0
	ds_read_b128 v[112:115], v82 offset:64
	v_max3_f32 v76, v2, v59, v58
	v_mov_b32_e32 v2, s94
	v_cndmask_b32_e64 v61, v54, v2, s[38:39]
	v_cndmask_b32_e64 v60, v55, v227, s[30:31]
	v_max3_f32 v2, v76, v61, v60
	v_cndmask_b32_e64 v55, v56, v227, s[34:35]
	v_cndmask_b32_e64 v54, v57, v227, s[36:37]
	v_max3_f32 v76, v2, v55, v54
	v_mov_b32_e32 v2, s94
	v_cndmask_b32_e64 v57, v50, v2, s[54:55]
	v_cndmask_b32_e64 v56, v51, v227, s[46:47]
	v_max3_f32 v2, v76, v57, v56
	v_cndmask_b32_e64 v51, v52, v227, s[50:51]
	v_cndmask_b32_e64 v50, v53, v227, s[52:53]
	v_max3_f32 v76, v2, v51, v50
	v_mov_b32_e32 v2, s94
	v_cndmask_b32_e64 v53, v46, v2, s[62:63]
	v_cndmask_b32_e64 v52, v47, v227, s[56:57]
	v_max3_f32 v2, v76, v53, v52
	v_cndmask_b32_e64 v47, v48, v227, s[58:59]
	v_cndmask_b32_e64 v46, v49, v227, s[60:61]
	s_waitcnt lgkmcnt(0)
	v_mfma_f32_16x16x32_bf16 v[38:41], v[112:115], v[116:119], v[38:41]
	v_max3_f32 v76, v2, v47, v46
	v_mov_b32_e32 v2, s94
	v_cndmask_b32_e64 v49, v42, v2, s[70:71]
	v_cndmask_b32_e64 v48, v43, v227, s[64:65]
	v_max3_f32 v2, v76, v49, v48
	v_cndmask_b32_e64 v43, v44, v227, s[66:67]
	v_cndmask_b32_e64 v42, v45, v227, s[68:69]
	s_mov_b64 s[4:5], s[24:25]
	v_max3_f32 v44, v2, v43, v42
	v_mov_b32_e32 v2, s94
	s_mov_b64 s[24:25], s[78:79]
	s_mov_b64 s[70:71], s[76:77]
	v_cndmask_b32_e64 v2, v38, v2, s[24:25]
	v_cndmask_b32_e64 v38, v39, v227, s[70:71]
	v_max3_f32 v39, v44, v2, v38
	v_cndmask_b32_e64 v40, v40, v227, s[72:73]
	v_cndmask_b32_e64 v41, v41, v227, s[74:75]
	v_max3_f32 v39, v39, v40, v41
	ds_bpermute_b32 v44, v109, v39
	s_mov_b32 s93, s95
	s_mov_b32 s6, 0xf800000
	v_readlane_b32 s8, v255, 0
	s_waitcnt lgkmcnt(0)
	v_max_f32_e32 v44, v44, v44
	v_max_f32_e32 v39, v39, v44
	ds_bpermute_b32 v44, v110, v39
	v_readlane_b32 s9, v255, 1
	v_readlane_b32 s18, v255, 6
	v_readlane_b32 s10, v255, 8
	v_readlane_b32 s19, v255, 7
	s_waitcnt vmcnt(0) lgkmcnt(0)
	v_max3_f32 v39, v39, v44, v3
	v_sub_f32_e32 v15, v15, v39
	v_mul_f32_e32 v15, 0x3fb8aa3b, v15
	v_sub_f32_e32 v14, v14, v39
	v_exp_f32_e32 v15, v15
	v_mul_f32_e32 v14, 0x3fb8aa3b, v14
	v_sub_f32_e32 v7, v7, v39
	v_exp_f32_e32 v14, v14
	v_mul_f32_e32 v7, 0x3fb8aa3b, v7
	v_sub_f32_e32 v6, v6, v39
	v_exp_f32_e32 v7, v7
	v_mul_f32_e32 v6, 0x3fb8aa3b, v6
	v_sub_f32_e32 v45, v75, v39
	v_exp_f32_e32 v6, v6
	v_mul_f32_e32 v45, 0x3fb8aa3b, v45
	v_sub_f32_e32 v74, v74, v39
	v_add_f32_e32 v44, 0, v15
	v_exp_f32_e32 v45, v45
	v_mul_f32_e32 v74, 0x3fb8aa3b, v74
	v_sub_f32_e32 v71, v71, v39
	v_add_f32_e32 v44, v14, v44
	v_exp_f32_e32 v74, v74
	v_mul_f32_e32 v71, 0x3fb8aa3b, v71
	v_sub_f32_e32 v70, v70, v39
	v_add_f32_e32 v44, v7, v44
	v_exp_f32_e32 v71, v71
	v_mul_f32_e32 v70, 0x3fb8aa3b, v70
	v_sub_f32_e32 v73, v73, v39
	v_add_f32_e32 v44, v6, v44
	v_exp_f32_e32 v70, v70
	v_mul_f32_e32 v73, 0x3fb8aa3b, v73
	v_sub_f32_e32 v72, v72, v39
	v_add_f32_e32 v44, v45, v44
	v_exp_f32_e32 v75, v73
	v_mul_f32_e32 v72, 0x3fb8aa3b, v72
	v_sub_f32_e32 v67, v67, v39
	v_add_f32_e32 v44, v74, v44
	v_exp_f32_e32 v76, v72
	v_mul_f32_e32 v67, 0x3fb8aa3b, v67
	v_sub_f32_e32 v66, v66, v39
	v_add_f32_e32 v44, v71, v44
	v_exp_f32_e32 v67, v67
	v_mul_f32_e32 v66, 0x3fb8aa3b, v66
	v_sub_f32_e32 v69, v69, v39
	v_add_f32_e32 v44, v70, v44
	v_exp_f32_e32 v66, v66
	v_mul_f32_e32 v69, 0x3fb8aa3b, v69
	v_sub_f32_e32 v68, v68, v39
	v_add_f32_e32 v44, v75, v44
	v_exp_f32_e32 v69, v69
	v_mul_f32_e32 v68, 0x3fb8aa3b, v68
	v_sub_f32_e32 v63, v63, v39
	v_add_f32_e32 v44, v76, v44
	v_exp_f32_e32 v68, v68
	v_mul_f32_e32 v63, 0x3fb8aa3b, v63
	v_sub_f32_e32 v62, v62, v39
	v_add_f32_e32 v44, v67, v44
	v_exp_f32_e32 v63, v63
	v_mul_f32_e32 v62, 0x3fb8aa3b, v62
	v_sub_f32_e32 v65, v65, v39
	v_add_f32_e32 v44, v66, v44
	v_exp_f32_e32 v62, v62
	v_mul_f32_e32 v65, 0x3fb8aa3b, v65
	v_sub_f32_e32 v64, v64, v39
	v_sub_f32_e32 v58, v58, v39
	v_add_f32_e32 v44, v69, v44
	v_exp_f32_e32 v65, v65
	v_mul_f32_e32 v64, 0x3fb8aa3b, v64
	v_sub_f32_e32 v59, v59, v39
	v_mul_f32_e32 v58, 0x3fb8aa3b, v58
	v_add_f32_e32 v44, v68, v44
	v_exp_f32_e32 v64, v64
	v_mul_f32_e32 v59, 0x3fb8aa3b, v59
	v_exp_f32_e32 v93, v58
	v_sub_f32_e32 v58, v61, v39
	v_add_f32_e32 v44, v63, v44
	v_exp_f32_e32 v77, v59
	v_mul_f32_e32 v58, 0x3fb8aa3b, v58
	v_add_f32_e32 v44, v62, v44
	v_exp_f32_e32 v95, v58
	v_sub_f32_e32 v58, v60, v39
	v_sub_f32_e32 v54, v54, v39
	v_add_f32_e32 v44, v65, v44
	v_mul_f32_e32 v58, 0x3fb8aa3b, v58
	v_sub_f32_e32 v55, v55, v39
	v_mul_f32_e32 v54, 0x3fb8aa3b, v54
	v_add_f32_e32 v44, v64, v44
	v_exp_f32_e32 v97, v58
	v_mul_f32_e32 v55, 0x3fb8aa3b, v55
	v_exp_f32_e32 v101, v54
	v_sub_f32_e32 v54, v57, v39
	v_add_f32_e32 v44, v77, v44
	v_exp_f32_e32 v99, v55
	v_mul_f32_e32 v54, 0x3fb8aa3b, v54
	v_add_f32_e32 v44, v93, v44
	v_exp_f32_e32 v111, v54
	v_sub_f32_e32 v54, v56, v39
	v_sub_f32_e32 v50, v50, v39
	v_add_f32_e32 v44, v95, v44
	v_mul_f32_e32 v54, 0x3fb8aa3b, v54
	v_sub_f32_e32 v51, v51, v39
	v_mul_f32_e32 v50, 0x3fb8aa3b, v50
	v_add_f32_e32 v44, v97, v44
	v_exp_f32_e32 v112, v54
	v_mul_f32_e32 v51, 0x3fb8aa3b, v51
	v_exp_f32_e32 v114, v50
	v_sub_f32_e32 v50, v53, v39
	v_add_f32_e32 v44, v99, v44
	v_exp_f32_e32 v113, v51
	v_mul_f32_e32 v50, 0x3fb8aa3b, v50
	v_add_f32_e32 v44, v101, v44
	v_exp_f32_e32 v115, v50
	v_sub_f32_e32 v50, v52, v39
	v_sub_f32_e32 v46, v46, v39
	v_add_f32_e32 v44, v111, v44
	v_mul_f32_e32 v50, 0x3fb8aa3b, v50
	v_sub_f32_e32 v47, v47, v39
	v_mul_f32_e32 v46, 0x3fb8aa3b, v46
	v_add_f32_e32 v44, v112, v44
	v_exp_f32_e32 v116, v50
	v_mul_f32_e32 v47, 0x3fb8aa3b, v47
	v_exp_f32_e32 v118, v46
	v_sub_f32_e32 v46, v49, v39
	v_add_f32_e32 v44, v113, v44
	v_exp_f32_e32 v117, v47
	v_mul_f32_e32 v46, 0x3fb8aa3b, v46
	v_add_f32_e32 v44, v114, v44
	v_exp_f32_e32 v119, v46
	v_sub_f32_e32 v46, v48, v39
	v_add_f32_e32 v44, v115, v44
	v_mul_f32_e32 v46, 0x3fb8aa3b, v46
	v_sub_f32_e32 v43, v43, v39
	v_add_f32_e32 v44, v116, v44
	v_exp_f32_e32 v120, v46
	v_mul_f32_e32 v43, 0x3fb8aa3b, v43
	v_sub_f32_e32 v42, v42, v39
	v_sub_f32_e32 v38, v38, v39
	v_add_f32_e32 v44, v117, v44
	v_exp_f32_e32 v121, v43
	v_mul_f32_e32 v42, 0x3fb8aa3b, v42
	v_sub_f32_e32 v2, v2, v39
	v_mul_f32_e32 v38, 0x3fb8aa3b, v38
	v_add_f32_e32 v44, v118, v44
	v_exp_f32_e32 v122, v42
	v_mul_f32_e32 v2, 0x3fb8aa3b, v2
	v_exp_f32_e32 v124, v38
	v_sub_f32_e32 v38, v40, v39
	v_add_f32_e32 v44, v119, v44
	v_exp_f32_e32 v123, v2
	v_mul_f32_e32 v38, 0x3fb8aa3b, v38
	v_add_f32_e32 v44, v120, v44
	v_exp_f32_e32 v125, v38
	v_sub_f32_e32 v38, v41, v39
	v_add_f32_e32 v43, v121, v44
	v_mul_f32_e32 v38, 0x3fb8aa3b, v38
	v_add_f32_e32 v42, v122, v43
	v_exp_f32_e32 v126, v38
	v_add_f32_e32 v2, v123, v42
	v_add_f32_e32 v2, v124, v2
	v_add_f32_e32 v2, v125, v2
	v_add_f32_e32 v2, v126, v2
	ds_bpermute_b32 v38, v109, v2
	v_sub_f32_e32 v3, v3, v39
	v_mul_f32_e32 v3, 0x3fb8aa3b, v3
	v_exp_f32_e32 v3, v3
	v_bfe_u32 v40, v14, 16, 1
	s_waitcnt lgkmcnt(0)
	v_add_f32_e32 v2, v2, v38
	ds_bpermute_b32 v38, v110, v2
	v_bfe_u32 v42, v71, 16, 1
	v_add3_u32 v14, v14, v40, s91
	v_bfe_u32 v40, v7, 16, 1
	v_bfe_u32 v41, v45, 16, 1
	s_waitcnt lgkmcnt(0)
	v_add_f32_e32 v2, v2, v38
	v_add_f32_e32 v2, v3, v2
	v_bfe_u32 v3, v70, 16, 1
	v_add3_u32 v3, v70, v3, s91
	v_add3_u32 v42, v71, v42, s91
	v_add_u32_e32 v73, 0x9000, v91
	v_add_u32_e32 v72, 0xb000, v91
	v_add_u32_e32 v71, 0xd000, v91
	v_add_u32_e32 v70, 0xf000, v91
	v_add3_u32 v41, v45, v41, s91
	v_add3_u32 v7, v7, v40, s91
	v_lshrrev_b32_e32 v40, 16, v42
	ds_read2_b64 v[42:45], v73 offset1:4
	ds_read2_b64 v[46:49], v72 offset0:32 offset1:36
	ds_read2_b64 v[50:53], v71 offset0:64 offset1:68
	ds_read2_b64 v[54:57], v70 offset0:96 offset1:100
	v_bfe_u32 v39, v6, 16, 1
	v_add3_u32 v6, v6, v39, s91
	v_bfe_u32 v39, v15, 16, 1
	v_bfe_u32 v38, v74, 16, 1
	v_add3_u32 v15, v15, v39, s91
	v_add3_u32 v38, v74, v38, s91
	v_lshrrev_b32_e32 v15, 16, v15
	v_lshrrev_b32_e32 v7, 16, v7
	v_lshrrev_b32_e32 v39, 16, v41
	v_and_or_b32 v41, v3, s33, v40
	v_and_or_b32 v40, v38, s33, v39
	v_and_or_b32 v39, v6, s33, v7
	v_and_or_b32 v38, v14, s33, v15
	v_bfe_u32 v15, v75, 16, 1
	v_bfe_u32 v3, v62, 16, 1
	s_waitcnt lgkmcnt(3)
	v_mfma_f32_16x16x32_bf16 v[42:45], v[42:45], v[38:41], 0
	v_bfe_u32 v6, v68, 16, 1
	v_bfe_u32 v7, v66, 16, 1
	v_bfe_u32 v14, v76, 16, 1
	s_waitcnt lgkmcnt(2)
	v_mfma_f32_16x16x32_bf16 v[46:49], v[46:49], v[38:41], 0
	v_add3_u32 v15, v75, v15, s91
	v_add3_u32 v14, v76, v14, s91
	v_add3_u32 v7, v66, v7, s91
	s_waitcnt lgkmcnt(1)
	v_mfma_f32_16x16x32_bf16 v[50:53], v[50:53], v[38:41], 0
	v_add3_u32 v6, v68, v6, s91
	v_add3_u32 v3, v62, v3, s91
	v_lshrrev_b32_e32 v15, 16, v15
	s_waitcnt lgkmcnt(0)
	v_mfma_f32_16x16x32_bf16 v[38:41], v[54:57], v[38:41], 0
	v_bfe_u32 v55, v69, 16, 1
	v_add3_u32 v55, v69, v55, s91
	v_add_u32_e32 v69, 0x9000, v89
	ds_read2_b64 v[58:61], v69 offset1:4
	v_bfe_u32 v54, v67, 16, 1
	v_bfe_u32 v56, v63, 16, 1
	v_add3_u32 v56, v63, v56, s91
	v_add3_u32 v54, v67, v54, s91
	v_lshrrev_b32_e32 v54, 16, v54
	v_lshrrev_b32_e32 v55, 16, v55
	v_lshrrev_b32_e32 v56, 16, v56
	v_and_or_b32 v57, v3, s33, v56
	v_and_or_b32 v56, v6, s33, v55
	v_and_or_b32 v55, v7, s33, v54
	v_and_or_b32 v54, v14, s33, v15
	v_add_u32_e32 v68, 0xb000, v89
	v_add_u32_e32 v67, 0xd000, v89
	s_waitcnt lgkmcnt(0)
	v_mfma_f32_16x16x32_bf16 v[42:45], v[58:61], v[54:57], v[42:45]
	ds_read2_b64 v[58:61], v68 offset0:32 offset1:36
	v_add_u32_e32 v66, 0xf000, v89
	v_bfe_u32 v15, v65, 16, 1
	s_waitcnt lgkmcnt(0)
	v_mfma_f32_16x16x32_bf16 v[46:49], v[58:61], v[54:57], v[46:49]
	ds_read2_b64 v[58:61], v67 offset0:64 offset1:68
	v_add3_u32 v15, v65, v15, s91
	v_add_u32_e32 v65, 0x9000, v87
	s_waitcnt lgkmcnt(0)
	v_mfma_f32_16x16x32_bf16 v[50:53], v[58:61], v[54:57], v[50:53]
	ds_read2_b64 v[58:61], v66 offset0:96 offset1:100
	v_bfe_u32 v3, v101, 16, 1
	s_waitcnt lgkmcnt(0)
	v_mfma_f32_16x16x32_bf16 v[38:41], v[58:61], v[54:57], v[38:41]
	ds_read2_b64 v[58:61], v65 offset1:4
	v_bfe_u32 v54, v77, 16, 1
	v_bfe_u32 v55, v95, 16, 1
	v_bfe_u32 v56, v99, 16, 1
	v_bfe_u32 v6, v97, 16, 1
	v_bfe_u32 v7, v93, 16, 1
	v_bfe_u32 v14, v64, 16, 1
	v_add3_u32 v56, v99, v56, s91
	v_add3_u32 v55, v95, v55, s91
	v_add3_u32 v54, v77, v54, s91
	v_add3_u32 v14, v64, v14, s91
	v_add3_u32 v7, v93, v7, s91
	v_add3_u32 v6, v97, v6, s91
	v_add3_u32 v3, v101, v3, s91
	v_lshrrev_b32_e32 v15, 16, v15
	v_lshrrev_b32_e32 v54, 16, v54
	v_lshrrev_b32_e32 v55, 16, v55
	v_lshrrev_b32_e32 v56, 16, v56
	v_and_or_b32 v57, v3, s33, v56
	v_and_or_b32 v56, v6, s33, v55
	v_and_or_b32 v55, v7, s33, v54
	v_and_or_b32 v54, v14, s33, v15
	v_add_u32_e32 v64, 0xb000, v87
	v_add_u32_e32 v63, 0xd000, v87
	s_waitcnt lgkmcnt(0)
	v_mfma_f32_16x16x32_bf16 v[42:45], v[58:61], v[54:57], v[42:45]
	ds_read2_b64 v[58:61], v64 offset0:32 offset1:36
	v_add_u32_e32 v62, 0xf000, v87
	v_bfe_u32 v15, v111, 16, 1
	s_waitcnt lgkmcnt(0)
	v_mfma_f32_16x16x32_bf16 v[46:49], v[58:61], v[54:57], v[46:49]
	ds_read2_b64 v[58:61], v63 offset0:64 offset1:68
	v_bfe_u32 v3, v118, 16, 1
	v_bfe_u32 v6, v116, 16, 1
	s_waitcnt lgkmcnt(0)
	v_mfma_f32_16x16x32_bf16 v[50:53], v[58:61], v[54:57], v[50:53]
	ds_read2_b64 v[58:61], v62 offset0:96 offset1:100
	v_bfe_u32 v7, v114, 16, 1
	s_waitcnt lgkmcnt(0)
	v_mfma_f32_16x16x32_bf16 v[38:41], v[58:61], v[54:57], v[38:41]
	v_add_u32_e32 v61, 0x9000, v85
	ds_read2_b64 v[74:77], v61 offset1:4
	v_bfe_u32 v54, v113, 16, 1
	v_bfe_u32 v55, v115, 16, 1
	v_bfe_u32 v56, v117, 16, 1
	v_bfe_u32 v14, v112, 16, 1
	v_add3_u32 v56, v117, v56, s91
	v_add3_u32 v55, v115, v55, s91
	v_add3_u32 v54, v113, v54, s91
	v_add3_u32 v15, v111, v15, s91
	v_add3_u32 v14, v112, v14, s91
	v_add3_u32 v7, v114, v7, s91
	v_add3_u32 v6, v116, v6, s91
	v_add3_u32 v3, v118, v3, s91
	v_lshrrev_b32_e32 v15, 16, v15
	v_lshrrev_b32_e32 v54, 16, v54
	v_lshrrev_b32_e32 v55, 16, v55
	v_lshrrev_b32_e32 v56, 16, v56
	v_and_or_b32 v57, v3, s33, v56
	v_and_or_b32 v56, v6, s33, v55
	v_and_or_b32 v55, v7, s33, v54
	v_and_or_b32 v54, v14, s33, v15
	v_add_u32_e32 v60, 0xb000, v85
	v_add_u32_e32 v59, 0xd000, v85
	s_waitcnt lgkmcnt(0)
	v_mfma_f32_16x16x32_bf16 v[42:45], v[74:77], v[54:57], v[42:45]
	ds_read2_b64 v[74:77], v60 offset0:32 offset1:36
	v_add_u32_e32 v58, 0xf000, v85
	v_bfe_u32 v3, v126, 16, 1
	s_waitcnt lgkmcnt(0)
	v_mfma_f32_16x16x32_bf16 v[46:49], v[74:77], v[54:57], v[46:49]
	ds_read2_b64 v[74:77], v59 offset0:64 offset1:68
	v_bfe_u32 v6, v124, 16, 1
	v_bfe_u32 v7, v122, 16, 1
	s_waitcnt lgkmcnt(0)
	v_mfma_f32_16x16x32_bf16 v[74:77], v[74:77], v[54:57], v[50:53]
	s_nop 2
	ds_read2_b64 v[50:53], v58 offset0:96 offset1:100
	v_add3_u32 v7, v122, v7, s91
	s_waitcnt lgkmcnt(0)
	v_mfma_f32_16x16x32_bf16 v[38:41], v[50:53], v[54:57], v[38:41]
	v_bfe_u32 v50, v121, 16, 1
	v_bfe_u32 v51, v123, 16, 1
	v_bfe_u32 v52, v125, 16, 1
	v_add3_u32 v52, v125, v52, s91
	v_add3_u32 v51, v123, v51, s91
	v_add3_u32 v50, v121, v50, s91
	v_add3_u32 v6, v124, v6, s91
	v_add3_u32 v3, v126, v3, s91
	v_lshrrev_b32_e32 v50, 16, v50
	v_lshrrev_b32_e32 v51, 16, v51
	v_lshrrev_b32_e32 v52, 16, v52
	v_add_u32_e32 v57, 0x9000, v83
	v_and_or_b32 v115, v3, s33, v52
	v_and_or_b32 v114, v6, s33, v51
	v_and_or_b32 v113, v7, s33, v50
	ds_read2_b64 v[50:53], v57 offset1:4
	v_bfe_u32 v15, v119, 16, 1
	v_bfe_u32 v14, v120, 16, 1
	v_add3_u32 v15, v119, v15, s91
	v_add3_u32 v14, v120, v14, s91
	v_lshrrev_b32_e32 v15, 16, v15
	v_and_or_b32 v112, v14, s33, v15
	v_add_u32_e32 v56, 0xb000, v83
	v_div_scale_f32 v3, s[48:49], v2, v2, 1.0
	s_waitcnt lgkmcnt(0)
	v_mfma_f32_16x16x32_bf16 v[50:53], v[50:53], v[112:115], v[42:45]
	v_rcp_f32_e32 v6, v3
	v_add_u32_e32 v55, 0xd000, v83
	v_add_u32_e32 v54, 0xf000, v83
	ds_read2_b64 v[42:45], v56 offset0:32 offset1:36
	v_fma_f32 v7, -v3, v6, 1.0
	v_fmac_f32_e32 v6, v7, v6
	v_div_scale_f32 v7, vcc, 1.0, v2, 1.0
	v_mul_f32_e32 v14, v7, v6
	v_fma_f32 v15, -v3, v14, v7
	v_fmac_f32_e32 v14, v15, v6
	s_waitcnt lgkmcnt(0)
	v_mfma_f32_16x16x32_bf16 v[46:49], v[42:45], v[112:115], v[46:49]
	ds_read2_b64 v[42:45], v55 offset0:64 offset1:68
	v_fma_f32 v3, -v3, v14, v7
	v_div_fmas_f32 v3, v3, v6, v14
	v_div_fixup_f32 v6, v3, v2, 1.0
	v_mov_b32_e32 v14, v50
	v_mov_b32_e32 v15, v52
	v_pk_mul_f32 v[14:15], v[6:7], v[14:15] op_sel_hi:[0,1]
	v_mov_b32_e32 v52, v51
	v_pk_mul_f32 v[50:51], v[6:7], v[52:53] op_sel_hi:[0,1]
	v_and_b32_sdwa v7, v15, v218 dst_sel:DWORD dst_unused:UNUSED_PAD src0_sel:WORD_1 src1_sel:DWORD
	v_and_b32_sdwa v52, v14, v218 dst_sel:DWORD dst_unused:UNUSED_PAD src0_sel:WORD_1 src1_sel:DWORD
	v_add3_u32 v14, v14, v52, s91
	v_add3_u32 v7, v15, v7, s91
	v_and_b32_sdwa v15, v51, v218 dst_sel:DWORD dst_unused:UNUSED_PAD src0_sel:WORD_1 src1_sel:DWORD
	v_and_b32_sdwa v52, v50, v218 dst_sel:DWORD dst_unused:UNUSED_PAD src0_sel:WORD_1 src1_sel:DWORD
	v_add3_u32 v15, v51, v15, s91
	v_add3_u32 v50, v50, v52, s91
	v_and_b32_e32 v15, 0xffff0000, v15
	v_and_b32_e32 v50, 0xffff0000, v50
	v_lshl_add_u64 v[2:3], v[80:81], 0, s[92:93]
	v_or_b32_sdwa v15, v15, v7 dst_sel:DWORD dst_unused:UNUSED_PAD src0_sel:DWORD src1_sel:WORD_1
	v_or_b32_sdwa v14, v50, v14 dst_sel:DWORD dst_unused:UNUSED_PAD src0_sel:DWORD src1_sel:WORD_1
	s_waitcnt lgkmcnt(0)
	v_mfma_f32_16x16x32_bf16 v[42:45], v[42:45], v[112:115], v[74:77]
	s_mov_b64 s[92:93], s[42:43]
	v_readlane_b32 s11, v255, 9
	v_readlane_b32 s12, v255, 10
	ds_read2_b64 v[74:77], v54 offset0:96 offset1:100
	flat_store_dwordx2 v[2:3], v[14:15]
	v_mov_b32_e32 v14, v46
	v_mov_b32_e32 v15, v48
	v_pk_mul_f32 v[14:15], v[6:7], v[14:15] op_sel_hi:[0,1]
	v_mov_b32_e32 v48, v47
	v_pk_mul_f32 v[46:47], v[6:7], v[48:49] op_sel_hi:[0,1]
	v_and_b32_sdwa v7, v15, v218 dst_sel:DWORD dst_unused:UNUSED_PAD src0_sel:WORD_1 src1_sel:DWORD
	v_and_b32_sdwa v48, v14, v218 dst_sel:DWORD dst_unused:UNUSED_PAD src0_sel:WORD_1 src1_sel:DWORD
	v_add3_u32 v14, v14, v48, s91
	v_add3_u32 v7, v15, v7, s91
	v_and_b32_sdwa v15, v47, v218 dst_sel:DWORD dst_unused:UNUSED_PAD src0_sel:WORD_1 src1_sel:DWORD
	v_and_b32_sdwa v48, v46, v218 dst_sel:DWORD dst_unused:UNUSED_PAD src0_sel:WORD_1 src1_sel:DWORD
	v_add3_u32 v15, v47, v15, s91
	v_add3_u32 v46, v46, v48, s91
	v_and_b32_e32 v15, 0xffff0000, v15
	v_and_b32_e32 v46, 0xffff0000, v46
	v_or_b32_sdwa v15, v15, v7 dst_sel:DWORD dst_unused:UNUSED_PAD src0_sel:DWORD src1_sel:WORD_1
	v_or_b32_sdwa v14, v46, v14 dst_sel:DWORD dst_unused:UNUSED_PAD src0_sel:DWORD src1_sel:WORD_1
	flat_store_dwordx2 v[2:3], v[14:15] offset:32
	v_mov_b32_e32 v14, v42
	v_mov_b32_e32 v15, v44
	v_pk_mul_f32 v[14:15], v[6:7], v[14:15] op_sel_hi:[0,1]
	v_mov_b32_e32 v44, v43
	v_pk_mul_f32 v[42:43], v[6:7], v[44:45] op_sel_hi:[0,1]
	v_and_b32_sdwa v7, v15, v218 dst_sel:DWORD dst_unused:UNUSED_PAD src0_sel:WORD_1 src1_sel:DWORD
	v_and_b32_sdwa v44, v14, v218 dst_sel:DWORD dst_unused:UNUSED_PAD src0_sel:WORD_1 src1_sel:DWORD
	s_waitcnt lgkmcnt(0)
	v_mfma_f32_16x16x32_bf16 v[38:41], v[74:77], v[112:115], v[38:41]
	v_add3_u32 v14, v14, v44, s91
	v_add3_u32 v7, v15, v7, s91
	v_and_b32_sdwa v15, v43, v218 dst_sel:DWORD dst_unused:UNUSED_PAD src0_sel:WORD_1 src1_sel:DWORD
	v_and_b32_sdwa v44, v42, v218 dst_sel:DWORD dst_unused:UNUSED_PAD src0_sel:WORD_1 src1_sel:DWORD
	v_add3_u32 v15, v43, v15, s91
	v_add3_u32 v42, v42, v44, s91
	v_and_b32_e32 v15, 0xffff0000, v15
	v_and_b32_e32 v42, 0xffff0000, v42
	v_or_b32_sdwa v15, v15, v7 dst_sel:DWORD dst_unused:UNUSED_PAD src0_sel:DWORD src1_sel:WORD_1
	v_or_b32_sdwa v14, v42, v14 dst_sel:DWORD dst_unused:UNUSED_PAD src0_sel:DWORD src1_sel:WORD_1
	flat_store_dwordx2 v[2:3], v[14:15] offset:64
	v_mov_b32_e32 v14, v38
	v_mov_b32_e32 v15, v40
	v_pk_mul_f32 v[14:15], v[6:7], v[14:15] op_sel_hi:[0,1]
	v_mov_b32_e32 v40, v39
	v_pk_mul_f32 v[6:7], v[6:7], v[40:41] op_sel_hi:[0,1]
	v_and_b32_sdwa v38, v15, v218 dst_sel:DWORD dst_unused:UNUSED_PAD src0_sel:WORD_1 src1_sel:DWORD
	v_and_b32_sdwa v39, v14, v218 dst_sel:DWORD dst_unused:UNUSED_PAD src0_sel:WORD_1 src1_sel:DWORD
	v_add3_u32 v14, v14, v39, s91
	v_add3_u32 v15, v15, v38, s91
	v_and_b32_sdwa v38, v7, v218 dst_sel:DWORD dst_unused:UNUSED_PAD src0_sel:WORD_1 src1_sel:DWORD
	v_and_b32_sdwa v39, v6, v218 dst_sel:DWORD dst_unused:UNUSED_PAD src0_sel:WORD_1 src1_sel:DWORD
	v_add3_u32 v7, v7, v38, s91
	v_add3_u32 v6, v6, v39, s91
	v_and_b32_e32 v7, 0xffff0000, v7
	v_and_b32_e32 v6, 0xffff0000, v6
	v_or_b32_sdwa v7, v7, v15 dst_sel:DWORD dst_unused:UNUSED_PAD src0_sel:DWORD src1_sel:WORD_1
	v_or_b32_sdwa v6, v6, v14 dst_sel:DWORD dst_unused:UNUSED_PAD src0_sel:DWORD src1_sel:WORD_1
	flat_store_dwordx2 v[2:3], v[6:7] offset:96
	v_lshlrev_b32_e32 v14, 16, v36
	v_and_b32_e32 v2, 0xffff0000, v36
	v_lshlrev_b32_e32 v15, 16, v37
	v_and_b32_e32 v3, 0xffff0000, v37
	ds_read2_b64 v[36:39], v79 offset1:1
	v_lshlrev_b32_e32 v45, 16, v31
	v_and_b32_e32 v43, 0xffff0000, v31
	v_lshlrev_b32_e32 v41, 16, v35
	v_and_b32_e32 v35, 0xffff0000, v35
	s_waitcnt lgkmcnt(0)
	v_readfirstlane_b32 s48, v36
	v_readfirstlane_b32 s49, v37
	s_add_u32 s48, s48, s0
	s_addc_u32 s49, s49, s1
	s_nop 1
	v_lshl_add_u64 v[138:139], s[48:49], 0, v[0:1]
	global_load_dwordx4 v[140:143], v[138:139], off offset:144
	s_nop 1
	v_lshl_add_u64 v[132:133], s[48:49], 0, v[0:1]
	global_load_dwordx4 v[134:137], v[132:133], off offset:16
	v_mov_b32_e32 v46, v43
	v_mov_b32_e32 v47, v45
	v_lshlrev_b32_e32 v44, 16, v30
	v_and_b32_e32 v42, 0xffff0000, v30
	v_lshlrev_b32_e32 v30, 16, v32
	v_and_b32_e32 v6, 0xffff0000, v32
	v_lshlrev_b32_e32 v31, 16, v33
	v_and_b32_e32 v7, 0xffff0000, v33
	v_lshl_add_u64 v[32:33], s[48:49], 0, v[0:1]
	v_mov_b32_e32 v36, v35
	v_mov_b32_e32 v37, v41
	v_pk_mul_f32 v[46:47], v[46:47], v[46:47]
	flat_load_dwordx4 v[50:53], v[32:33] offset:128
	v_pk_fma_f32 v[36:37], v[36:37], v[36:37], v[46:47]
	flat_load_dwordx4 v[46:49], v[32:33]
	v_mov_b32_e32 v74, v7
	v_mov_b32_e32 v75, v31
	v_pk_mul_f32 v[74:75], v[74:75], v[74:75]
	v_lshlrev_b32_e32 v40, 16, v34
	v_and_b32_e32 v34, 0xffff0000, v34
	v_readlane_b32 s13, v255, 11
	v_readlane_b32 s16, v255, 12
	v_readlane_b32 s17, v255, 13
	v_readlane_b32 s76, v255, 16
	v_readlane_b32 s77, v255, 17
	v_readlane_b32 s78, v255, 18
	v_readlane_b32 s79, v255, 19
	s_mov_b64 s[42:43], s[4:5]
	v_readlane_b32 s4, v255, 20
	v_readlane_b32 s5, v255, 21
	v_readlane_b32 s7, v254, 62
	s_waitcnt vmcnt(0) lgkmcnt(0)
	v_mov_b32_e32 v118, v50
	v_mov_b32_e32 v119, v52
	v_mov_b32_e32 v52, v51
	v_mov_b32_e32 v50, v6
	v_mov_b32_e32 v51, v30
	v_mov_b32_e32 v116, v46
	v_mov_b32_e32 v117, v48
	v_mov_b32_e32 v48, v47
	v_mov_b32_e32 v46, v2
	v_mov_b32_e32 v47, v14
	v_pk_mul_f32 v[50:51], v[50:51], v[50:51]
	s_nop 0
	v_pk_fma_f32 v[46:47], v[46:47], v[46:47], v[50:51]
	v_mov_b32_e32 v50, v3
	v_mov_b32_e32 v51, v15
	v_pk_fma_f32 v[50:51], v[50:51], v[50:51], v[74:75]
	s_waitcnt vmcnt(0)
	s_nop 0
	v_mov_b32_e32 v74, v134
	v_mov_b32_e32 v75, v135
	v_mov_b32_e32 v76, v136
	v_mov_b32_e32 v77, v137
	s_nop 1
	s_waitcnt vmcnt(0)
	s_nop 0
	v_mov_b32_e32 v112, v140
	v_mov_b32_e32 v113, v141
	v_mov_b32_e32 v114, v142
	v_mov_b32_e32 v115, v143
	s_nop 1
	v_mul_f32_e32 v32, v34, v34
	v_mul_f32_e32 v33, v40, v40
	v_fmac_f32_e32 v32, v42, v42
	v_fmac_f32_e32 v33, v44, v44
	v_add_f32_e32 v32, v33, v32
	v_add_f32_e32 v32, v37, v32
	v_add_f32_e32 v32, v36, v32
	v_add_f32_e32 v32, v47, v32
	v_add_f32_e32 v32, v46, v32
	v_add_f32_e32 v32, v51, v32
	v_add_f32_e32 v32, v50, v32
	ds_bpermute_b32 v33, v109, v32
	s_waitcnt lgkmcnt(0)
	v_add_f32_e32 v32, v32, v33
	ds_bpermute_b32 v33, v110, v32
	s_waitcnt lgkmcnt(0)
	v_add_f32_e32 v32, v32, v33
	v_fmamk_f32 v32, v32, 0x3c800000, v219
	v_cmp_gt_f32_e32 vcc, s6, v32
	v_mul_f32_e32 v33, 0x4f800000, v32
	s_nop 0
	v_cndmask_b32_e32 v32, v32, v33, vcc
	v_sqrt_f32_e32 v33, v32
	s_nop 0
	v_add_u32_e32 v36, -1, v33
	v_fma_f32 v37, -v36, v33, v32
	v_cmp_ge_f32_e64 s[88:89], 0, v37
	v_add_u32_e32 v37, 1, v33
	s_nop 0
	v_cndmask_b32_e64 v36, v33, v36, s[88:89]
	v_fma_f32 v33, -v37, v33, v32
	v_cmp_lt_f32_e64 s[88:89], 0, v33
	s_nop 1
	v_cndmask_b32_e64 v33, v36, v37, s[88:89]
	v_mul_f32_e32 v36, 0x37800000, v33
	v_cndmask_b32_e32 v33, v33, v36, vcc
	v_cmp_class_f32_e32 vcc, v32, v221
	s_nop 1
	v_cndmask_b32_e32 v32, v33, v32, vcc
	v_div_scale_f32 v33, s[48:49], v32, v32, 1.0
	v_rcp_f32_e32 v36, v33
	v_readfirstlane_b32 s48, v38
	v_readfirstlane_b32 s49, v39
	s_add_u32 s48, s48, s2
	v_fma_f32 v37, -v33, v36, 1.0
	v_fmac_f32_e32 v36, v37, v36
	v_div_scale_f32 v37, vcc, 1.0, v32, 1.0
	v_mul_f32_e32 v46, v37, v36
	v_fma_f32 v47, -v33, v46, v37
	v_fmac_f32_e32 v46, v47, v36
	v_fma_f32 v33, -v33, v46, v37
	v_div_fmas_f32 v33, v33, v36, v46
	v_div_fixup_f32 v32, v33, v32, 1.0
	v_pk_mul_f32 v[34:35], v[32:33], v[34:35] op_sel_hi:[0,1]
	v_pk_mul_f32 v[34:35], v[34:35], v[48:49]
	v_pk_mul_f32 v[14:15], v[32:33], v[14:15] op_sel_hi:[0,1]
	v_pk_mul_f32 v[30:31], v[32:33], v[30:31] op_sel_hi:[0,1]
	v_pk_mul_f32 v[36:37], v[32:33], v[40:41] op_sel_hi:[0,1]
	v_pk_mul_f32 v[40:41], v[32:33], v[44:45] op_sel_hi:[0,1]
	v_pk_mul_f32 v[42:43], v[32:33], v[42:43] op_sel_hi:[0,1]
	v_pk_mul_f32 v[2:3], v[32:33], v[2:3] op_sel_hi:[0,1]
	v_pk_mul_f32 v[6:7], v[32:33], v[6:7] op_sel_hi:[0,1]
	v_pk_mul_f32 v[40:41], v[118:119], v[40:41]
	v_pk_mul_f32 v[36:37], v[116:117], v[36:37]
	v_pk_mul_f32 v[42:43], v[42:43], v[52:53]
	v_pk_mul_f32 v[44:45], v[102:103], v[40:41]
	s_waitcnt vmcnt(0)
	v_mov_b32_e32 v48, v74
	v_mov_b32_e32 v49, v76
	v_pk_mul_f32 v[14:15], v[14:15], v[48:49]
	v_mov_b32_e32 v48, v112
	v_mov_b32_e32 v49, v114
	v_pk_mul_f32 v[30:31], v[30:31], v[48:49]
	v_mov_b32_e32 v114, v113
	v_pk_mul_f32 v[32:33], v[10:11], v[30:31]
	v_mov_b32_e32 v76, v75
	v_pk_mul_f32 v[6:7], v[6:7], v[114:115]
	v_pk_fma_f32 v[32:33], v[18:19], v[14:15], v[32:33]
	v_pk_mul_f32 v[2:3], v[2:3], v[76:77]
	v_pk_mul_f32 v[48:49], v[32:33], s[86:87] op_sel_hi:[1,0]
	v_pk_mul_f32 v[32:33], v[8:9], v[6:7]
	v_pk_fma_f32 v[44:45], v[104:105], v[36:37], v[44:45]
	v_pk_fma_f32 v[32:33], v[16:17], v[2:3], v[32:33]
	v_pk_mul_f32 v[46:47], v[12:13], v[42:43]
	v_pk_mul_f32 v[50:51], v[32:33], s[86:87] op_sel_hi:[1,0]
	v_pk_mul_f32 v[32:33], v[104:105], v[40:41]
	v_pk_fma_f32 v[46:47], v[20:21], v[34:35], v[46:47]
	v_pk_fma_f32 v[32:33], v[102:103], v[36:37], v[32:33] neg_lo:[0,0,1] neg_hi:[0,0,1]
	v_pk_mul_f32 v[36:37], v[20:21], v[42:43]
	v_pk_mul_f32 v[30:31], v[18:19], v[30:31]
	v_pk_fma_f32 v[34:35], v[12:13], v[34:35], v[36:37] neg_lo:[0,0,1] neg_hi:[0,0,1]
	v_pk_fma_f32 v[14:15], v[10:11], v[14:15], v[30:31] neg_lo:[0,0,1] neg_hi:[0,0,1]
	v_pk_mul_f32 v[34:35], v[34:35], s[86:87] op_sel_hi:[1,0]
	v_pk_mul_f32 v[6:7], v[16:17], v[6:7]
	v_pk_mul_f32 v[14:15], v[14:15], s[86:87] op_sel_hi:[1,0]
	v_pk_fma_f32 v[2:3], v[8:9], v[2:3], v[6:7] neg_lo:[0,0,1] neg_hi:[0,0,1]
	v_bfe_u32 v30, v35, 16, 1
	v_bfe_u32 v31, v34, 16, 1
	v_pk_mul_f32 v[2:3], v[2:3], s[86:87] op_sel_hi:[1,0]
	v_add3_u32 v34, v34, v31, s91
	v_add3_u32 v30, v35, v30, s91
	v_bfe_u32 v31, v14, 16, 1
	v_bfe_u32 v35, v15, 16, 1
	ds_read_b128 v[38:41], v100
	v_pk_mul_f32 v[32:33], v[32:33], s[86:87] op_sel_hi:[1,0]
	v_bfe_u32 v6, v3, 16, 1
	v_bfe_u32 v7, v2, 16, 1
	v_add3_u32 v15, v15, v35, s91
	v_add3_u32 v14, v14, v31, s91
	v_pk_mul_f32 v[44:45], v[44:45], s[86:87] op_sel_hi:[1,0]
	v_add3_u32 v2, v2, v7, s91
	v_add3_u32 v3, v3, v6, s91
	v_bfe_u32 v6, v32, 16, 1
	v_bfe_u32 v7, v33, 16, 1
	v_lshrrev_b32_e32 v14, 16, v14
	v_lshrrev_b32_e32 v15, 16, v15
	v_add3_u32 v7, v33, v7, s91
	v_add3_u32 v6, v32, v6, s91
	v_and_or_b32 v33, v3, s33, v15
	v_and_or_b32 v32, v2, s33, v14
	v_bfe_u32 v14, v44, 16, 1
	v_bfe_u32 v15, v45, 16, 1
	v_add3_u32 v15, v45, v15, s91
	v_add3_u32 v14, v44, v14, s91
	ds_read_b128 v[42:45], v100 offset:64
	v_lshrrev_b32_e32 v6, 16, v6
	v_lshrrev_b32_e32 v7, 16, v7
	v_and_or_b32 v31, v30, s33, v7
	v_and_or_b32 v30, v34, s33, v6
	v_pk_mul_f32 v[46:47], v[46:47], s[86:87] op_sel_hi:[1,0]
	v_bfe_u32 v34, v48, 16, 1
	v_bfe_u32 v35, v49, 16, 1
	s_waitcnt lgkmcnt(1)
	v_mfma_f32_16x16x32_bf16 v[38:41], v[38:41], v[30:33], 0
	v_bfe_u32 v2, v51, 16, 1
	v_bfe_u32 v3, v50, 16, 1
	v_bfe_u32 v6, v47, 16, 1
	v_bfe_u32 v7, v46, 16, 1
	v_add3_u32 v35, v49, v35, s91
	v_add3_u32 v34, v48, v34, s91
	v_add3_u32 v7, v46, v7, s91
	v_add3_u32 v6, v47, v6, s91
	v_add3_u32 v3, v50, v3, s91
	v_add3_u32 v2, v51, v2, s91
	v_lshrrev_b32_e32 v14, 16, v14
	v_lshrrev_b32_e32 v15, 16, v15
	v_lshrrev_b32_e32 v34, 16, v34
	v_lshrrev_b32_e32 v35, 16, v35
	v_and_or_b32 v37, v2, s33, v35
	v_and_or_b32 v36, v3, s33, v34
	v_and_or_b32 v35, v6, s33, v15
	v_and_or_b32 v34, v7, s33, v14
	ds_read_b128 v[46:49], v98 offset:64
	s_addc_u32 s49, s49, s3
	s_nop 1
	v_mov_b64_e32 v[144:145], s[48:49]
	global_load_dword v146, v[144:145], off offset:4
	s_waitcnt lgkmcnt(1)
	v_mfma_f32_16x16x32_bf16 v[38:41], v[42:45], v[34:37], v[38:41]
	ds_read_b128 v[42:45], v98
	v_mov_b64_e32 v[2:3], s[48:49]
	s_waitcnt vmcnt(0)
	s_nop 0
	v_mov_b32_e32 v2, v146
	s_nop 1
	s_waitcnt lgkmcnt(0)
	v_mfma_f32_16x16x32_bf16 v[42:45], v[42:45], v[30:33], 0
	ds_read_b128 v[50:53], v96 offset:64
	ds_read_b128 v[74:77], v94 offset:64
	v_mfma_f32_16x16x32_bf16 v[42:45], v[46:49], v[34:37], v[42:45]
	ds_read_b128 v[46:49], v96
	v_mov_b32_e32 v6, s94
	v_cndmask_b32_e64 v3, v38, v6, s[8:9]
	s_waitcnt lgkmcnt(0)
	v_mfma_f32_16x16x32_bf16 v[46:49], v[46:49], v[30:33], 0
	v_cndmask_b32_e64 v7, v39, v227, s[40:41]
	s_mov_b64 s[40:41], s[80:81]
	v_max3_f32 v6, v3, s94, v7
	v_mfma_f32_16x16x32_bf16 v[46:49], v[50:53], v[34:37], v[46:49]
	ds_read_b128 v[50:53], v94
	ds_read_b128 v[112:115], v92 offset:64
	s_waitcnt lgkmcnt(0)
	v_mfma_f32_16x16x32_bf16 v[50:53], v[50:53], v[30:33], 0
	ds_read_b128 v[116:119], v90 offset:64
	v_cndmask_b32_e64 v14, v40, v227, s[40:41]
	v_cndmask_b32_e64 v15, v41, v227, s[92:93]
	v_mfma_f32_16x16x32_bf16 v[50:53], v[74:77], v[34:37], v[50:53]
	ds_read_b128 v[74:77], v92
	v_readlane_b32 s80, v255, 14
	v_readlane_b32 s81, v255, 15
	s_waitcnt lgkmcnt(0)
	v_mfma_f32_16x16x32_bf16 v[74:77], v[74:77], v[30:33], 0
	v_cndmask_b32_e64 v40, v47, v227, s[80:81]
	v_cndmask_b32_e64 v41, v49, v227, s[84:85]
	v_mfma_f32_16x16x32_bf16 v[74:77], v[112:115], v[34:37], v[74:77]
	ds_read_b128 v[112:115], v90
	ds_read_b128 v[120:123], v88 offset:64
	s_waitcnt lgkmcnt(0)
	v_mfma_f32_16x16x32_bf16 v[112:115], v[112:115], v[30:33], 0
	ds_read_b128 v[124:127], v86 offset:64
	s_nop 2
	v_cndmask_b32_e64 v49, v77, v227, s[26:27]
	v_mfma_f32_16x16x32_bf16 v[112:115], v[116:119], v[34:37], v[112:115]
	ds_read_b128 v[116:119], v88
	s_waitcnt lgkmcnt(0)
	v_mfma_f32_16x16x32_bf16 v[116:119], v[116:119], v[30:33], 0
	v_mfma_f32_16x16x32_bf16 v[116:119], v[120:123], v[34:37], v[116:119]
	ds_read_b128 v[120:123], v86
	ds_read_b128 v[128:131], v84 offset:64
	s_waitcnt lgkmcnt(0)
	v_mfma_f32_16x16x32_bf16 v[120:123], v[120:123], v[30:33], 0
	s_nop 3
	v_cndmask_b32_e64 v77, v119, v227, s[52:53]
	v_mfma_f32_16x16x32_bf16 v[120:123], v[124:127], v[34:37], v[120:123]
	ds_read_b128 v[124:127], v84
	s_waitcnt lgkmcnt(0)
	v_mfma_f32_16x16x32_bf16 v[124:127], v[124:127], v[30:33], 0
	s_nop 4
	v_cndmask_b32_e64 v87, v121, v227, s[56:57]
	v_cndmask_b32_e64 v89, v123, v227, s[60:61]
	v_mfma_f32_16x16x32_bf16 v[124:127], v[128:131], v[34:37], v[124:127]
	ds_read_b128 v[128:131], v82
	s_waitcnt lgkmcnt(0)
	v_mfma_f32_16x16x32_bf16 v[30:33], v[128:131], v[30:33], 0
	ds_read_b128 v[128:131], v82 offset:64
	s_nop 3
	v_cndmask_b32_e64 v95, v125, v227, s[64:65]
	v_cndmask_b32_e64 v97, v127, v227, s[68:69]
	s_waitcnt lgkmcnt(0)
	v_mfma_f32_16x16x32_bf16 v[30:33], v[128:131], v[34:37], v[30:33]
	v_max3_f32 v34, v6, v14, v15
	v_mov_b32_e32 v6, s94
	v_cndmask_b32_e64 v35, v42, v6, s[18:19]
	v_cndmask_b32_e64 v36, v43, v227, s[10:11]
	v_max3_f32 v6, v34, v35, v36
	v_cndmask_b32_e64 v34, v44, v227, s[12:13]
	v_cndmask_b32_e64 v37, v45, v227, s[44:45]
	v_max3_f32 v38, v6, v34, v37
	v_mov_b32_e32 v6, s94
	v_cndmask_b32_e64 v39, v46, v6, s[16:17]
	v_max3_f32 v6, v38, v39, v40
	v_cndmask_b32_e64 v38, v48, v227, s[82:83]
	v_max3_f32 v42, v6, v38, v41
	v_mov_b32_e32 v6, s94
	v_cndmask_b32_e64 v43, v50, v6, s[20:21]
	v_cndmask_b32_e64 v44, v51, v227, s[76:77]
	v_max3_f32 v6, v42, v43, v44
	v_cndmask_b32_e64 v42, v52, v227, s[78:79]
	v_cndmask_b32_e64 v45, v53, v227, s[14:15]
	v_max3_f32 v46, v6, v42, v45
	v_mov_b32_e32 v6, s94
	v_cndmask_b32_e64 v47, v74, v6, s[28:29]
	v_cndmask_b32_e64 v48, v75, v227, s[42:43]
	v_max3_f32 v6, v46, v47, v48
	v_cndmask_b32_e64 v46, v76, v227, s[22:23]
	v_max3_f32 v50, v6, v46, v49
	v_mov_b32_e32 v6, s94
	v_cndmask_b32_e64 v51, v112, v6, s[38:39]
	v_cndmask_b32_e64 v52, v113, v227, s[30:31]
	v_max3_f32 v6, v50, v51, v52
	v_cndmask_b32_e64 v50, v114, v227, s[34:35]
	v_cndmask_b32_e64 v53, v115, v227, s[36:37]
	v_max3_f32 v74, v6, v50, v53
	v_mov_b32_e32 v6, s94
	v_cndmask_b32_e64 v75, v116, v6, s[54:55]
	v_cndmask_b32_e64 v76, v117, v227, s[46:47]
	v_max3_f32 v6, v74, v75, v76
	v_cndmask_b32_e64 v74, v118, v227, s[50:51]
	v_max3_f32 v83, v6, v74, v77
	v_mov_b32_e32 v6, s94
	v_cndmask_b32_e64 v85, v120, v6, s[62:63]
	v_max3_f32 v6, v83, v85, v87
	v_cndmask_b32_e64 v83, v122, v227, s[58:59]
	v_max3_f32 v91, v6, v83, v89
	v_mov_b32_e32 v6, s94
	v_cndmask_b32_e64 v93, v124, v6, s[4:5]
	v_max3_f32 v6, v91, v93, v95
	v_cndmask_b32_e64 v91, v126, v227, s[66:67]
	v_max3_f32 v99, v6, v91, v97
	v_mov_b32_e32 v6, s94
	v_cndmask_b32_e64 v6, v30, v6, s[24:25]
	v_cndmask_b32_e64 v30, v31, v227, s[70:71]
	v_max3_f32 v31, v99, v6, v30
	v_cndmask_b32_e64 v32, v32, v227, s[72:73]
	v_cndmask_b32_e64 v33, v33, v227, s[74:75]
	v_max3_f32 v31, v31, v32, v33
	ds_bpermute_b32 v99, v109, v31
	s_lshl_b32 s94, s7, 1
	s_waitcnt lgkmcnt(0)
	v_max_f32_e32 v99, v99, v99
	v_max_f32_e32 v31, v31, v99
	ds_bpermute_b32 v99, v110, v31
	s_waitcnt vmcnt(0) lgkmcnt(0)
	v_max3_f32 v31, v31, v99, v2
	v_sub_f32_e32 v3, v3, v31
	v_mul_f32_e32 v3, 0x3fb8aa3b, v3
	v_sub_f32_e32 v7, v7, v31
	v_exp_f32_e32 v3, v3
	v_mul_f32_e32 v7, 0x3fb8aa3b, v7
	v_sub_f32_e32 v14, v14, v31
	v_exp_f32_e32 v7, v7
	v_mul_f32_e32 v14, 0x3fb8aa3b, v14
	v_sub_f32_e32 v15, v15, v31
	v_exp_f32_e32 v14, v14
	v_mul_f32_e32 v15, 0x3fb8aa3b, v15
	v_sub_f32_e32 v35, v35, v31
	v_exp_f32_e32 v15, v15
	v_mul_f32_e32 v35, 0x3fb8aa3b, v35
	v_sub_f32_e32 v36, v36, v31
	v_add_f32_e32 v99, 0, v3
	v_exp_f32_e32 v35, v35
	v_mul_f32_e32 v36, 0x3fb8aa3b, v36
	v_sub_f32_e32 v34, v34, v31
	v_add_f32_e32 v99, v7, v99
	v_exp_f32_e32 v36, v36
	v_mul_f32_e32 v34, 0x3fb8aa3b, v34
	v_sub_f32_e32 v37, v37, v31
	v_add_f32_e32 v99, v14, v99
	v_exp_f32_e32 v34, v34
	v_mul_f32_e32 v37, 0x3fb8aa3b, v37
	v_sub_f32_e32 v39, v39, v31
	v_add_f32_e32 v99, v15, v99
	v_exp_f32_e32 v37, v37
	v_mul_f32_e32 v39, 0x3fb8aa3b, v39
	v_add_f32_e32 v99, v35, v99
	v_exp_f32_e32 v101, v39
	v_add_f32_e32 v99, v36, v99
	v_add_f32_e32 v99, v34, v99
	v_sub_f32_e32 v40, v40, v31
	v_add_f32_e32 v99, v37, v99
	v_mul_f32_e32 v40, 0x3fb8aa3b, v40
	v_sub_f32_e32 v38, v38, v31
	v_add_f32_e32 v39, v101, v99
	v_exp_f32_e32 v99, v40
	v_mul_f32_e32 v38, 0x3fb8aa3b, v38
	v_exp_f32_e32 v111, v38
	v_sub_f32_e32 v6, v6, v31
	v_add_f32_e32 v39, v99, v39
	v_mul_f32_e32 v6, 0x3fb8aa3b, v6
	v_add_f32_e32 v38, v111, v39
	v_sub_f32_e32 v39, v41, v31
	v_mul_f32_e32 v39, 0x3fb8aa3b, v39
	v_exp_f32_e32 v112, v39
	v_sub_f32_e32 v39, v43, v31
	v_mul_f32_e32 v39, 0x3fb8aa3b, v39
	v_exp_f32_e32 v113, v39
	v_sub_f32_e32 v39, v44, v31
	v_mul_f32_e32 v39, 0x3fb8aa3b, v39
	v_exp_f32_e32 v114, v39
	v_sub_f32_e32 v39, v42, v31
	v_mul_f32_e32 v39, 0x3fb8aa3b, v39
	v_exp_f32_e32 v115, v39
	v_sub_f32_e32 v39, v45, v31
	v_mul_f32_e32 v39, 0x3fb8aa3b, v39
	v_exp_f32_e32 v116, v39
	v_sub_f32_e32 v39, v47, v31
	v_mul_f32_e32 v39, 0x3fb8aa3b, v39
	v_exp_f32_e32 v117, v39
	v_sub_f32_e32 v39, v48, v31
	v_mul_f32_e32 v39, 0x3fb8aa3b, v39
	v_exp_f32_e32 v118, v39
	v_sub_f32_e32 v39, v46, v31
	v_mul_f32_e32 v39, 0x3fb8aa3b, v39
	v_exp_f32_e32 v119, v39
	v_sub_f32_e32 v39, v49, v31
	v_mul_f32_e32 v39, 0x3fb8aa3b, v39
	v_exp_f32_e32 v120, v39
	v_sub_f32_e32 v39, v51, v31
	v_mul_f32_e32 v39, 0x3fb8aa3b, v39
	v_exp_f32_e32 v121, v39
	v_sub_f32_e32 v39, v52, v31
	v_mul_f32_e32 v39, 0x3fb8aa3b, v39
	v_exp_f32_e32 v122, v39
	v_sub_f32_e32 v39, v50, v31
	v_mul_f32_e32 v39, 0x3fb8aa3b, v39
	v_exp_f32_e32 v123, v39
	v_sub_f32_e32 v39, v53, v31
	v_mul_f32_e32 v39, 0x3fb8aa3b, v39
	v_exp_f32_e32 v124, v39
	v_sub_f32_e32 v39, v75, v31
	v_mul_f32_e32 v39, 0x3fb8aa3b, v39
	v_exp_f32_e32 v75, v39
	v_sub_f32_e32 v39, v76, v31
	v_mul_f32_e32 v39, 0x3fb8aa3b, v39
	v_add_f32_e32 v38, v112, v38
	v_exp_f32_e32 v76, v39
	v_sub_f32_e32 v39, v74, v31
	v_add_f32_e32 v38, v113, v38
	v_mul_f32_e32 v39, 0x3fb8aa3b, v39
	v_add_f32_e32 v38, v114, v38
	v_exp_f32_e32 v74, v39
	v_sub_f32_e32 v39, v77, v31
	v_add_f32_e32 v38, v115, v38
	v_mul_f32_e32 v39, 0x3fb8aa3b, v39
	v_add_f32_e32 v38, v116, v38
	v_exp_f32_e32 v77, v39
	v_sub_f32_e32 v39, v85, v31
	v_add_f32_e32 v38, v117, v38
	v_mul_f32_e32 v39, 0x3fb8aa3b, v39
	v_add_f32_e32 v38, v118, v38
	v_exp_f32_e32 v85, v39
	v_sub_f32_e32 v39, v87, v31
	v_add_f32_e32 v38, v119, v38
	v_mul_f32_e32 v39, 0x3fb8aa3b, v39
	v_add_f32_e32 v38, v120, v38
	v_exp_f32_e32 v87, v39
	v_sub_f32_e32 v39, v83, v31
	v_add_f32_e32 v38, v121, v38
	v_mul_f32_e32 v39, 0x3fb8aa3b, v39
	v_add_f32_e32 v38, v122, v38
	v_exp_f32_e32 v83, v39
	v_sub_f32_e32 v39, v89, v31
	v_add_f32_e32 v38, v123, v38
	v_mul_f32_e32 v39, 0x3fb8aa3b, v39
	v_add_f32_e32 v38, v124, v38
	v_exp_f32_e32 v89, v39
	v_sub_f32_e32 v39, v93, v31
	v_add_f32_e32 v38, v75, v38
	v_mul_f32_e32 v39, 0x3fb8aa3b, v39
	v_add_f32_e32 v38, v76, v38
	v_exp_f32_e32 v93, v39
	v_sub_f32_e32 v39, v95, v31
	v_add_f32_e32 v38, v74, v38
	v_mul_f32_e32 v39, 0x3fb8aa3b, v39
	v_add_f32_e32 v38, v77, v38
	v_exp_f32_e32 v95, v39
	v_sub_f32_e32 v39, v91, v31
	v_add_f32_e32 v38, v85, v38
	v_mul_f32_e32 v39, 0x3fb8aa3b, v39
	v_add_f32_e32 v38, v87, v38
	v_exp_f32_e32 v91, v39
	v_sub_f32_e32 v39, v97, v31
	v_add_f32_e32 v38, v83, v38
	v_mul_f32_e32 v39, 0x3fb8aa3b, v39
	v_add_f32_e32 v38, v89, v38
	v_exp_f32_e32 v97, v39
	v_sub_f32_e32 v30, v30, v31
	v_sub_f32_e32 v32, v32, v31
	v_add_f32_e32 v38, v93, v38
	v_exp_f32_e32 v6, v6
	v_mul_f32_e32 v30, 0x3fb8aa3b, v30
	v_mul_f32_e32 v32, 0x3fb8aa3b, v32
	v_add_f32_e32 v38, v95, v38
	v_exp_f32_e32 v125, v30
	v_exp_f32_e32 v126, v32
	v_sub_f32_e32 v32, v33, v31
	v_add_f32_e32 v38, v91, v38
	v_mul_f32_e32 v32, 0x3fb8aa3b, v32
	v_add_f32_e32 v38, v97, v38
	v_exp_f32_e32 v127, v32
	v_add_f32_e32 v38, v6, v38
	v_add_f32_e32 v30, v125, v38
	v_add_f32_e32 v30, v126, v30
	v_add_f32_e32 v30, v127, v30
	ds_bpermute_b32 v32, v109, v30
	v_sub_f32_e32 v2, v2, v31
	v_mul_f32_e32 v2, 0x3fb8aa3b, v2
	v_exp_f32_e32 v2, v2
	v_bfe_u32 v31, v36, 16, 1
	s_waitcnt lgkmcnt(0)
	v_add_f32_e32 v30, v30, v32
	ds_bpermute_b32 v32, v110, v30
	v_bfe_u32 v33, v7, 16, 1
	v_add3_u32 v31, v36, v31, s91
	v_bfe_u32 v36, v35, 16, 1
	v_add3_u32 v7, v7, v33, s91
	s_waitcnt lgkmcnt(0)
	v_add_f32_e32 v30, v30, v32
	v_add_f32_e32 v2, v2, v30
	v_bfe_u32 v30, v37, 16, 1
	v_bfe_u32 v32, v15, 16, 1
	v_add3_u32 v30, v37, v30, s91
	v_bfe_u32 v37, v34, 16, 1
	v_add3_u32 v15, v15, v32, s91
	v_bfe_u32 v32, v3, 16, 1
	v_bfe_u32 v33, v14, 16, 1
	v_add3_u32 v34, v34, v37, s91
	v_add3_u32 v35, v35, v36, s91
	v_add3_u32 v14, v14, v33, s91
	v_add3_u32 v3, v3, v32, s91
	v_lshrrev_b32_e32 v32, 16, v35
	v_lshrrev_b32_e32 v33, 16, v34
	ds_read2_b64 v[34:37], v73 offset1:4
	ds_read2_b64 v[38:41], v72 offset0:32 offset1:36
	ds_read2_b64 v[42:45], v71 offset0:64 offset1:68
	ds_read2_b64 v[46:49], v70 offset0:96 offset1:100
	ds_read2_b64 v[50:53], v69 offset1:4
	v_lshrrev_b32_e32 v3, 16, v3
	v_lshrrev_b32_e32 v14, 16, v14
	v_and_or_b32 v33, v30, s33, v33
	v_and_or_b32 v32, v31, s33, v32
	v_and_or_b32 v31, v15, s33, v14
	v_and_or_b32 v30, v7, s33, v3
	v_bfe_u32 v3, v116, 16, 1
	v_bfe_u32 v7, v114, 16, 1
	s_waitcnt lgkmcnt(4)
	v_mfma_f32_16x16x32_bf16 v[34:37], v[34:37], v[30:33], 0
	v_bfe_u32 v14, v112, 16, 1
	v_bfe_u32 v15, v99, 16, 1
	v_add3_u32 v15, v99, v15, s91
	s_waitcnt lgkmcnt(3)
	v_mfma_f32_16x16x32_bf16 v[38:41], v[38:41], v[30:33], 0
	v_add3_u32 v14, v112, v14, s91
	v_add3_u32 v7, v114, v7, s91
	v_add3_u32 v3, v116, v3, s91
	s_waitcnt lgkmcnt(2)
	v_mfma_f32_16x16x32_bf16 v[42:45], v[42:45], v[30:33], 0
	s_waitcnt lgkmcnt(1)
	v_mfma_f32_16x16x32_bf16 v[30:33], v[46:49], v[30:33], 0
	v_bfe_u32 v46, v101, 16, 1
	v_bfe_u32 v47, v111, 16, 1
	v_bfe_u32 v48, v113, 16, 1
	v_bfe_u32 v49, v115, 16, 1
	v_add3_u32 v49, v115, v49, s91
	v_add3_u32 v48, v113, v48, s91
	v_add3_u32 v47, v111, v47, s91
	v_add3_u32 v46, v101, v46, s91
	v_lshrrev_b32_e32 v46, 16, v46
	v_lshrrev_b32_e32 v47, 16, v47
	v_lshrrev_b32_e32 v48, 16, v48
	v_lshrrev_b32_e32 v49, 16, v49
	v_and_or_b32 v49, v3, s33, v49
	v_and_or_b32 v48, v7, s33, v48
	v_and_or_b32 v47, v14, s33, v47
	v_and_or_b32 v46, v15, s33, v46
	v_bfe_u32 v3, v124, 16, 1
	v_bfe_u32 v7, v122, 16, 1
	s_waitcnt lgkmcnt(0)
	v_mfma_f32_16x16x32_bf16 v[34:37], v[50:53], v[46:49], v[34:37]
	ds_read2_b64 v[50:53], v68 offset0:32 offset1:36
	v_bfe_u32 v14, v120, 16, 1
	v_bfe_u32 v15, v118, 16, 1
	s_waitcnt lgkmcnt(0)
	v_mfma_f32_16x16x32_bf16 v[38:41], v[50:53], v[46:49], v[38:41]
	ds_read2_b64 v[50:53], v67 offset0:64 offset1:68
	v_add3_u32 v15, v118, v15, s91
	v_add3_u32 v14, v120, v14, s91
	s_waitcnt lgkmcnt(0)
	v_mfma_f32_16x16x32_bf16 v[42:45], v[50:53], v[46:49], v[42:45]
	ds_read2_b64 v[50:53], v66 offset0:96 offset1:100
	v_add3_u32 v7, v122, v7, s91
	s_waitcnt lgkmcnt(0)
	v_mfma_f32_16x16x32_bf16 v[30:33], v[50:53], v[46:49], v[30:33]
	ds_read2_b64 v[50:53], v65 offset1:4
	v_bfe_u32 v46, v117, 16, 1
	v_bfe_u32 v47, v119, 16, 1
	v_bfe_u32 v48, v121, 16, 1
	v_bfe_u32 v49, v123, 16, 1
	v_add3_u32 v49, v123, v49, s91
	v_add3_u32 v48, v121, v48, s91
	v_add3_u32 v47, v119, v47, s91
	v_add3_u32 v46, v117, v46, s91
	v_add3_u32 v3, v124, v3, s91
	v_lshrrev_b32_e32 v46, 16, v46
	v_lshrrev_b32_e32 v47, 16, v47
	v_lshrrev_b32_e32 v48, 16, v48
	v_lshrrev_b32_e32 v49, 16, v49
	v_and_or_b32 v49, v3, s33, v49
	v_and_or_b32 v48, v7, s33, v48
	v_and_or_b32 v47, v14, s33, v47
	v_and_or_b32 v46, v15, s33, v46
	v_bfe_u32 v3, v89, 16, 1
	v_bfe_u32 v7, v87, 16, 1
	s_waitcnt lgkmcnt(0)
	v_mfma_f32_16x16x32_bf16 v[34:37], v[50:53], v[46:49], v[34:37]
	ds_read2_b64 v[50:53], v64 offset0:32 offset1:36
	v_bfe_u32 v14, v77, 16, 1
	v_bfe_u32 v15, v76, 16, 1
	s_waitcnt lgkmcnt(0)
	v_mfma_f32_16x16x32_bf16 v[38:41], v[50:53], v[46:49], v[38:41]
	ds_read2_b64 v[50:53], v63 offset0:64 offset1:68
	v_add3_u32 v15, v76, v15, s91
	v_add3_u32 v14, v77, v14, s91
	s_waitcnt lgkmcnt(0)
	v_mfma_f32_16x16x32_bf16 v[42:45], v[50:53], v[46:49], v[42:45]
	ds_read2_b64 v[50:53], v62 offset0:96 offset1:100
	v_add3_u32 v7, v87, v7, s91
	s_waitcnt lgkmcnt(0)
	v_mfma_f32_16x16x32_bf16 v[30:33], v[50:53], v[46:49], v[30:33]
	ds_read2_b64 v[50:53], v61 offset1:4
	v_bfe_u32 v46, v75, 16, 1
	v_bfe_u32 v47, v74, 16, 1
	v_bfe_u32 v48, v85, 16, 1
	v_bfe_u32 v49, v83, 16, 1
	v_add3_u32 v49, v83, v49, s91
	v_add3_u32 v48, v85, v48, s91
	v_add3_u32 v47, v74, v47, s91
	v_add3_u32 v46, v75, v46, s91
	v_add3_u32 v3, v89, v3, s91
	v_lshrrev_b32_e32 v46, 16, v46
	v_lshrrev_b32_e32 v47, 16, v47
	v_lshrrev_b32_e32 v48, 16, v48
	v_lshrrev_b32_e32 v49, 16, v49
	v_and_or_b32 v49, v3, s33, v49
	v_and_or_b32 v48, v7, s33, v48
	v_and_or_b32 v47, v14, s33, v47
	v_and_or_b32 v46, v15, s33, v46
	v_bfe_u32 v3, v127, 16, 1
	v_bfe_u32 v14, v97, 16, 1
	s_waitcnt lgkmcnt(0)
	v_mfma_f32_16x16x32_bf16 v[34:37], v[50:53], v[46:49], v[34:37]
	ds_read2_b64 v[50:53], v60 offset0:32 offset1:36
	v_bfe_u32 v15, v95, 16, 1
	v_add3_u32 v15, v95, v15, s91
	s_waitcnt lgkmcnt(0)
	v_mfma_f32_16x16x32_bf16 v[38:41], v[50:53], v[46:49], v[38:41]
	ds_read2_b64 v[50:53], v59 offset0:64 offset1:68
	v_add3_u32 v14, v97, v14, s91
	v_add3_u32 v3, v127, v3, s91
	s_waitcnt lgkmcnt(0)
	v_mfma_f32_16x16x32_bf16 v[50:53], v[50:53], v[46:49], v[42:45]
	s_nop 2
	ds_read2_b64 v[42:45], v58 offset0:96 offset1:100
	v_bfe_u32 v7, v125, 16, 1
	s_waitcnt lgkmcnt(0)
	v_mfma_f32_16x16x32_bf16 v[30:33], v[42:45], v[46:49], v[30:33]
	v_bfe_u32 v42, v93, 16, 1
	v_bfe_u32 v43, v91, 16, 1
	v_bfe_u32 v45, v126, 16, 1
	v_bfe_u32 v44, v6, 16, 1
	v_add3_u32 v45, v126, v45, s91
	v_add3_u32 v43, v91, v43, s91
	v_add3_u32 v42, v93, v42, s91
	v_add3_u32 v6, v6, v44, s91
	v_lshrrev_b32_e32 v42, 16, v42
	v_lshrrev_b32_e32 v43, 16, v43
	v_lshrrev_b32_e32 v44, 16, v45
	v_and_or_b32 v49, v3, s33, v44
	v_and_or_b32 v47, v14, s33, v43
	v_and_or_b32 v46, v15, s33, v42
	ds_read2_b64 v[42:45], v57 offset1:4
	v_add3_u32 v7, v125, v7, s91
	v_lshrrev_b32_e32 v6, 16, v6
	v_and_or_b32 v48, v7, s33, v6
	v_div_scale_f32 v3, s[48:49], v2, v2, 1.0
	s_waitcnt lgkmcnt(0)
	v_mfma_f32_16x16x32_bf16 v[42:45], v[42:45], v[46:49], v[34:37]
	s_nop 2
	ds_read2_b64 v[34:37], v56 offset0:32 offset1:36
	v_rcp_f32_e32 v6, v3
	s_waitcnt lgkmcnt(0)
	v_mfma_f32_16x16x32_bf16 v[38:41], v[34:37], v[46:49], v[38:41]
	v_fma_f32 v7, -v3, v6, 1.0
	v_fmac_f32_e32 v6, v7, v6
	v_div_scale_f32 v7, vcc, 1.0, v2, 1.0
	v_mul_f32_e32 v14, v7, v6
	v_fma_f32 v15, -v3, v14, v7
	v_fmac_f32_e32 v14, v15, v6
	ds_read2_b64 v[34:37], v55 offset0:64 offset1:68
	v_fma_f32 v3, -v3, v14, v7
	v_div_fmas_f32 v3, v3, v6, v14
	v_div_fixup_f32 v2, v3, v2, 1.0
	v_mov_b32_e32 v14, v42
	v_mov_b32_e32 v15, v44
	v_pk_mul_f32 v[14:15], v[2:3], v[14:15] op_sel_hi:[0,1]
	v_mov_b32_e32 v44, v43
	v_pk_mul_f32 v[42:43], v[2:3], v[44:45] op_sel_hi:[0,1]
	v_and_b32_sdwa v3, v15, v218 dst_sel:DWORD dst_unused:UNUSED_PAD src0_sel:WORD_1 src1_sel:DWORD
	v_and_b32_sdwa v44, v14, v218 dst_sel:DWORD dst_unused:UNUSED_PAD src0_sel:WORD_1 src1_sel:DWORD
	v_add3_u32 v14, v14, v44, s91
	v_add3_u32 v3, v15, v3, s91
	v_and_b32_sdwa v15, v43, v218 dst_sel:DWORD dst_unused:UNUSED_PAD src0_sel:WORD_1 src1_sel:DWORD
	v_and_b32_sdwa v44, v42, v218 dst_sel:DWORD dst_unused:UNUSED_PAD src0_sel:WORD_1 src1_sel:DWORD
	v_add3_u32 v15, v43, v15, s91
	v_add3_u32 v42, v42, v44, s91
	v_and_b32_e32 v15, 0xffff0000, v15
	v_and_b32_e32 v42, 0xffff0000, v42
	v_lshl_add_u64 v[6:7], v[80:81], 0, s[94:95]
	v_or_b32_sdwa v15, v15, v3 dst_sel:DWORD dst_unused:UNUSED_PAD src0_sel:DWORD src1_sel:WORD_1
	v_or_b32_sdwa v14, v42, v14 dst_sel:DWORD dst_unused:UNUSED_PAD src0_sel:DWORD src1_sel:WORD_1
	s_waitcnt lgkmcnt(0)
	v_mfma_f32_16x16x32_bf16 v[34:37], v[34:37], v[46:49], v[50:53]
	v_lshlrev_b32_e32 v44, 16, v22
	v_lshlrev_b32_e32 v45, 16, v23
	v_and_b32_e32 v42, 0xffff0000, v28
	ds_read2_b64 v[50:53], v54 offset0:96 offset1:100
	flat_store_dwordx2 v[6:7], v[14:15]
	v_mov_b32_e32 v14, v38
	v_mov_b32_e32 v15, v40
	v_pk_mul_f32 v[14:15], v[2:3], v[14:15] op_sel_hi:[0,1]
	v_mov_b32_e32 v40, v39
	v_pk_mul_f32 v[38:39], v[2:3], v[40:41] op_sel_hi:[0,1]
	v_and_b32_sdwa v3, v15, v218 dst_sel:DWORD dst_unused:UNUSED_PAD src0_sel:WORD_1 src1_sel:DWORD
	v_and_b32_sdwa v40, v14, v218 dst_sel:DWORD dst_unused:UNUSED_PAD src0_sel:WORD_1 src1_sel:DWORD
	v_add3_u32 v14, v14, v40, s91
	v_add3_u32 v3, v15, v3, s91
	v_and_b32_sdwa v15, v39, v218 dst_sel:DWORD dst_unused:UNUSED_PAD src0_sel:WORD_1 src1_sel:DWORD
	v_and_b32_sdwa v40, v38, v218 dst_sel:DWORD dst_unused:UNUSED_PAD src0_sel:WORD_1 src1_sel:DWORD
	v_add3_u32 v15, v39, v15, s91
	v_add3_u32 v38, v38, v40, s91
	v_and_b32_e32 v15, 0xffff0000, v15
	v_and_b32_e32 v38, 0xffff0000, v38
	v_or_b32_sdwa v15, v15, v3 dst_sel:DWORD dst_unused:UNUSED_PAD src0_sel:DWORD src1_sel:WORD_1
	v_or_b32_sdwa v14, v38, v14 dst_sel:DWORD dst_unused:UNUSED_PAD src0_sel:DWORD src1_sel:WORD_1
	flat_store_dwordx2 v[6:7], v[14:15] offset:32
	v_mov_b32_e32 v14, v34
	v_mov_b32_e32 v15, v36
	v_pk_mul_f32 v[14:15], v[2:3], v[14:15] op_sel_hi:[0,1]
	v_mov_b32_e32 v36, v35
	v_pk_mul_f32 v[34:35], v[2:3], v[36:37] op_sel_hi:[0,1]
	v_and_b32_sdwa v3, v15, v218 dst_sel:DWORD dst_unused:UNUSED_PAD src0_sel:WORD_1 src1_sel:DWORD
	v_and_b32_sdwa v36, v14, v218 dst_sel:DWORD dst_unused:UNUSED_PAD src0_sel:WORD_1 src1_sel:DWORD
	s_waitcnt lgkmcnt(0)
	v_mfma_f32_16x16x32_bf16 v[30:33], v[50:53], v[46:49], v[30:33]
	v_add3_u32 v14, v14, v36, s91
	v_add3_u32 v3, v15, v3, s91
	v_and_b32_sdwa v15, v35, v218 dst_sel:DWORD dst_unused:UNUSED_PAD src0_sel:WORD_1 src1_sel:DWORD
	v_and_b32_sdwa v36, v34, v218 dst_sel:DWORD dst_unused:UNUSED_PAD src0_sel:WORD_1 src1_sel:DWORD
	v_add3_u32 v15, v35, v15, s91
	v_add3_u32 v34, v34, v36, s91
	v_and_b32_e32 v15, 0xffff0000, v15
	v_and_b32_e32 v34, 0xffff0000, v34
	v_or_b32_sdwa v15, v15, v3 dst_sel:DWORD dst_unused:UNUSED_PAD src0_sel:DWORD src1_sel:WORD_1
	v_or_b32_sdwa v14, v34, v14 dst_sel:DWORD dst_unused:UNUSED_PAD src0_sel:DWORD src1_sel:WORD_1
	flat_store_dwordx2 v[6:7], v[14:15] offset:64
	v_mov_b32_e32 v14, v30
	v_mov_b32_e32 v15, v32
	v_pk_mul_f32 v[14:15], v[2:3], v[14:15] op_sel_hi:[0,1]
	v_mov_b32_e32 v32, v31
	v_pk_mul_f32 v[2:3], v[2:3], v[32:33] op_sel_hi:[0,1]
	v_and_b32_sdwa v30, v15, v218 dst_sel:DWORD dst_unused:UNUSED_PAD src0_sel:WORD_1 src1_sel:DWORD
	v_and_b32_sdwa v31, v14, v218 dst_sel:DWORD dst_unused:UNUSED_PAD src0_sel:WORD_1 src1_sel:DWORD
	v_add3_u32 v14, v14, v31, s91
	v_add3_u32 v15, v15, v30, s91
	v_and_b32_sdwa v30, v3, v218 dst_sel:DWORD dst_unused:UNUSED_PAD src0_sel:WORD_1 src1_sel:DWORD
	v_and_b32_sdwa v31, v2, v218 dst_sel:DWORD dst_unused:UNUSED_PAD src0_sel:WORD_1 src1_sel:DWORD
	v_add3_u32 v3, v3, v30, s91
	v_add3_u32 v2, v2, v31, s91
	v_and_b32_e32 v3, 0xffff0000, v3
	v_and_b32_e32 v2, 0xffff0000, v2
	v_or_b32_sdwa v3, v3, v15 dst_sel:DWORD dst_unused:UNUSED_PAD src0_sel:DWORD src1_sel:WORD_1
	v_or_b32_sdwa v2, v2, v14 dst_sel:DWORD dst_unused:UNUSED_PAD src0_sel:DWORD src1_sel:WORD_1
	flat_store_dwordx2 v[6:7], v[2:3] offset:96
	v_and_b32_e32 v46, 0xffff0000, v22
	v_and_b32_e32 v47, 0xffff0000, v23
	v_lshlrev_b32_e32 v48, 16, v24
	v_and_b32_e32 v50, 0xffff0000, v24
	v_lshlrev_b32_e32 v49, 16, v25
	v_and_b32_e32 v51, 0xffff0000, v25
	ds_read2_b64 v[22:25], v79 offset1:1
	v_lshlrev_b32_e32 v3, 16, v27
	v_and_b32_e32 v7, 0xffff0000, v27
	v_lshlrev_b32_e32 v14, 16, v28
	v_lshlrev_b32_e32 v15, 16, v29
	s_waitcnt lgkmcnt(0)
	v_readfirstlane_b32 s48, v22
	v_readfirstlane_b32 s49, v23
	s_add_u32 s0, s48, s0
	v_and_b32_e32 v43, 0xffff0000, v29
	s_addc_u32 s1, s49, s1
	s_nop 1
	v_lshl_add_u64 v[138:139], s[0:1], 0, v[0:1]
	global_load_dwordx4 v[140:143], v[138:139], off offset:144
	s_nop 1
	v_lshl_add_u64 v[132:133], s[0:1], 0, v[0:1]
	global_load_dwordx4 v[134:137], v[132:133], off offset:16
	v_mov_b32_e32 v28, v47
	v_mov_b32_e32 v29, v45
	v_lshlrev_b32_e32 v2, 16, v26
	v_and_b32_e32 v6, 0xffff0000, v26
	v_lshl_add_u64 v[22:23], s[0:1], 0, v[0:1]
	v_mov_b32_e32 v26, v7
	v_mov_b32_e32 v27, v3
	v_pk_mul_f32 v[28:29], v[28:29], v[28:29]
	flat_load_dwordx4 v[30:33], v[22:23] offset:128
	v_pk_fma_f32 v[52:53], v[26:27], v[26:27], v[28:29]
	flat_load_dwordx4 v[26:29], v[22:23]
	v_mov_b32_e32 v34, v51
	v_mov_b32_e32 v35, v49
	v_pk_mul_f32 v[34:35], v[34:35], v[34:35]
	v_mul_f32_e32 v0, v6, v6
	v_fmac_f32_e32 v0, v46, v46
	s_waitcnt vmcnt(0) lgkmcnt(0)
	v_mov_b32_e32 v76, v30
	v_mov_b32_e32 v77, v32
	v_mov_b32_e32 v32, v31
	v_mov_b32_e32 v30, v50
	v_mov_b32_e32 v31, v48
	v_mov_b32_e32 v74, v26
	v_mov_b32_e32 v75, v28
	v_mov_b32_e32 v28, v27
	v_mov_b32_e32 v26, v42
	v_mov_b32_e32 v27, v14
	v_pk_mul_f32 v[30:31], v[30:31], v[30:31]
	s_nop 0
	v_pk_fma_f32 v[26:27], v[26:27], v[26:27], v[30:31]
	v_mov_b32_e32 v30, v43
	v_mov_b32_e32 v31, v15
	v_pk_fma_f32 v[30:31], v[30:31], v[30:31], v[34:35]
	s_waitcnt vmcnt(0)
	s_nop 0
	v_mov_b32_e32 v34, v134
	v_mov_b32_e32 v35, v135
	v_mov_b32_e32 v36, v136
	v_mov_b32_e32 v37, v137
	s_nop 1
	s_waitcnt vmcnt(0)
	s_nop 0
	v_mov_b32_e32 v38, v140
	v_mov_b32_e32 v39, v141
	v_mov_b32_e32 v40, v142
	v_mov_b32_e32 v41, v143
	s_nop 1
	v_mul_f32_e32 v22, v2, v2
	v_fmac_f32_e32 v22, v44, v44
	v_add_f32_e32 v0, v22, v0
	v_add_f32_e32 v0, v53, v0
	v_add_f32_e32 v0, v52, v0
	v_add_f32_e32 v0, v27, v0
	v_add_f32_e32 v0, v26, v0
	v_add_f32_e32 v0, v31, v0
	v_add_f32_e32 v0, v30, v0
	ds_bpermute_b32 v22, v109, v0
	s_waitcnt lgkmcnt(0)
	v_add_f32_e32 v0, v0, v22
	ds_bpermute_b32 v22, v110, v0
	s_waitcnt lgkmcnt(0)
	v_add_f32_e32 v0, v0, v22
	v_fmamk_f32 v0, v0, 0x3c800000, v219
	v_cmp_gt_f32_e32 vcc, s6, v0
	v_mul_f32_e32 v22, 0x4f800000, v0
	s_nop 0
	v_cndmask_b32_e32 v0, v0, v22, vcc
	v_sqrt_f32_e32 v22, v0
	s_nop 0
	v_add_u32_e32 v23, -1, v22
	v_fma_f32 v26, -v23, v22, v0
	v_cmp_ge_f32_e64 s[88:89], 0, v26
	v_add_u32_e32 v26, 1, v22
	s_nop 0
	v_cndmask_b32_e64 v23, v22, v23, s[88:89]
	v_fma_f32 v22, -v26, v22, v0
	v_cmp_lt_f32_e64 s[88:89], 0, v22
	s_nop 1
	v_cndmask_b32_e64 v22, v23, v26, s[88:89]
	v_mul_f32_e32 v23, 0x37800000, v22
	v_cndmask_b32_e32 v22, v22, v23, vcc
	v_cmp_class_f32_e32 vcc, v0, v221
	s_mov_b32 s89, 0xf149f2ca
	s_movk_i32 s88, 0x90
	v_cndmask_b32_e32 v0, v22, v0, vcc
	v_div_scale_f32 v22, s[0:1], v0, v0, 1.0
	v_rcp_f32_e32 v23, v22
	v_readfirstlane_b32 s0, v24
	v_readfirstlane_b32 s1, v25
	s_add_u32 s0, s0, s2
	v_fma_f32 v26, -v22, v23, 1.0
	v_fmac_f32_e32 v23, v26, v23
	v_div_scale_f32 v26, vcc, 1.0, v0, 1.0
	v_mul_f32_e32 v27, v26, v23
	v_fma_f32 v30, -v22, v27, v26
	v_fmac_f32_e32 v27, v30, v23
	v_fma_f32 v22, -v22, v27, v26
	v_div_fmas_f32 v22, v22, v23, v27
	v_div_fixup_f32 v0, v22, v0, 1.0
	v_pk_mul_f32 v[26:27], v[0:1], v[46:47] op_sel_hi:[0,1]
	v_pk_mul_f32 v[6:7], v[0:1], v[6:7] op_sel_hi:[0,1]
	v_pk_mul_f32 v[26:27], v[26:27], v[32:33]
	v_pk_mul_f32 v[14:15], v[0:1], v[14:15] op_sel_hi:[0,1]
	v_pk_mul_f32 v[22:23], v[0:1], v[44:45] op_sel_hi:[0,1]
	v_pk_mul_f32 v[6:7], v[6:7], v[28:29]
	v_pk_mul_f32 v[30:31], v[12:13], v[26:27]
	v_pk_mul_f32 v[42:43], v[0:1], v[42:43] op_sel_hi:[0,1]
	v_pk_fma_f32 v[30:31], v[20:21], v[6:7], v[30:31]
	v_pk_mul_f32 v[20:21], v[20:21], v[26:27]
	v_pk_mul_f32 v[2:3], v[0:1], v[2:3] op_sel_hi:[0,1]
	v_pk_fma_f32 v[6:7], v[12:13], v[6:7], v[20:21] neg_lo:[0,0,1] neg_hi:[0,0,1]
	v_pk_mul_f32 v[22:23], v[76:77], v[22:23]
	v_pk_mul_f32 v[2:3], v[74:75], v[2:3]
	v_pk_mul_f32 v[28:29], v[102:103], v[22:23]
	s_waitcnt vmcnt(0)
	v_mov_b32_e32 v32, v34
	v_mov_b32_e32 v33, v36
	v_pk_mul_f32 v[14:15], v[14:15], v[32:33]
	v_pk_mul_f32 v[32:33], v[0:1], v[48:49] op_sel_hi:[0,1]
	v_mov_b32_e32 v44, v38
	v_mov_b32_e32 v45, v40
	v_mov_b32_e32 v36, v35
	v_pk_mul_f32 v[32:33], v[32:33], v[44:45]
	v_pk_mul_f32 v[34:35], v[42:43], v[36:37]
	v_pk_mul_f32 v[36:37], v[0:1], v[50:51] op_sel_hi:[0,1]
	v_mov_b32_e32 v40, v39
	v_pk_mul_f32 v[36:37], v[36:37], v[40:41]
	v_pk_mul_f32 v[12:13], v[18:19], v[32:33]
	v_pk_mul_f32 v[38:39], v[10:11], v[32:33]
	v_pk_fma_f32 v[10:11], v[10:11], v[14:15], v[12:13] neg_lo:[0,0,1] neg_hi:[0,0,1]
	v_pk_mul_f32 v[12:13], v[16:17], v[36:37]
	v_pk_mul_f32 v[40:41], v[8:9], v[36:37]
	v_pk_mul_f32 v[22:23], v[104:105], v[22:23]
	v_pk_mul_f32 v[6:7], v[6:7], s[86:87] op_sel_hi:[1,0]
	v_pk_fma_f32 v[8:9], v[8:9], v[34:35], v[12:13] neg_lo:[0,0,1] neg_hi:[0,0,1]
	v_pk_fma_f32 v[28:29], v[104:105], v[2:3], v[28:29]
	v_pk_fma_f32 v[38:39], v[18:19], v[14:15], v[38:39]
	v_pk_fma_f32 v[2:3], v[102:103], v[2:3], v[22:23] neg_lo:[0,0,1] neg_hi:[0,0,1]
	v_pk_mul_f32 v[10:11], v[10:11], s[86:87] op_sel_hi:[1,0]
	v_pk_mul_f32 v[8:9], v[8:9], s[86:87] op_sel_hi:[1,0]
	v_bfe_u32 v13, v7, 16, 1
	v_bfe_u32 v14, v6, 16, 1
	v_pk_mul_f32 v[2:3], v[2:3], s[86:87] op_sel_hi:[1,0]
	v_bfe_u32 v0, v9, 16, 1
	v_add3_u32 v6, v6, v14, s91
	v_add3_u32 v7, v7, v13, s91
	v_bfe_u32 v13, v10, 16, 1
	v_bfe_u32 v14, v11, 16, 1
	v_pk_mul_f32 v[28:29], v[28:29], s[86:87] op_sel_hi:[1,0]
	v_bfe_u32 v12, v8, 16, 1
	v_add3_u32 v0, v9, v0, s91
	v_bfe_u32 v9, v2, 16, 1
	v_add3_u32 v11, v11, v14, s91
	v_add3_u32 v10, v10, v13, s91
	v_pk_mul_f32 v[30:31], v[30:31], s[86:87] op_sel_hi:[1,0]
	v_pk_mul_f32 v[38:39], v[38:39], s[86:87] op_sel_hi:[1,0]
	v_add3_u32 v8, v8, v12, s91
	v_bfe_u32 v12, v3, 16, 1
	v_add3_u32 v2, v2, v9, s91
	v_lshrrev_b32_e32 v10, 16, v10
	v_lshrrev_b32_e32 v9, 16, v11
	v_bfe_u32 v11, v28, 16, 1
	v_add3_u32 v3, v3, v12, s91
	v_and_or_b32 v8, v8, s33, v10
	v_bfe_u32 v10, v30, 16, 1
	v_bfe_u32 v12, v29, 16, 1
	v_bfe_u32 v13, v38, 16, 1
	v_bfe_u32 v14, v39, 16, 1
	v_add3_u32 v11, v28, v11, s91
	v_add3_u32 v10, v30, v10, s91
	v_add3_u32 v14, v39, v14, s91
	v_add3_u32 v13, v38, v13, s91
	v_add3_u32 v12, v29, v12, s91
	v_lshrrev_b32_e32 v15, 16, v11
	v_pk_fma_f32 v[40:41], v[16:17], v[34:35], v[40:41]
	v_lshrrev_b32_e32 v11, 16, v12
	v_lshrrev_b32_e32 v12, 16, v13
	v_lshrrev_b32_e32 v13, 16, v14
	v_and_or_b32 v10, v10, s33, v15
	ds_read_b128 v[14:17], v100
	ds_read_b128 v[18:21], v100 offset:64
	v_lshrrev_b32_e32 v2, 16, v2
	v_lshrrev_b32_e32 v3, 16, v3
	v_and_or_b32 v9, v0, s33, v9
	v_and_or_b32 v7, v7, s33, v3
	v_and_or_b32 v6, v6, s33, v2
	v_pk_mul_f32 v[40:41], v[40:41], s[86:87] op_sel_hi:[1,0]
	v_bfe_u32 v3, v31, 16, 1
	s_waitcnt lgkmcnt(1)
	v_mfma_f32_16x16x32_bf16 v[14:17], v[14:17], v[6:9], 0
	v_bfe_u32 v0, v41, 16, 1
	v_bfe_u32 v2, v40, 16, 1
	v_add3_u32 v3, v31, v3, s91
	v_add3_u32 v2, v40, v2, s91
	v_add3_u32 v0, v41, v0, s91
	v_and_or_b32 v13, v0, s33, v13
	v_and_or_b32 v12, v2, s33, v12
	v_and_or_b32 v11, v3, s33, v11
	ds_read_b128 v[22:25], v98 offset:64
	s_addc_u32 s1, s1, s3
	s_nop 1
	v_mov_b64_e32 v[144:145], s[0:1]
	global_load_dword v146, v[144:145], off offset:8
	s_waitcnt lgkmcnt(1)
	v_mfma_f32_16x16x32_bf16 v[14:17], v[18:21], v[10:13], v[14:17]
	ds_read_b128 v[18:21], v98
	v_mov_b64_e32 v[2:3], s[0:1]
	s_waitcnt vmcnt(0)
	s_nop 0
	v_mov_b32_e32 v0, v146
	s_nop 1
	s_waitcnt lgkmcnt(0)
	v_mfma_f32_16x16x32_bf16 v[18:21], v[18:21], v[6:9], 0
	ds_read_b128 v[26:29], v96 offset:64
	ds_read_b128 v[30:33], v94 offset:64
	v_mfma_f32_16x16x32_bf16 v[18:21], v[22:25], v[10:13], v[18:21]
	ds_read_b128 v[22:25], v96
	v_readlane_b32 s0, v255, 22
	v_mov_b32_e32 v2, s89
	s_waitcnt lgkmcnt(0)
	v_mfma_f32_16x16x32_bf16 v[22:25], v[22:25], v[6:9], 0
	v_readlane_b32 s1, v255, 23
	v_cndmask_b32_e64 v3, v14, v2, s[8:9]
	v_mfma_f32_16x16x32_bf16 v[22:25], v[26:29], v[10:13], v[22:25]
	ds_read_b128 v[26:29], v94
	ds_read_b128 v[34:37], v92 offset:64
	s_waitcnt lgkmcnt(0)
	v_mfma_f32_16x16x32_bf16 v[26:29], v[26:29], v[6:9], 0
	ds_read_b128 v[38:41], v90 offset:64
	v_mfma_f32_16x16x32_bf16 v[26:29], v[30:33], v[10:13], v[26:29]
	ds_read_b128 v[30:33], v92
	s_waitcnt lgkmcnt(0)
	v_mfma_f32_16x16x32_bf16 v[30:33], v[30:33], v[6:9], 0
	v_mfma_f32_16x16x32_bf16 v[30:33], v[34:37], v[10:13], v[30:33]
	ds_read_b128 v[34:37], v90
	ds_read_b128 v[42:45], v88 offset:64
	s_waitcnt lgkmcnt(0)
	v_mfma_f32_16x16x32_bf16 v[34:37], v[34:37], v[6:9], 0
	ds_read_b128 v[46:49], v86 offset:64
	v_mfma_f32_16x16x32_bf16 v[34:37], v[38:41], v[10:13], v[34:37]
	ds_read_b128 v[38:41], v88
	s_waitcnt lgkmcnt(0)
	v_mfma_f32_16x16x32_bf16 v[38:41], v[38:41], v[6:9], 0
	s_nop 4
	v_cndmask_b32_e64 v37, v37, v227, s[36:37]
	v_mfma_f32_16x16x32_bf16 v[38:41], v[42:45], v[10:13], v[38:41]
	ds_read_b128 v[42:45], v86
	ds_read_b128 v[50:53], v84 offset:64
	s_waitcnt lgkmcnt(0)
	v_mfma_f32_16x16x32_bf16 v[42:45], v[42:45], v[6:9], 0
	s_nop 3
	v_cndmask_b32_e64 v39, v39, v227, s[46:47]
	v_cndmask_b32_e64 v40, v40, v227, s[50:51]
	v_cndmask_b32_e64 v41, v41, v227, s[52:53]
	v_mfma_f32_16x16x32_bf16 v[42:45], v[46:49], v[10:13], v[42:45]
	ds_read_b128 v[46:49], v84
	s_waitcnt lgkmcnt(0)
	v_mfma_f32_16x16x32_bf16 v[46:49], v[46:49], v[6:9], 0
	s_nop 4
	v_cndmask_b32_e64 v43, v43, v227, s[56:57]
	v_cndmask_b32_e64 v44, v44, v227, s[58:59]
	v_cndmask_b32_e64 v45, v45, v227, s[60:61]
	v_mfma_f32_16x16x32_bf16 v[46:49], v[50:53], v[10:13], v[46:49]
	ds_read_b128 v[50:53], v82
	s_waitcnt lgkmcnt(0)
	v_mfma_f32_16x16x32_bf16 v[6:9], v[50:53], v[6:9], 0
	ds_read_b128 v[50:53], v82 offset:64
	s_nop 3
	v_cndmask_b32_e64 v47, v47, v227, s[64:65]
	v_cndmask_b32_e64 v48, v48, v227, s[66:67]
	s_waitcnt lgkmcnt(0)
	v_mfma_f32_16x16x32_bf16 v[6:9], v[50:53], v[10:13], v[6:9]
	v_cndmask_b32_e64 v10, v15, v227, s[0:1]
	v_max3_f32 v2, v3, s89, v10
	v_cndmask_b32_e64 v11, v16, v227, s[40:41]
	v_cndmask_b32_e64 v12, v17, v227, s[92:93]
	v_max3_f32 v13, v2, v11, v12
	v_mov_b32_e32 v2, s89
	v_cndmask_b32_e64 v14, v18, v2, s[18:19]
	v_cndmask_b32_e64 v15, v19, v227, s[10:11]
	v_max3_f32 v2, v13, v14, v15
	v_cndmask_b32_e64 v13, v20, v227, s[12:13]
	v_cndmask_b32_e64 v16, v21, v227, s[44:45]
	v_max3_f32 v17, v2, v13, v16
	v_mov_b32_e32 v2, s89
	v_cndmask_b32_e64 v18, v22, v2, s[16:17]
	v_cndmask_b32_e64 v19, v23, v227, s[80:81]
	v_max3_f32 v2, v17, v18, v19
	v_cndmask_b32_e64 v17, v24, v227, s[82:83]
	v_cndmask_b32_e64 v20, v25, v227, s[84:85]
	v_max3_f32 v21, v2, v17, v20
	v_mov_b32_e32 v2, s89
	v_cndmask_b32_e64 v22, v26, v2, s[20:21]
	v_cndmask_b32_e64 v23, v27, v227, s[76:77]
	v_max3_f32 v2, v21, v22, v23
	v_cndmask_b32_e64 v21, v28, v227, s[78:79]
	v_cndmask_b32_e64 v24, v29, v227, s[14:15]
	v_max3_f32 v25, v2, v21, v24
	v_mov_b32_e32 v2, s89
	v_cndmask_b32_e64 v26, v30, v2, s[28:29]
	v_cndmask_b32_e64 v27, v31, v227, s[42:43]
	v_max3_f32 v2, v25, v26, v27
	v_cndmask_b32_e64 v25, v32, v227, s[22:23]
	v_cndmask_b32_e64 v50, v33, v227, s[26:27]
	v_max3_f32 v28, v2, v25, v50
	v_mov_b32_e32 v2, s89
	v_cndmask_b32_e64 v51, v34, v2, s[38:39]
	v_cndmask_b32_e64 v52, v35, v227, s[30:31]
	v_max3_f32 v2, v28, v51, v52
	v_cndmask_b32_e64 v53, v36, v227, s[34:35]
	v_max3_f32 v28, v2, v53, v37
	v_mov_b32_e32 v2, s89
	v_cndmask_b32_e64 v38, v38, v2, s[54:55]
	v_max3_f32 v2, v28, v38, v39
	v_max3_f32 v28, v2, v40, v41
	v_mov_b32_e32 v2, s89
	v_cndmask_b32_e64 v42, v42, v2, s[62:63]
	v_max3_f32 v2, v28, v42, v43
	v_max3_f32 v28, v2, v44, v45
	v_mov_b32_e32 v2, s89
	v_cndmask_b32_e64 v46, v46, v2, s[4:5]
	v_max3_f32 v2, v28, v46, v47
	v_cndmask_b32_e64 v49, v49, v227, s[68:69]
	v_max3_f32 v28, v2, v48, v49
	v_mov_b32_e32 v2, s89
	v_cndmask_b32_e64 v74, v6, v2, s[24:25]
	v_cndmask_b32_e64 v75, v7, v227, s[70:71]
	v_max3_f32 v2, v28, v74, v75
	v_cndmask_b32_e64 v76, v8, v227, s[72:73]
	v_cndmask_b32_e64 v77, v9, v227, s[74:75]
	v_max3_f32 v2, v2, v76, v77
	ds_bpermute_b32 v6, v109, v2
	v_readlane_b32 s40, v254, 60
	s_mov_b32 s85, 0xf800000
	s_waitcnt lgkmcnt(0)
	v_max_f32_e32 v6, v6, v6
	v_max_f32_e32 v2, v2, v6
	ds_bpermute_b32 v6, v110, v2
	s_waitcnt vmcnt(0) lgkmcnt(0)
	v_max3_f32 v79, v2, v6, v0
	v_sub_f32_e32 v2, v3, v79
	v_sub_f32_e32 v3, v10, v79
	v_mul_f32_e32 v3, 0x3fb8aa3b, v3
	v_exp_f32_e32 v82, v3
	v_sub_f32_e32 v3, v11, v79
	v_mul_f32_e32 v3, 0x3fb8aa3b, v3
	v_exp_f32_e32 v83, v3
	v_sub_f32_e32 v3, v12, v79
	v_mul_f32_e32 v3, 0x3fb8aa3b, v3
	v_exp_f32_e32 v84, v3
	v_sub_f32_e32 v3, v14, v79
	v_mul_f32_e32 v3, 0x3fb8aa3b, v3
	v_exp_f32_e32 v85, v3
	v_sub_f32_e32 v3, v15, v79
	v_mul_f32_e32 v3, 0x3fb8aa3b, v3
	v_exp_f32_e32 v86, v3
	v_sub_f32_e32 v3, v13, v79
	v_mul_f32_e32 v3, 0x3fb8aa3b, v3
	v_exp_f32_e32 v87, v3
	v_sub_f32_e32 v3, v16, v79
	v_mul_f32_e32 v3, 0x3fb8aa3b, v3
	v_exp_f32_e32 v88, v3
	v_sub_f32_e32 v3, v18, v79
	v_mul_f32_e32 v3, 0x3fb8aa3b, v3
	v_exp_f32_e32 v28, v3
	v_sub_f32_e32 v3, v19, v79
	v_mul_f32_e32 v3, 0x3fb8aa3b, v3
	v_exp_f32_e32 v30, v3
	v_sub_f32_e32 v3, v17, v79
	v_mul_f32_e32 v3, 0x3fb8aa3b, v3
	v_exp_f32_e32 v29, v3
	v_sub_f32_e32 v3, v20, v79
	v_mul_f32_e32 v3, 0x3fb8aa3b, v3
	v_exp_f32_e32 v31, v3
	v_sub_f32_e32 v3, v22, v79
	v_mul_f32_e32 v3, 0x3fb8aa3b, v3
	v_exp_f32_e32 v32, v3
	v_sub_f32_e32 v3, v23, v79
	v_mul_f32_e32 v3, 0x3fb8aa3b, v3
	v_exp_f32_e32 v33, v3
	v_sub_f32_e32 v3, v21, v79
	v_mul_f32_e32 v3, 0x3fb8aa3b, v3
	v_exp_f32_e32 v34, v3
	v_sub_f32_e32 v3, v24, v79
	v_mul_f32_e32 v3, 0x3fb8aa3b, v3
	v_mul_f32_e32 v2, 0x3fb8aa3b, v2
	v_exp_f32_e32 v35, v3
	v_sub_f32_e32 v3, v26, v79
	v_exp_f32_e32 v36, v2
	v_mul_f32_e32 v3, 0x3fb8aa3b, v3
	v_exp_f32_e32 v20, v3
	v_sub_f32_e32 v3, v27, v79
	v_mul_f32_e32 v3, 0x3fb8aa3b, v3
	v_exp_f32_e32 v22, v3
	v_sub_f32_e32 v3, v25, v79
	v_add_f32_e32 v2, 0, v36
	v_mul_f32_e32 v3, 0x3fb8aa3b, v3
	v_add_f32_e32 v2, v82, v2
	v_exp_f32_e32 v21, v3
	v_sub_f32_e32 v3, v50, v79
	v_add_f32_e32 v2, v83, v2
	v_mul_f32_e32 v3, 0x3fb8aa3b, v3
	v_add_f32_e32 v2, v84, v2
	v_exp_f32_e32 v23, v3
	v_sub_f32_e32 v3, v51, v79
	v_add_f32_e32 v2, v85, v2
	v_mul_f32_e32 v3, 0x3fb8aa3b, v3
	v_add_f32_e32 v2, v86, v2
	v_exp_f32_e32 v24, v3
	v_sub_f32_e32 v3, v52, v79
	v_add_f32_e32 v2, v87, v2
	v_mul_f32_e32 v3, 0x3fb8aa3b, v3
	v_add_f32_e32 v2, v88, v2
	v_exp_f32_e32 v25, v3
	v_sub_f32_e32 v3, v53, v79
	v_add_f32_e32 v2, v28, v2
	v_mul_f32_e32 v3, 0x3fb8aa3b, v3
	v_add_f32_e32 v2, v30, v2
	v_exp_f32_e32 v26, v3
	v_sub_f32_e32 v3, v37, v79
	v_add_f32_e32 v2, v29, v2
	v_mul_f32_e32 v3, 0x3fb8aa3b, v3
	v_add_f32_e32 v2, v31, v2
	v_exp_f32_e32 v27, v3
	v_sub_f32_e32 v3, v38, v79
	v_add_f32_e32 v2, v32, v2
	v_mul_f32_e32 v3, 0x3fb8aa3b, v3
	v_add_f32_e32 v2, v33, v2
	v_exp_f32_e32 v12, v3
	v_sub_f32_e32 v3, v39, v79
	v_add_f32_e32 v2, v34, v2
	v_mul_f32_e32 v3, 0x3fb8aa3b, v3
	v_add_f32_e32 v2, v35, v2
	v_exp_f32_e32 v14, v3
	v_sub_f32_e32 v3, v40, v79
	v_add_f32_e32 v2, v20, v2
	v_mul_f32_e32 v3, 0x3fb8aa3b, v3
	v_add_f32_e32 v2, v22, v2
	v_exp_f32_e32 v13, v3
	v_sub_f32_e32 v3, v41, v79
	v_add_f32_e32 v2, v21, v2
	v_mul_f32_e32 v3, 0x3fb8aa3b, v3
	v_add_f32_e32 v2, v23, v2
	v_exp_f32_e32 v15, v3
	v_sub_f32_e32 v3, v42, v79
	v_add_f32_e32 v2, v24, v2
	v_mul_f32_e32 v3, 0x3fb8aa3b, v3
	v_add_f32_e32 v2, v25, v2
	v_exp_f32_e32 v16, v3
	v_sub_f32_e32 v3, v43, v79
	v_add_f32_e32 v2, v26, v2
	v_mul_f32_e32 v3, 0x3fb8aa3b, v3
	v_add_f32_e32 v2, v27, v2
	v_exp_f32_e32 v17, v3
	v_sub_f32_e32 v3, v44, v79
	v_add_f32_e32 v2, v12, v2
	v_mul_f32_e32 v3, 0x3fb8aa3b, v3
	v_add_f32_e32 v2, v14, v2
	v_exp_f32_e32 v18, v3
	v_sub_f32_e32 v3, v45, v79
	v_add_f32_e32 v2, v13, v2
	v_mul_f32_e32 v3, 0x3fb8aa3b, v3
	v_add_f32_e32 v2, v15, v2
	v_exp_f32_e32 v19, v3
	v_add_f32_e32 v2, v16, v2
	v_add_f32_e32 v2, v17, v2
	v_add_f32_e32 v2, v18, v2
	v_add_f32_e32 v3, v19, v2
	v_sub_f32_e32 v2, v46, v79
	v_mul_f32_e32 v2, 0x3fb8aa3b, v2
	v_sub_f32_e32 v6, v47, v79
	v_exp_f32_e32 v2, v2
	v_mul_f32_e32 v6, 0x3fb8aa3b, v6
	v_exp_f32_e32 v6, v6
	v_sub_f32_e32 v8, v49, v79
	v_add_f32_e32 v3, v2, v3
	v_mul_f32_e32 v8, 0x3fb8aa3b, v8
	v_add_f32_e32 v7, v6, v3
	v_sub_f32_e32 v3, v48, v79
	v_mul_f32_e32 v3, 0x3fb8aa3b, v3
	v_exp_f32_e32 v3, v3
	v_exp_f32_e32 v8, v8
	v_sub_f32_e32 v10, v75, v79
	v_mul_f32_e32 v10, 0x3fb8aa3b, v10
	v_add_f32_e32 v7, v3, v7
	v_add_f32_e32 v9, v8, v7
	v_sub_f32_e32 v7, v74, v79
	v_mul_f32_e32 v7, 0x3fb8aa3b, v7
	v_exp_f32_e32 v7, v7
	v_exp_f32_e32 v10, v10
	v_sub_f32_e32 v0, v0, v79
	v_mul_f32_e32 v0, 0x3fb8aa3b, v0
	v_add_f32_e32 v9, v7, v9
	v_add_f32_e32 v11, v10, v9
	v_sub_f32_e32 v9, v76, v79
	v_mul_f32_e32 v9, 0x3fb8aa3b, v9
	v_exp_f32_e32 v9, v9
	v_exp_f32_e32 v0, v0
	v_bfe_u32 v39, v84, 16, 1
	v_add3_u32 v41, v84, v39, s91
	v_add_f32_e32 v37, v9, v11
	v_sub_f32_e32 v11, v77, v79
	v_mul_f32_e32 v11, 0x3fb8aa3b, v11
	v_exp_f32_e32 v11, v11
	v_bfe_u32 v39, v36, 16, 1
	v_bfe_u32 v42, v83, 16, 1
	v_bfe_u32 v43, v85, 16, 1
	v_add_f32_e32 v37, v11, v37
	ds_bpermute_b32 v38, v109, v37
	v_bfe_u32 v44, v87, 16, 1
	v_bfe_u32 v40, v82, 16, 1
	v_add3_u32 v44, v87, v44, s91
	v_add3_u32 v43, v85, v43, s91
	s_waitcnt lgkmcnt(0)
	v_add_f32_e32 v37, v37, v38
	ds_bpermute_b32 v38, v110, v37
	v_add3_u32 v42, v83, v42, s91
	v_add3_u32 v36, v36, v39, s91
	v_add3_u32 v40, v82, v40, s91
	v_lshrrev_b32_e32 v36, 16, v36
	s_waitcnt lgkmcnt(0)
	v_add_f32_e32 v37, v37, v38
	v_add_f32_e32 v0, v0, v37
	v_bfe_u32 v37, v88, 16, 1
	v_bfe_u32 v38, v86, 16, 1
	v_add3_u32 v38, v86, v38, s91
	v_add3_u32 v37, v88, v37, s91
	v_lshrrev_b32_e32 v42, 16, v42
	v_lshrrev_b32_e32 v43, 16, v43
	v_lshrrev_b32_e32 v39, 16, v44
	v_and_or_b32 v39, v37, s33, v39
	v_and_or_b32 v38, v38, s33, v43
	v_and_or_b32 v37, v41, s33, v42
	v_and_or_b32 v36, v40, s33, v36
	ds_read2_b64 v[40:43], v73 offset1:4
	ds_read2_b64 v[44:47], v72 offset0:32 offset1:36
	ds_read2_b64 v[48:51], v71 offset0:64 offset1:68
	ds_read2_b64 v[70:73], v70 offset0:96 offset1:100
	s_waitcnt lgkmcnt(3)
	v_mfma_f32_16x16x32_bf16 v[40:43], v[40:43], v[36:39], 0
	v_bfe_u32 v52, v35, 16, 1
	v_bfe_u32 v53, v33, 16, 1
	s_waitcnt lgkmcnt(2)
	v_mfma_f32_16x16x32_bf16 v[44:47], v[44:47], v[36:39], 0
	s_waitcnt lgkmcnt(1)
	v_mfma_f32_16x16x32_bf16 v[48:51], v[48:51], v[36:39], 0
	s_waitcnt lgkmcnt(0)
	v_mfma_f32_16x16x32_bf16 v[36:39], v[70:73], v[36:39], 0
	v_bfe_u32 v70, v31, 16, 1
	v_bfe_u32 v71, v30, 16, 1
	v_add3_u32 v71, v30, v71, s91
	v_add3_u32 v70, v31, v70, s91
	v_add3_u32 v30, v33, v53, s91
	v_add3_u32 v31, v35, v52, s91
	v_bfe_u32 v52, v32, 16, 1
	v_bfe_u32 v53, v34, 16, 1
	v_bfe_u32 v33, v28, 16, 1
	v_add3_u32 v34, v34, v53, s91
	v_add3_u32 v32, v32, v52, s91
	v_bfe_u32 v35, v29, 16, 1
	v_add3_u32 v28, v28, v33, s91
	v_lshrrev_b32_e32 v32, 16, v32
	v_lshrrev_b32_e32 v33, 16, v34
	v_add3_u32 v29, v29, v35, s91
	v_and_or_b32 v31, v31, s33, v33
	v_and_or_b32 v30, v30, s33, v32
	ds_read2_b64 v[32:35], v69 offset1:4
	v_lshrrev_b32_e32 v28, 16, v28
	v_lshrrev_b32_e32 v29, 16, v29
	v_and_or_b32 v29, v70, s33, v29
	v_and_or_b32 v28, v71, s33, v28
	s_waitcnt lgkmcnt(0)
	s_nop 0
	v_mfma_f32_16x16x32_bf16 v[32:35], v[32:35], v[28:31], v[40:43]
	s_nop 2
	ds_read2_b64 v[40:43], v68 offset0:32 offset1:36
	s_waitcnt lgkmcnt(0)
	v_mfma_f32_16x16x32_bf16 v[40:43], v[40:43], v[28:31], v[44:47]
	s_nop 2
	ds_read2_b64 v[44:47], v67 offset0:64 offset1:68
	s_waitcnt lgkmcnt(0)
	v_mfma_f32_16x16x32_bf16 v[44:47], v[44:47], v[28:31], v[48:51]
	s_nop 2
	ds_read2_b64 v[48:51], v66 offset0:96 offset1:100
	s_waitcnt lgkmcnt(0)
	v_mfma_f32_16x16x32_bf16 v[28:31], v[48:51], v[28:31], v[36:39]
	s_nop 2
	v_bfe_u32 v36, v27, 16, 1
	v_bfe_u32 v37, v25, 16, 1
	v_bfe_u32 v38, v23, 16, 1
	v_bfe_u32 v39, v22, 16, 1
	v_add3_u32 v39, v22, v39, s91
	v_add3_u32 v38, v23, v38, s91
	v_add3_u32 v22, v25, v37, s91
	v_add3_u32 v23, v27, v36, s91
	v_bfe_u32 v36, v24, 16, 1
	v_bfe_u32 v37, v26, 16, 1
	v_bfe_u32 v25, v20, 16, 1
	v_add3_u32 v26, v26, v37, s91
	v_add3_u32 v24, v24, v36, s91
	v_bfe_u32 v27, v21, 16, 1
	v_add3_u32 v20, v20, v25, s91
	v_lshrrev_b32_e32 v24, 16, v24
	v_lshrrev_b32_e32 v25, 16, v26
	v_add3_u32 v21, v21, v27, s91
	v_and_or_b32 v23, v23, s33, v25
	v_and_or_b32 v22, v22, s33, v24
	ds_read2_b64 v[24:27], v65 offset1:4
	v_lshrrev_b32_e32 v20, 16, v20
	v_lshrrev_b32_e32 v21, 16, v21
	v_and_or_b32 v21, v38, s33, v21
	v_and_or_b32 v20, v39, s33, v20
	ds_read2_b64 v[36:39], v63 offset0:64 offset1:68
	s_waitcnt lgkmcnt(1)
	v_mfma_f32_16x16x32_bf16 v[24:27], v[24:27], v[20:23], v[32:35]
	s_nop 2
	ds_read2_b64 v[32:35], v64 offset0:32 offset1:36
	s_waitcnt lgkmcnt(0)
	v_mfma_f32_16x16x32_bf16 v[32:35], v[32:35], v[20:23], v[40:43]
	s_nop 2
	ds_read2_b64 v[40:43], v62 offset0:96 offset1:100
	v_mfma_f32_16x16x32_bf16 v[36:39], v[36:39], v[20:23], v[44:47]
	s_waitcnt lgkmcnt(0)
	v_mfma_f32_16x16x32_bf16 v[20:23], v[40:43], v[20:23], v[28:31]
	s_nop 2
	v_bfe_u32 v28, v19, 16, 1
	v_bfe_u32 v29, v17, 16, 1
	v_bfe_u32 v30, v15, 16, 1
	v_bfe_u32 v31, v14, 16, 1
	v_add3_u32 v31, v14, v31, s91
	v_add3_u32 v30, v15, v30, s91
	v_add3_u32 v14, v17, v29, s91
	v_add3_u32 v15, v19, v28, s91
	v_bfe_u32 v28, v16, 16, 1
	v_bfe_u32 v29, v18, 16, 1
	v_bfe_u32 v17, v12, 16, 1
	v_add3_u32 v18, v18, v29, s91
	v_add3_u32 v16, v16, v28, s91
	v_bfe_u32 v19, v13, 16, 1
	v_add3_u32 v12, v12, v17, s91
	v_lshrrev_b32_e32 v16, 16, v16
	v_lshrrev_b32_e32 v17, 16, v18
	v_add3_u32 v13, v13, v19, s91
	v_and_or_b32 v15, v15, s33, v17
	v_and_or_b32 v14, v14, s33, v16
	ds_read2_b64 v[16:19], v61 offset1:4
	v_lshrrev_b32_e32 v12, 16, v12
	v_lshrrev_b32_e32 v13, 16, v13
	v_and_or_b32 v13, v30, s33, v13
	v_and_or_b32 v12, v31, s33, v12
	ds_read2_b64 v[28:31], v59 offset0:64 offset1:68
	s_waitcnt lgkmcnt(1)
	v_mfma_f32_16x16x32_bf16 v[16:19], v[16:19], v[12:15], v[24:27]
	s_nop 2
	ds_read2_b64 v[24:27], v60 offset0:32 offset1:36
	s_waitcnt lgkmcnt(0)
	v_mfma_f32_16x16x32_bf16 v[24:27], v[24:27], v[12:15], v[32:35]
	s_nop 2
	ds_read2_b64 v[32:35], v58 offset0:96 offset1:100
	v_mfma_f32_16x16x32_bf16 v[28:31], v[28:31], v[12:15], v[36:39]
	s_waitcnt lgkmcnt(0)
	v_mfma_f32_16x16x32_bf16 v[12:15], v[32:35], v[12:15], v[20:23]
	s_nop 2
	v_bfe_u32 v20, v11, 16, 1
	v_bfe_u32 v21, v10, 16, 1
	v_bfe_u32 v22, v8, 16, 1
	v_add3_u32 v22, v8, v22, s91
	v_add3_u32 v8, v10, v21, s91
	v_add3_u32 v10, v11, v20, s91
	v_bfe_u32 v20, v3, 16, 1
	v_bfe_u32 v21, v7, 16, 1
	v_bfe_u32 v23, v6, 16, 1
	v_add3_u32 v7, v7, v21, s91
	v_add3_u32 v3, v3, v20, s91
	v_add3_u32 v6, v6, v23, s91
	v_bfe_u32 v23, v9, 16, 1
	v_lshrrev_b32_e32 v3, 16, v3
	v_lshrrev_b32_e32 v7, 16, v7
	v_add3_u32 v9, v9, v23, s91
	v_and_or_b32 v8, v8, s33, v7
	v_and_or_b32 v7, v22, s33, v3
	ds_read2_b64 v[20:23], v57 offset1:4
	v_bfe_u32 v11, v2, 16, 1
	v_add3_u32 v2, v2, v11, s91
	v_lshrrev_b32_e32 v2, 16, v2
	v_lshrrev_b32_e32 v9, 16, v9
	v_and_or_b32 v9, v10, s33, v9
	v_and_or_b32 v6, v6, s33, v2
	v_div_scale_f32 v2, s[0:1], v0, v0, 1.0
	s_waitcnt lgkmcnt(0)
	v_mfma_f32_16x16x32_bf16 v[16:19], v[20:23], v[6:9], v[16:19]
	ds_read2_b64 v[20:23], v56 offset0:32 offset1:36
	v_rcp_f32_e32 v3, v2
	v_readlane_b32 s0, v254, 63
	s_waitcnt lgkmcnt(0)
	v_mfma_f32_16x16x32_bf16 v[20:23], v[20:23], v[6:9], v[24:27]
	s_nop 2
	ds_read2_b64 v[24:27], v55 offset0:64 offset1:68
	v_fma_f32 v10, -v2, v3, 1.0
	v_fmac_f32_e32 v3, v10, v3
	s_waitcnt lgkmcnt(0)
	v_mfma_f32_16x16x32_bf16 v[24:27], v[24:27], v[6:9], v[28:31]
	s_nop 2
	ds_read2_b64 v[28:31], v54 offset0:96 offset1:100
	v_div_scale_f32 v10, vcc, 1.0, v0, 1.0
	v_mul_f32_e32 v11, v10, v3
	s_waitcnt lgkmcnt(0)
	v_mfma_f32_16x16x32_bf16 v[6:9], v[28:31], v[6:9], v[12:15]
	s_nop 2
	v_fma_f32 v12, -v2, v11, v10
	v_fmac_f32_e32 v11, v12, v3
	v_fma_f32 v2, -v2, v11, v10
	v_div_fmas_f32 v2, v2, v3, v11
	v_div_fixup_f32 v0, v2, v0, 1.0
	v_mov_b32_e32 v10, v16
	v_mov_b32_e32 v11, v18
	v_pk_mul_f32 v[10:11], v[0:1], v[10:11] op_sel_hi:[0,1]
	v_mov_b32_e32 v18, v17
	v_pk_mul_f32 v[12:13], v[0:1], v[18:19] op_sel_hi:[0,1]
	v_and_b32_sdwa v14, v11, v218 dst_sel:DWORD dst_unused:UNUSED_PAD src0_sel:WORD_1 src1_sel:DWORD
	v_and_b32_sdwa v15, v10, v218 dst_sel:DWORD dst_unused:UNUSED_PAD src0_sel:WORD_1 src1_sel:DWORD
	v_add3_u32 v10, v10, v15, s91
	v_add3_u32 v11, v11, v14, s91
	v_and_b32_sdwa v14, v13, v218 dst_sel:DWORD dst_unused:UNUSED_PAD src0_sel:WORD_1 src1_sel:DWORD
	v_and_b32_sdwa v15, v12, v218 dst_sel:DWORD dst_unused:UNUSED_PAD src0_sel:WORD_1 src1_sel:DWORD
	v_add3_u32 v13, v13, v14, s91
	v_add3_u32 v12, v12, v15, s91
	s_lshl_b32 s94, s0, 1
	v_and_b32_e32 v13, 0xffff0000, v13
	v_and_b32_e32 v12, 0xffff0000, v12
	v_lshl_add_u64 v[2:3], v[80:81], 0, s[94:95]
	v_or_b32_sdwa v11, v13, v11 dst_sel:DWORD dst_unused:UNUSED_PAD src0_sel:DWORD src1_sel:WORD_1
	v_or_b32_sdwa v10, v12, v10 dst_sel:DWORD dst_unused:UNUSED_PAD src0_sel:DWORD src1_sel:WORD_1
	flat_store_dwordx2 v[2:3], v[10:11]
	v_mov_b32_e32 v10, v20
	v_mov_b32_e32 v11, v22
	v_pk_mul_f32 v[10:11], v[0:1], v[10:11] op_sel_hi:[0,1]
	v_mov_b32_e32 v22, v21
	v_pk_mul_f32 v[12:13], v[0:1], v[22:23] op_sel_hi:[0,1]
	v_and_b32_sdwa v14, v11, v218 dst_sel:DWORD dst_unused:UNUSED_PAD src0_sel:WORD_1 src1_sel:DWORD
	v_and_b32_sdwa v15, v10, v218 dst_sel:DWORD dst_unused:UNUSED_PAD src0_sel:WORD_1 src1_sel:DWORD
	v_add3_u32 v10, v10, v15, s91
	v_add3_u32 v11, v11, v14, s91
	v_and_b32_sdwa v14, v13, v218 dst_sel:DWORD dst_unused:UNUSED_PAD src0_sel:WORD_1 src1_sel:DWORD
	v_and_b32_sdwa v15, v12, v218 dst_sel:DWORD dst_unused:UNUSED_PAD src0_sel:WORD_1 src1_sel:DWORD
	v_add3_u32 v13, v13, v14, s91
	v_add3_u32 v12, v12, v15, s91
	v_and_b32_e32 v13, 0xffff0000, v13
	v_and_b32_e32 v12, 0xffff0000, v12
	v_or_b32_sdwa v11, v13, v11 dst_sel:DWORD dst_unused:UNUSED_PAD src0_sel:DWORD src1_sel:WORD_1
	v_or_b32_sdwa v10, v12, v10 dst_sel:DWORD dst_unused:UNUSED_PAD src0_sel:DWORD src1_sel:WORD_1
	flat_store_dwordx2 v[2:3], v[10:11] offset:32
	v_mov_b32_e32 v10, v24
	v_mov_b32_e32 v11, v26
	v_pk_mul_f32 v[10:11], v[0:1], v[10:11] op_sel_hi:[0,1]
	v_mov_b32_e32 v26, v25
	v_pk_mul_f32 v[12:13], v[0:1], v[26:27] op_sel_hi:[0,1]
	v_and_b32_sdwa v14, v11, v218 dst_sel:DWORD dst_unused:UNUSED_PAD src0_sel:WORD_1 src1_sel:DWORD
	v_and_b32_sdwa v15, v10, v218 dst_sel:DWORD dst_unused:UNUSED_PAD src0_sel:WORD_1 src1_sel:DWORD
	v_add3_u32 v10, v10, v15, s91
	v_add3_u32 v11, v11, v14, s91
	v_and_b32_sdwa v14, v13, v218 dst_sel:DWORD dst_unused:UNUSED_PAD src0_sel:WORD_1 src1_sel:DWORD
	v_and_b32_sdwa v15, v12, v218 dst_sel:DWORD dst_unused:UNUSED_PAD src0_sel:WORD_1 src1_sel:DWORD
	v_add3_u32 v13, v13, v14, s91
	v_add3_u32 v12, v12, v15, s91
	v_and_b32_e32 v13, 0xffff0000, v13
	v_and_b32_e32 v12, 0xffff0000, v12
	v_or_b32_sdwa v11, v13, v11 dst_sel:DWORD dst_unused:UNUSED_PAD src0_sel:DWORD src1_sel:WORD_1
	v_or_b32_sdwa v10, v12, v10 dst_sel:DWORD dst_unused:UNUSED_PAD src0_sel:DWORD src1_sel:WORD_1
	flat_store_dwordx2 v[2:3], v[10:11] offset:64
	v_mov_b32_e32 v10, v6
	v_mov_b32_e32 v11, v8
	v_pk_mul_f32 v[10:11], v[0:1], v[10:11] op_sel_hi:[0,1]
	v_mov_b32_e32 v8, v7
	v_pk_mul_f32 v[6:7], v[0:1], v[8:9] op_sel_hi:[0,1]
	v_and_b32_sdwa v8, v10, v218 dst_sel:DWORD dst_unused:UNUSED_PAD src0_sel:WORD_1 src1_sel:DWORD
	v_add3_u32 v8, v10, v8, s91
	v_and_b32_sdwa v9, v7, v218 dst_sel:DWORD dst_unused:UNUSED_PAD src0_sel:WORD_1 src1_sel:DWORD
	v_and_b32_sdwa v10, v6, v218 dst_sel:DWORD dst_unused:UNUSED_PAD src0_sel:WORD_1 src1_sel:DWORD
	v_and_b32_sdwa v0, v11, v218 dst_sel:DWORD dst_unused:UNUSED_PAD src0_sel:WORD_1 src1_sel:DWORD
	v_add3_u32 v7, v7, v9, s91
	v_add3_u32 v6, v6, v10, s91
	v_add3_u32 v0, v11, v0, s91
	v_and_b32_e32 v7, 0xffff0000, v7
	v_and_b32_e32 v6, 0xffff0000, v6
	v_or_b32_sdwa v7, v7, v0 dst_sel:DWORD dst_unused:UNUSED_PAD src0_sel:DWORD src1_sel:WORD_1
	v_or_b32_sdwa v6, v6, v8 dst_sel:DWORD dst_unused:UNUSED_PAD src0_sel:DWORD src1_sel:WORD_1
	flat_store_dwordx2 v[2:3], v[6:7] offset:96
	s_waitcnt lgkmcnt(0)
	s_barrier

.LBB0_406:
	s_nop 1
	global_load_dword v132, v[8:9], off
	flat_load_dword v13, v[10:11]
	v_add_u32_e32 v7, 8, v7
	s_waitcnt vmcnt(0) lgkmcnt(0)
	v_mul_f32_e32 v14, v13, v13
	ds_bpermute_b32 v14, v5, v14
	s_waitcnt lgkmcnt(0)
	v_fmac_f32_e32 v14, v13, v13
	ds_bpermute_b32 v15, v106, v14
	s_waitcnt lgkmcnt(0)
	v_add_f32_e32 v14, v14, v15
	ds_bpermute_b32 v15, v107, v14
	s_waitcnt lgkmcnt(0)
	v_add_f32_e32 v14, v14, v15
	ds_bpermute_b32 v15, v108, v14
	s_waitcnt lgkmcnt(0)
	v_add_f32_e32 v14, v14, v15
	ds_bpermute_b32 v15, v109, v14
	s_waitcnt lgkmcnt(0)
	v_add_f32_e32 v14, v14, v15
	ds_bpermute_b32 v15, v110, v14
	s_waitcnt lgkmcnt(0)
	v_add_f32_e32 v14, v14, v15
	v_fmamk_f32 v14, v14, 0x3c800000, v219
	v_cmp_gt_f32_e32 vcc, s85, v14
	v_mul_f32_e32 v15, 0x4f800000, v14
	s_nop 0
	v_cndmask_b32_e32 v14, v14, v15, vcc
	v_sqrt_f32_e32 v15, v14
	s_nop 0
	v_add_u32_e32 v16, -1, v15
	v_fma_f32 v17, -v16, v15, v14
	v_cmp_ge_f32_e64 s[6:7], 0, v17
	v_add_u32_e32 v17, 1, v15
	s_nop 0
	v_cndmask_b32_e64 v16, v15, v16, s[6:7]
	v_fma_f32 v15, -v17, v15, v14
	v_cmp_lt_f32_e64 s[6:7], 0, v15
	s_nop 1
	v_cndmask_b32_e64 v15, v16, v17, s[6:7]
	v_mul_f32_e32 v16, 0x37800000, v15
	v_cndmask_b32_e32 v15, v15, v16, vcc
	v_cmp_class_f32_e32 vcc, v14, v221
	s_nop 1
	v_cndmask_b32_e32 v14, v15, v14, vcc
	v_div_scale_f32 v15, s[6:7], v14, v14, 1.0
	v_rcp_f32_e32 v16, v15
	s_mov_b64 s[6:7], 0x800
	v_lshl_add_u64 v[10:11], v[10:11], 0, s[6:7]
	v_fma_f32 v17, -v15, v16, 1.0
	v_fmac_f32_e32 v16, v17, v16
	v_div_scale_f32 v17, vcc, 1.0, v14, 1.0
	v_mul_f32_e32 v18, v17, v16
	v_fma_f32 v19, -v15, v18, v17
	v_fmac_f32_e32 v18, v19, v16
	v_fma_f32 v15, -v15, v18, v17
	v_div_fmas_f32 v15, v15, v16, v18
	v_div_fixup_f32 v14, v15, v14, 1.0
	v_mul_f32_e32 v13, v13, v14
	s_waitcnt vmcnt(0)
	s_nop 0
	v_mov_b32_e32 v14, v132
	s_nop 1
	v_cmp_lt_i32_e32 vcc, -5, v7
	s_or_b64 s[2:3], vcc, s[2:3]
	s_waitcnt vmcnt(0) lgkmcnt(0)
	v_mul_f32_e32 v13, v14, v13
	v_mul_f32_e32 v13, 0x3e000000, v13
	ds_write_b32 v12, v13
	v_add_u32_e32 v12, 0x800, v12
	s_andn2_b64 exec, exec, s[2:3]
	s_cbranch_execnz .LBB0_406

.LBB0_443:
	s_nop 1
	global_load_dword v134, v[12:13], off
	s_nop 1
	global_load_dword v133, v[10:11], off
	s_nop 1
	global_load_dword v132, v[8:9], off
	v_ashrrev_i32_e32 v15, 31, v14
	v_lshl_add_u64 v[18:19], v[14:15], 2, s[10:11]
	flat_load_dword v15, v[18:19]
	v_add_u32_e32 v3, 8, v3
	v_add_u32_e32 v14, 0x200, v14
	s_waitcnt vmcnt(0) lgkmcnt(0)
	v_mul_f32_e32 v17, v15, v15
	ds_bpermute_b32 v17, v5, v17
	s_waitcnt lgkmcnt(0)
	v_fmac_f32_e32 v17, v15, v15
	ds_bpermute_b32 v18, v106, v17
	s_waitcnt lgkmcnt(0)
	v_add_f32_e32 v17, v17, v18
	ds_bpermute_b32 v18, v107, v17
	s_waitcnt lgkmcnt(0)
	v_add_f32_e32 v17, v17, v18
	ds_bpermute_b32 v18, v108, v17
	s_waitcnt lgkmcnt(0)
	v_add_f32_e32 v17, v17, v18
	ds_bpermute_b32 v18, v109, v17
	s_waitcnt lgkmcnt(0)
	v_add_f32_e32 v17, v17, v18
	ds_bpermute_b32 v18, v110, v17
	s_waitcnt lgkmcnt(0)
	v_add_f32_e32 v17, v17, v18
	v_fmamk_f32 v17, v17, 0x3c800000, v219
	v_cmp_gt_f32_e32 vcc, s85, v17
	v_mul_f32_e32 v18, 0x4f800000, v17
	s_nop 0
	v_cndmask_b32_e32 v17, v17, v18, vcc
	v_sqrt_f32_e32 v18, v17
	s_nop 0
	v_add_u32_e32 v19, -1, v18
	v_fma_f32 v20, -v19, v18, v17
	v_cmp_ge_f32_e64 s[8:9], 0, v20
	v_add_u32_e32 v20, 1, v18
	s_nop 0
	v_cndmask_b32_e64 v19, v18, v19, s[8:9]
	v_fma_f32 v18, -v20, v18, v17
	v_cmp_lt_f32_e64 s[8:9], 0, v18
	s_nop 1
	v_cndmask_b32_e64 v18, v19, v20, s[8:9]
	v_mul_f32_e32 v19, 0x37800000, v18
	v_cndmask_b32_e32 v18, v18, v19, vcc
	v_cmp_class_f32_e32 vcc, v17, v221
	s_nop 1
	v_cndmask_b32_e32 v17, v18, v17, vcc
	v_div_scale_f32 v18, s[8:9], v17, v17, 1.0
	v_rcp_f32_e32 v19, v18
	s_nop 0
	v_fma_f32 v20, -v18, v19, 1.0
	v_fmac_f32_e32 v19, v20, v19
	v_div_scale_f32 v20, vcc, 1.0, v17, 1.0
	v_mul_f32_e32 v21, v20, v19
	v_fma_f32 v23, -v18, v21, v20
	v_fmac_f32_e32 v21, v23, v19
	v_fma_f32 v18, -v18, v21, v20
	v_div_fmas_f32 v18, v18, v19, v21
	v_div_fixup_f32 v17, v18, v17, 1.0
	v_mul_f32_e32 v15, v15, v17
	s_waitcnt vmcnt(0)
	s_nop 0
	v_mov_b32_e32 v17, v132
	s_nop 1
	s_waitcnt vmcnt(0)
	s_nop 0
	v_mov_b32_e32 v18, v133
	s_nop 1
	s_waitcnt vmcnt(0)
	s_nop 0
	v_mov_b32_e32 v19, v134
	s_nop 1
	v_cmp_lt_i32_e32 vcc, 3, v3
	s_or_b64 s[18:19], vcc, s[18:19]
	s_waitcnt vmcnt(0) lgkmcnt(0)
	v_mul_f32_e32 v15, v17, v15
	ds_bpermute_b32 v17, v110, v15
	s_waitcnt lgkmcnt(0)
	v_mul_f32_e32 v17, v19, v17
	v_cndmask_b32_e64 v17, v17, -v17, s[6:7]
	v_fmac_f32_e32 v17, v18, v15
	v_mul_f32_e32 v15, 0x3e000000, v17
	ds_write_b32 v7, v15
	v_add_u32_e32 v7, 0x800, v7
	s_andn2_b64 exec, exec, s[18:19]
	s_cbranch_execnz .LBB0_443
.LBB0_444:
	s_or_b64 exec, exec, s[16:17]
	v_cmp_gt_i32_e32 vcc, 4, v2
	s_and_saveexec_b64 s[8:9], vcc
	s_cbranch_execz .LBB0_447
	s_nop 1
	v_and_b32_e32 v136, 0xffffffc0, v78
	v_or_b32_e32 v132, v136, v22
	v_add_u32_e32 v134, 0x500, v132
	v_ashrrev_i32_e32 v135, 31, v134
	v_lshl_add_u64 v[134:135], v[134:135], 2, s[10:11]
	global_load_dword v133, v[134:135], off
	v_and_b32_e32 v8, 0xffffffc0, v78
	v_or_b32_e32 v3, v8, v22
	v_add_u32_e32 v10, 0x400, v3
	v_ashrrev_i32_e32 v11, 31, v10
	v_lshl_add_u64 v[10:11], v[10:11], 2, s[10:11]
	flat_load_dword v9, v[10:11]
	v_readlane_b32 s6, v254, 15
	s_nop 1
	v_mov_b32_e32 v7, s6
	ds_read_b64 v[10:11], v7
	v_mov_b32_e32 v7, v1
	s_waitcnt lgkmcnt(0)
	v_readfirstlane_b32 s6, v10
	v_readfirstlane_b32 s7, v11
	s_nop 1
	v_lshl_add_u64 v[10:11], s[6:7], 0, v[0:1]
	flat_load_dword v12, v[10:11]
	v_lshl_add_u64 v[10:11], s[12:13], 0, v[6:7]
	v_lshl_add_u64 v[6:7], s[14:15], 0, v[6:7]
	flat_load_dword v10, v[10:11]
	s_nop 0
	flat_load_dword v11, v[6:7]
	v_add_u32_e32 v6, 0x500, v3
	v_ashrrev_i32_e32 v7, 31, v6
	v_lshl_add_u64 v[6:7], v[6:7], 2, s[10:11]
	s_waitcnt vmcnt(0)
	v_mul_f32_e32 v3, v9, v9
	ds_bpermute_b32 v13, v5, v3
	s_waitcnt vmcnt(0)
	s_nop 0
	v_mov_b32_e32 v3, v133
	s_nop 1
	s_waitcnt lgkmcnt(0)
	v_fmac_f32_e32 v13, v9, v9
	ds_bpermute_b32 v6, v106, v13
	s_waitcnt lgkmcnt(0)
	v_add_f32_e32 v6, v13, v6
	ds_bpermute_b32 v7, v107, v6
	s_waitcnt lgkmcnt(0)
	v_add_f32_e32 v6, v6, v7
	ds_bpermute_b32 v7, v108, v6
	s_waitcnt lgkmcnt(0)
	v_add_f32_e32 v6, v6, v7
	ds_bpermute_b32 v7, v109, v6
	s_waitcnt lgkmcnt(0)
	v_add_f32_e32 v6, v6, v7
	ds_bpermute_b32 v7, v110, v6
	s_waitcnt lgkmcnt(0)
	v_add_f32_e32 v6, v6, v7
	v_fmamk_f32 v6, v6, 0x3c800000, v219
	v_mul_f32_e32 v7, 0x4f800000, v6
	v_cmp_gt_f32_e32 vcc, s85, v6
	s_nop 1
	v_cndmask_b32_e32 v6, v6, v7, vcc
	v_sqrt_f32_e32 v7, v6
	s_nop 0
	v_add_u32_e32 v13, -1, v7
	v_add_u32_e32 v14, 1, v7
	v_fma_f32 v15, -v13, v7, v6
	v_fma_f32 v17, -v14, v7, v6
	v_cmp_ge_f32_e64 s[6:7], 0, v15
	s_nop 1
	v_cndmask_b32_e64 v7, v7, v13, s[6:7]
	v_cmp_lt_f32_e64 s[6:7], 0, v17
	s_nop 1
	v_cndmask_b32_e64 v7, v7, v14, s[6:7]
	v_mul_f32_e32 v13, 0x37800000, v7
	v_cndmask_b32_e32 v7, v7, v13, vcc
	v_cmp_class_f32_e32 vcc, v6, v221
	s_nop 1
	v_cndmask_b32_e32 v6, v7, v6, vcc
	v_div_scale_f32 v7, s[6:7], v6, v6, 1.0
	v_rcp_f32_e32 v13, v7
	v_div_scale_f32 v14, vcc, 1.0, v6, 1.0
	v_readlane_b32 s6, v254, 49
	v_fma_f32 v15, -v7, v13, 1.0
	v_fmac_f32_e32 v13, v15, v13
	v_mul_f32_e32 v15, v14, v13
	v_fma_f32 v17, -v7, v15, v14
	v_fmac_f32_e32 v15, v17, v13
	v_fma_f32 v7, -v7, v15, v14
	v_div_fmas_f32 v7, v7, v13, v15
	v_div_fixup_f32 v6, v7, v6, 1.0
	v_mul_f32_e32 v6, v9, v6
	v_mul_f32_e32 v7, v12, v6
	ds_bpermute_b32 v6, v110, v7
	v_cmp_gt_u32_e32 vcc, 32, v22
	v_lshl_add_u32 v9, v78, 2, 0
	v_readlane_b32 s7, v254, 50
	v_add_u32_e32 v9, 0xc0, v9
	s_waitcnt lgkmcnt(0)
	v_mul_f32_e32 v6, v11, v6
	v_cndmask_b32_e64 v6, v6, -v6, vcc
	v_fmac_f32_e32 v6, v10, v7
	s_andn2_b64 vcc, exec, s[6:7]
	s_waitcnt vmcnt(0)
	ds_write2st64_b32 v9, v6, v3 offset0:60 offset1:64
	s_cbranch_vccnz .LBB0_447
	v_readlane_b32 s6, v254, 8
	v_ashrrev_i32_e32 v9, 31, v8
	s_nop 0
	v_mov_b32_e32 v7, s6
	ds_read_b64 v[10:11], v7
	s_lshl_b64 s[6:7], s[94:95], 10
	s_waitcnt lgkmcnt(0)
	v_readfirstlane_b32 s10, v10
	v_readfirstlane_b32 s11, v11
	s_add_u32 s6, s10, s6
	s_addc_u32 s7, s11, s7
	v_lshl_add_u64 v[8:9], v[8:9], 2, s[6:7]
	v_lshl_add_u64 v[8:9], v[8:9], 0, v[0:1]
	v_add_co_u32_e32 v10, vcc, 0x6558000, v8
	s_nop 1
	v_addc_co_u32_e32 v11, vcc, 0, v9, vcc
	flat_store_dword v[10:11], v6
	v_add_co_u32_e32 v6, vcc, 0x6578000, v8
	s_nop 1
	v_addc_co_u32_e32 v7, vcc, 0, v9, vcc
	flat_store_dword v[6:7], v3

.LBB0_459:
	v_add_u32_e32 v28, s4, v30
	v_mad_i64_i32 v[6:7], s[4:5], s14, v28, 0
	v_lshl_add_u64 v[10:11], v[6:7], 1, v[2:3]
	v_mov_b32_e32 v14, s9
	flat_load_dwordx4 v[6:9], v[10:11] nt
	s_nop 0
	flat_load_dwordx4 v[10:13], v[10:11] offset:64 nt
	ds_read_b64 v[14:15], v14
	s_lshl_b64 s[4:5], s[12:13], 2
	v_ashrrev_i32_e32 v29, 31, v28
	s_waitcnt lgkmcnt(0)
	v_readfirstlane_b32 s6, v14
	v_readfirstlane_b32 s7, v15
	s_add_u32 s4, s6, s4
	s_addc_u32 s5, s7, s5
	s_nop 1
	v_lshl_add_u64 v[144:145], s[4:5], 0, v[0:1]
	global_load_dwordx4 v[146:149], v[144:145], off offset:144
	s_nop 1
	v_lshl_add_u64 v[138:139], s[4:5], 0, v[0:1]
	global_load_dwordx4 v[140:143], v[138:139], off offset:16
	s_nop 1
	v_lshl_add_u64 v[132:133], s[4:5], 0, v[0:1]
	global_load_dwordx4 v[134:137], v[132:133], off
	v_lshl_add_u64 v[18:19], s[4:5], 0, v[0:1]
	flat_load_dwordx4 v[14:17], v[18:19] offset:128
	s_waitcnt vmcnt(0)
	v_lshlrev_b32_e32 v37, 16, v7
	v_lshlrev_b32_e32 v21, 16, v11
	v_lshlrev_b32_e32 v20, 16, v10
	v_and_b32_e32 v23, 0xffff0000, v11
	v_and_b32_e32 v22, 0xffff0000, v10
	v_and_b32_e32 v35, 0xffff0000, v13
	v_and_b32_e32 v34, 0xffff0000, v12
	v_lshlrev_b32_e32 v36, 16, v6
	v_and_b32_e32 v39, 0xffff0000, v7
	v_and_b32_e32 v38, 0xffff0000, v6
	v_mov_b32_e32 v6, v23
	v_mov_b32_e32 v7, v21
	s_waitcnt lgkmcnt(0)
	v_mov_b32_e32 v24, v14
	v_mov_b32_e32 v25, v16
	v_mov_b32_e32 v16, v15
	v_lshlrev_b32_e32 v15, 16, v13
	v_lshlrev_b32_e32 v14, 16, v12
	s_waitcnt vmcnt(0)
	s_nop 0
	v_mov_b32_e32 v10, v134
	v_mov_b32_e32 v11, v135
	v_mov_b32_e32 v12, v136
	v_mov_b32_e32 v13, v137
	s_nop 1
	v_pk_mul_f32 v[6:7], v[6:7], v[6:7]
	v_mov_b32_e32 v40, v39
	v_mov_b32_e32 v41, v37
	v_pk_fma_f32 v[40:41], v[40:41], v[40:41], v[6:7]
	v_and_b32_e32 v45, 0xffff0000, v9
	v_and_b32_e32 v44, 0xffff0000, v8
	v_mul_f32_e32 v27, v38, v38
	v_mul_f32_e32 v33, v36, v36
	v_fmac_f32_e32 v27, v22, v22
	v_fmac_f32_e32 v33, v20, v20
	v_mov_b32_e32 v46, v34
	v_mov_b32_e32 v47, v14
	v_add_f32_e32 v27, v33, v27
	v_pk_mul_f32 v[46:47], v[46:47], v[46:47]
	v_mov_b32_e32 v48, v44
	v_add_f32_e32 v27, v41, v27
	v_add_f32_e32 v27, v40, v27
	v_mov_b32_e32 v50, v45
	s_waitcnt vmcnt(0) lgkmcnt(0)
	v_mov_b32_e32 v42, v10
	v_mov_b32_e32 v43, v12
	v_mov_b32_e32 v12, v11
	v_lshlrev_b32_e32 v11, 16, v9
	v_lshlrev_b32_e32 v10, 16, v8
	s_waitcnt vmcnt(0)
	s_nop 0
	v_mov_b32_e32 v6, v140
	v_mov_b32_e32 v7, v141
	v_mov_b32_e32 v8, v142
	v_mov_b32_e32 v9, v143
	s_nop 1
	v_mov_b32_e32 v49, v10
	v_pk_fma_f32 v[46:47], v[48:49], v[48:49], v[46:47]
	v_mov_b32_e32 v48, v35
	v_mov_b32_e32 v49, v15
	v_pk_mul_f32 v[48:49], v[48:49], v[48:49]
	v_mov_b32_e32 v51, v11
	v_add_f32_e32 v27, v47, v27
	v_pk_fma_f32 v[48:49], v[50:51], v[50:51], v[48:49]
	v_add_f32_e32 v27, v46, v27
	v_add_f32_e32 v27, v49, v27
	v_add_f32_e32 v27, v48, v27
	ds_bpermute_b32 v33, v109, v27
	s_waitcnt lgkmcnt(0)
	v_add_f32_e32 v27, v27, v33
	ds_bpermute_b32 v33, v110, v27
	s_waitcnt lgkmcnt(0)
	v_add_f32_e32 v27, v27, v33
	v_fmamk_f32 v27, v27, 0x3c800000, v219
	v_cmp_gt_f32_e32 vcc, s85, v27
	v_mul_f32_e32 v33, 0x4f800000, v27
	s_nop 0
	v_cndmask_b32_e32 v27, v27, v33, vcc
	v_sqrt_f32_e32 v33, v27
	s_nop 0
	v_add_u32_e32 v40, -1, v33
	v_fma_f32 v41, -v40, v33, v27
	v_cmp_ge_f32_e64 s[4:5], 0, v41
	v_add_u32_e32 v41, 1, v33
	s_nop 0
	v_cndmask_b32_e64 v40, v33, v40, s[4:5]
	v_fma_f32 v33, -v41, v33, v27
	v_cmp_lt_f32_e64 s[4:5], 0, v33
	s_nop 1
	v_cndmask_b32_e64 v33, v40, v41, s[4:5]
	v_mul_f32_e32 v40, 0x37800000, v33
	v_cndmask_b32_e32 v33, v33, v40, vcc
	v_cmp_class_f32_e32 vcc, v27, v221
	s_nop 1
	v_cndmask_b32_e32 v27, v33, v27, vcc
	v_div_scale_f32 v33, s[4:5], v27, v27, s86
	v_rcp_f32_e32 v40, v33
	s_nop 0
	v_fma_f32 v41, -v33, v40, 1.0
	v_fmac_f32_e32 v40, v41, v40
	v_div_scale_f32 v41, vcc, s86, v27, s86
	v_mul_f32_e32 v46, v41, v40
	v_fma_f32 v47, -v33, v46, v41
	v_fmac_f32_e32 v46, v47, v40
	v_fma_f32 v33, -v33, v46, v41
	v_div_fmas_f32 v33, v33, v40, v46
	v_div_fixup_f32 v40, v33, v27, s86
	v_pk_mul_f32 v[38:39], v[40:41], v[38:39] op_sel_hi:[0,1]
	v_pk_mul_f32 v[12:13], v[12:13], v[38:39]
	v_pk_mul_f32 v[10:11], v[40:41], v[10:11] op_sel_hi:[0,1]
	v_pk_mul_f32 v[36:37], v[40:41], v[36:37] op_sel_hi:[0,1]
	v_pk_mul_f32 v[36:37], v[42:43], v[36:37]
	v_bfe_u32 v27, v13, 16, 1
	v_bfe_u32 v33, v12, 16, 1
	v_add3_u32 v12, v12, v33, s91
	v_add3_u32 v13, v13, v27, s91
	v_pk_mul_f32 v[14:15], v[40:41], v[14:15] op_sel_hi:[0,1]
	s_waitcnt vmcnt(0)
	v_mov_b32_e32 v38, v6
	v_mov_b32_e32 v39, v8
	v_pk_mul_f32 v[10:11], v[38:39], v[10:11]
	v_pk_mul_f32 v[38:39], v[40:41], v[44:45] op_sel_hi:[0,1]
	v_mov_b32_e32 v8, v7
	v_pk_mul_f32 v[6:7], v[8:9], v[38:39]
	v_bfe_u32 v27, v10, 16, 1
	v_bfe_u32 v8, v7, 16, 1
	v_bfe_u32 v9, v6, 16, 1
	v_add3_u32 v6, v6, v9, s91
	v_add3_u32 v7, v7, v8, s91
	v_bfe_u32 v8, v36, 16, 1
	v_bfe_u32 v9, v37, 16, 1
	v_bfe_u32 v33, v11, 16, 1
	v_add3_u32 v11, v11, v33, s91
	v_add3_u32 v10, v10, v27, s91
	v_add3_u32 v9, v37, v9, s91
	v_add3_u32 v8, v36, v8, s91
	v_lshrrev_b32_e32 v27, 16, v8
	v_lshrrev_b32_e32 v33, 16, v9
	v_lshrrev_b32_e32 v8, 16, v10
	v_lshrrev_b32_e32 v9, 16, v11
	v_pk_mul_f32 v[10:11], v[40:41], v[20:21] op_sel_hi:[0,1]
	v_pk_mul_f32 v[20:21], v[24:25], v[10:11]
	v_pk_mul_f32 v[10:11], v[40:41], v[22:23] op_sel_hi:[0,1]
	v_and_or_b32 v9, v7, s33, v9
	v_and_or_b32 v8, v6, s33, v8
	v_and_or_b32 v7, v13, s33, v33
	v_and_or_b32 v6, v12, s33, v27
	v_pk_mul_f32 v[16:17], v[16:17], v[10:11]
	s_waitcnt vmcnt(0)
	s_nop 0
	v_mov_b32_e32 v10, v146
	v_mov_b32_e32 v11, v147
	v_mov_b32_e32 v12, v148
	v_mov_b32_e32 v13, v149
	s_nop 1
	s_waitcnt vmcnt(0) lgkmcnt(0)
	v_mov_b32_e32 v18, v10
	v_mov_b32_e32 v19, v12
	v_pk_mul_f32 v[14:15], v[18:19], v[14:15]
	v_pk_mul_f32 v[18:19], v[40:41], v[34:35] op_sel_hi:[0,1]
	v_mov_b32_e32 v12, v11
	v_pk_mul_f32 v[10:11], v[18:19], v[12:13]
	v_bfe_u32 v18, v17, 16, 1
	v_bfe_u32 v12, v11, 16, 1
	v_bfe_u32 v13, v10, 16, 1
	v_bfe_u32 v19, v16, 16, 1
	v_add3_u32 v16, v16, v19, s91
	v_add3_u32 v17, v17, v18, s91
	v_add3_u32 v10, v10, v13, s91
	v_add3_u32 v11, v11, v12, s91
	v_bfe_u32 v12, v20, 16, 1
	v_bfe_u32 v13, v21, 16, 1
	v_bfe_u32 v18, v14, 16, 1
	v_bfe_u32 v19, v15, 16, 1
	v_add3_u32 v15, v15, v19, s91
	v_add3_u32 v14, v14, v18, s91
	v_add3_u32 v13, v21, v13, s91
	v_add3_u32 v12, v20, v12, s91
	v_lshrrev_b32_e32 v18, 16, v12
	v_lshrrev_b32_e32 v19, 16, v13
	v_lshrrev_b32_e32 v12, 16, v14
	v_lshrrev_b32_e32 v13, 16, v15
	v_and_or_b32 v13, v11, s33, v13
	v_and_or_b32 v12, v10, s33, v12
	v_and_or_b32 v11, v17, s33, v19
	v_and_or_b32 v10, v16, s33, v18
	ds_read_b128 v[14:17], v31
	ds_read_b128 v[18:21], v31 offset:64
	s_waitcnt lgkmcnt(1)
	v_mfma_f32_16x16x32_bf16 v[14:17], v[14:17], v[6:9], 0
	s_waitcnt lgkmcnt(0)
	v_mfma_f32_16x16x32_bf16 v[34:37], v[18:21], v[10:13], v[14:17]
	ds_read_b128 v[18:21], v31 offset:2368
	s_nop 4
	ds_read_b128 v[14:17], v31 offset:2304
	s_waitcnt lgkmcnt(0)
	v_mfma_f32_16x16x32_bf16 v[14:17], v[14:17], v[6:9], 0
	v_mfma_f32_16x16x32_bf16 v[38:41], v[18:21], v[10:13], v[14:17]
	ds_read_b128 v[18:21], v31 offset:4672
	s_nop 5
	ds_read_b128 v[14:17], v31 offset:4608
	s_waitcnt lgkmcnt(0)
	v_mfma_f32_16x16x32_bf16 v[14:17], v[14:17], v[6:9], 0
	v_mfma_f32_16x16x32_bf16 v[42:45], v[18:21], v[10:13], v[14:17]
	ds_read_b128 v[18:21], v31 offset:6976
	s_nop 5
	ds_read_b128 v[14:17], v31 offset:6912
	s_waitcnt lgkmcnt(0)
	v_mfma_f32_16x16x32_bf16 v[14:17], v[14:17], v[6:9], 0
	v_mfma_f32_16x16x32_bf16 v[50:53], v[18:21], v[10:13], v[14:17]
	ds_read_b128 v[18:21], v31 offset:9280
	s_nop 5
	ds_read_b128 v[14:17], v31 offset:9216
	s_waitcnt lgkmcnt(0)
	v_mfma_f32_16x16x32_bf16 v[14:17], v[14:17], v[6:9], 0
	v_mfma_f32_16x16x32_bf16 v[56:59], v[18:21], v[10:13], v[14:17]
	ds_read_b128 v[18:21], v31 offset:11584
	s_nop 5
	ds_read_b128 v[14:17], v31 offset:11520
	s_waitcnt lgkmcnt(0)
	v_mfma_f32_16x16x32_bf16 v[14:17], v[14:17], v[6:9], 0
	v_mfma_f32_16x16x32_bf16 v[66:69], v[18:21], v[10:13], v[14:17]
	ds_read_b128 v[18:21], v31 offset:13888
	s_nop 5
	ds_read_b128 v[14:17], v31 offset:13824
	s_waitcnt lgkmcnt(0)
	v_mfma_f32_16x16x32_bf16 v[14:17], v[14:17], v[6:9], 0
	v_mfma_f32_16x16x32_bf16 v[74:77], v[18:21], v[10:13], v[14:17]
	ds_read_b128 v[18:21], v31 offset:16192
	s_nop 5
	ds_read_b128 v[14:17], v31 offset:16128
	s_waitcnt lgkmcnt(0)
	v_mfma_f32_16x16x32_bf16 v[14:17], v[14:17], v[6:9], 0
	v_mfma_f32_16x16x32_bf16 v[80:83], v[18:21], v[10:13], v[14:17]
	ds_read_b128 v[18:21], v31 offset:18496
	s_nop 5
	ds_read_b128 v[14:17], v31 offset:18432
	s_waitcnt lgkmcnt(0)
	v_mfma_f32_16x16x32_bf16 v[14:17], v[14:17], v[6:9], 0
	v_mfma_f32_16x16x32_bf16 v[84:87], v[18:21], v[10:13], v[14:17]
	ds_read_b128 v[18:21], v31 offset:20800
	s_nop 5
	ds_read_b128 v[14:17], v31 offset:20736
	s_waitcnt lgkmcnt(0)
	v_mfma_f32_16x16x32_bf16 v[14:17], v[14:17], v[6:9], 0
	v_mfma_f32_16x16x32_bf16 v[88:91], v[18:21], v[10:13], v[14:17]
	ds_read_b128 v[18:21], v31 offset:23104
	s_nop 5
	ds_read_b128 v[14:17], v31 offset:23040
	s_waitcnt lgkmcnt(0)
	v_mfma_f32_16x16x32_bf16 v[14:17], v[14:17], v[6:9], 0
	v_mfma_f32_16x16x32_bf16 v[92:95], v[18:21], v[10:13], v[14:17]
	ds_read_b128 v[18:21], v31 offset:25408
	s_nop 5
	ds_read_b128 v[14:17], v31 offset:25344
	s_waitcnt lgkmcnt(0)
	v_mfma_f32_16x16x32_bf16 v[14:17], v[14:17], v[6:9], 0
	v_mfma_f32_16x16x32_bf16 v[96:99], v[18:21], v[10:13], v[14:17]
	ds_read_b128 v[18:21], v31 offset:27712
	s_nop 5
	ds_read_b128 v[14:17], v31 offset:27648
	s_waitcnt lgkmcnt(0)
	v_mfma_f32_16x16x32_bf16 v[14:17], v[14:17], v[6:9], 0
	v_mfma_f32_16x16x32_bf16 v[22:25], v[18:21], v[10:13], v[14:17]
	ds_read_b128 v[18:21], v31 offset:30016
	s_nop 5
	ds_read_b128 v[14:17], v31 offset:29952
	s_waitcnt lgkmcnt(0)
	v_mfma_f32_16x16x32_bf16 v[14:17], v[14:17], v[6:9], 0
	ds_read_b128 v[46:49], v31 offset:32320
	v_mfma_f32_16x16x32_bf16 v[18:21], v[18:21], v[10:13], v[14:17]
	s_nop 5
	ds_read_b128 v[14:17], v31 offset:32256
	s_waitcnt lgkmcnt(0)
	v_mfma_f32_16x16x32_bf16 v[14:17], v[14:17], v[6:9], 0
	v_mfma_f32_16x16x32_bf16 v[14:17], v[46:49], v[10:13], v[14:17]
	ds_read_b128 v[46:49], v31 offset:34560
	s_waitcnt lgkmcnt(0)
	v_mfma_f32_16x16x32_bf16 v[6:9], v[46:49], v[6:9], 0
	ds_read_b128 v[46:49], v31 offset:34624
	s_waitcnt lgkmcnt(0)
	v_mfma_f32_16x16x32_bf16 v[6:9], v[46:49], v[10:13], v[6:9]
	v_max3_f32 v10, v34, s89, v35
	v_max3_f32 v10, v10, v36, v37
	v_max3_f32 v10, v10, v38, v39
	v_max3_f32 v10, v10, v40, v41
	v_max3_f32 v10, v10, v42, v43
	v_max3_f32 v10, v10, v44, v45
	v_max3_f32 v10, v10, v50, v51
	v_max3_f32 v10, v10, v52, v53
	v_max3_f32 v10, v10, v56, v57
	v_max3_f32 v10, v10, v58, v59
	v_max3_f32 v10, v10, v66, v67
	v_max3_f32 v10, v10, v68, v69
	v_max3_f32 v10, v10, v74, v75
	v_max3_f32 v10, v10, v76, v77
	v_max3_f32 v10, v10, v80, v81
	v_max3_f32 v10, v10, v82, v83
	v_max3_f32 v10, v10, v84, v85
	v_max3_f32 v10, v10, v86, v87
	v_max3_f32 v10, v10, v88, v89
	v_max3_f32 v10, v10, v90, v91
	v_max3_f32 v10, v10, v92, v93
	v_max3_f32 v10, v10, v94, v95
	v_max3_f32 v10, v10, v96, v97
	v_max3_f32 v10, v10, v98, v99
	v_max3_f32 v10, v10, v22, v23
	v_max3_f32 v10, v10, v24, v25
	v_max3_f32 v10, v10, v18, v19
	v_max3_f32 v10, v10, v20, v21
	v_max3_f32 v10, v10, v14, v15
	v_max3_f32 v10, v10, v16, v17
	v_max3_f32 v10, v10, v6, v7
	v_max3_f32 v10, v10, v8, v9
	ds_bpermute_b32 v11, v109, v10
	s_waitcnt lgkmcnt(0)
	v_max_f32_e32 v11, v11, v11
	v_max_f32_e32 v10, v10, v11
	ds_bpermute_b32 v11, v110, v10
	s_waitcnt lgkmcnt(0)
	v_max_f32_e32 v11, v11, v11
	v_max_f32_e32 v73, v10, v11
	v_sub_f32_e32 v11, v35, v73
	v_mul_f32_e32 v11, 0x3fb8aa3b, v11
	v_exp_f32_e32 v100, v11
	v_sub_f32_e32 v11, v36, v73
	v_mul_f32_e32 v11, 0x3fb8aa3b, v11
	v_exp_f32_e32 v101, v11
	v_sub_f32_e32 v11, v37, v73
	v_mul_f32_e32 v11, 0x3fb8aa3b, v11
	v_exp_f32_e32 v102, v11
	v_sub_f32_e32 v11, v38, v73
	v_mul_f32_e32 v11, 0x3fb8aa3b, v11
	v_exp_f32_e32 v103, v11
	v_sub_f32_e32 v11, v39, v73
	v_mul_f32_e32 v11, 0x3fb8aa3b, v11
	v_exp_f32_e32 v104, v11
	v_sub_f32_e32 v11, v40, v73
	v_mul_f32_e32 v11, 0x3fb8aa3b, v11
	v_exp_f32_e32 v105, v11
	v_sub_f32_e32 v11, v41, v73
	v_mul_f32_e32 v11, 0x3fb8aa3b, v11
	v_exp_f32_e32 v111, v11
	v_sub_f32_e32 v11, v42, v73
	v_mul_f32_e32 v11, 0x3fb8aa3b, v11
	v_sub_f32_e32 v10, v34, v73
	v_exp_f32_e32 v34, v11
	v_sub_f32_e32 v11, v43, v73
	v_mul_f32_e32 v11, 0x3fb8aa3b, v11
	v_exp_f32_e32 v46, v11
	v_sub_f32_e32 v11, v44, v73
	v_mul_f32_e32 v11, 0x3fb8aa3b, v11
	v_exp_f32_e32 v39, v11
	v_sub_f32_e32 v11, v45, v73
	v_mul_f32_e32 v11, 0x3fb8aa3b, v11
	v_exp_f32_e32 v55, v11
	v_sub_f32_e32 v11, v50, v73
	v_mul_f32_e32 v11, 0x3fb8aa3b, v11
	v_exp_f32_e32 v50, v11
	v_sub_f32_e32 v11, v51, v73
	v_mul_f32_e32 v11, 0x3fb8aa3b, v11
	v_exp_f32_e32 v65, v11
	v_sub_f32_e32 v11, v52, v73
	v_mul_f32_e32 v11, 0x3fb8aa3b, v11
	v_exp_f32_e32 v62, v11
	v_sub_f32_e32 v11, v53, v73
	v_mul_f32_e32 v11, 0x3fb8aa3b, v11
	v_exp_f32_e32 v72, v11
	v_sub_f32_e32 v11, v56, v73
	v_mul_f32_e32 v11, 0x3fb8aa3b, v11
	v_exp_f32_e32 v33, v11
	v_sub_f32_e32 v11, v57, v73
	v_mul_f32_e32 v11, 0x3fb8aa3b, v11
	v_exp_f32_e32 v44, v11
	v_sub_f32_e32 v11, v58, v73
	v_mul_f32_e32 v11, 0x3fb8aa3b, v11
	v_exp_f32_e32 v38, v11
	v_sub_f32_e32 v11, v59, v73
	v_mul_f32_e32 v11, 0x3fb8aa3b, v11
	v_exp_f32_e32 v54, v11
	v_sub_f32_e32 v11, v66, v73
	v_mul_f32_e32 v11, 0x3fb8aa3b, v11
	v_exp_f32_e32 v49, v11
	v_sub_f32_e32 v11, v67, v73
	v_mul_f32_e32 v11, 0x3fb8aa3b, v11
	v_exp_f32_e32 v64, v11
	v_sub_f32_e32 v11, v68, v73
	v_mul_f32_e32 v11, 0x3fb8aa3b, v11
	v_exp_f32_e32 v60, v11
	v_sub_f32_e32 v11, v69, v73
	v_mul_f32_e32 v11, 0x3fb8aa3b, v11
	v_exp_f32_e32 v71, v11
	v_sub_f32_e32 v11, v74, v73
	v_mul_f32_e32 v11, 0x3fb8aa3b, v11
	v_mul_f32_e32 v10, 0x3fb8aa3b, v10
	v_exp_f32_e32 v27, v11
	v_sub_f32_e32 v11, v75, v73
	v_exp_f32_e32 v79, v10
	v_mul_f32_e32 v11, 0x3fb8aa3b, v11
	v_exp_f32_e32 v43, v11
	v_sub_f32_e32 v11, v76, v73
	v_mul_f32_e32 v11, 0x3fb8aa3b, v11
	v_exp_f32_e32 v37, v11
	v_sub_f32_e32 v11, v77, v73
	v_add_f32_e32 v10, 0, v79
	v_mul_f32_e32 v11, 0x3fb8aa3b, v11
	v_add_f32_e32 v10, v100, v10
	v_exp_f32_e32 v53, v11
	v_sub_f32_e32 v11, v80, v73
	v_add_f32_e32 v10, v101, v10
	v_mul_f32_e32 v11, 0x3fb8aa3b, v11
	v_add_f32_e32 v10, v102, v10
	v_exp_f32_e32 v48, v11
	v_sub_f32_e32 v11, v81, v73
	v_add_f32_e32 v10, v103, v10
	v_mul_f32_e32 v11, 0x3fb8aa3b, v11
	v_add_f32_e32 v10, v104, v10
	v_exp_f32_e32 v63, v11
	v_sub_f32_e32 v11, v82, v73
	v_add_f32_e32 v10, v105, v10
	v_mul_f32_e32 v11, 0x3fb8aa3b, v11
	v_add_f32_e32 v10, v111, v10
	v_exp_f32_e32 v58, v11
	v_sub_f32_e32 v11, v83, v73
	v_add_f32_e32 v10, v34, v10
	v_mul_f32_e32 v11, 0x3fb8aa3b, v11
	v_add_f32_e32 v10, v46, v10
	v_exp_f32_e32 v70, v11
	v_sub_f32_e32 v11, v84, v73
	v_add_f32_e32 v10, v39, v10
	v_mul_f32_e32 v11, 0x3fb8aa3b, v11
	v_add_f32_e32 v10, v55, v10
	v_exp_f32_e32 v13, v11
	v_sub_f32_e32 v11, v85, v73
	v_add_f32_e32 v10, v50, v10
	v_mul_f32_e32 v11, 0x3fb8aa3b, v11
	v_add_f32_e32 v10, v65, v10
	v_exp_f32_e32 v42, v11
	v_sub_f32_e32 v11, v86, v73
	v_add_f32_e32 v10, v62, v10
	v_mul_f32_e32 v11, 0x3fb8aa3b, v11
	v_add_f32_e32 v10, v72, v10
	v_exp_f32_e32 v36, v11
	v_sub_f32_e32 v11, v87, v73
	v_add_f32_e32 v10, v33, v10
	v_mul_f32_e32 v11, 0x3fb8aa3b, v11
	v_add_f32_e32 v10, v44, v10
	v_exp_f32_e32 v52, v11
	v_sub_f32_e32 v11, v88, v73
	v_add_f32_e32 v10, v38, v10
	v_mul_f32_e32 v11, 0x3fb8aa3b, v11
	v_add_f32_e32 v10, v54, v10
	v_exp_f32_e32 v47, v11
	v_sub_f32_e32 v11, v89, v73
	v_add_f32_e32 v10, v49, v10
	v_mul_f32_e32 v11, 0x3fb8aa3b, v11
	v_add_f32_e32 v10, v64, v10
	v_exp_f32_e32 v61, v11
	v_sub_f32_e32 v11, v90, v73
	v_add_f32_e32 v10, v60, v10
	v_mul_f32_e32 v11, 0x3fb8aa3b, v11
	v_add_f32_e32 v10, v71, v10
	v_exp_f32_e32 v57, v11
	v_sub_f32_e32 v11, v91, v73
	v_add_f32_e32 v10, v27, v10
	v_mul_f32_e32 v11, 0x3fb8aa3b, v11
	v_add_f32_e32 v10, v43, v10
	v_exp_f32_e32 v69, v11
	v_sub_f32_e32 v11, v92, v73
	v_add_f32_e32 v10, v37, v10
	v_mul_f32_e32 v11, 0x3fb8aa3b, v11
	v_add_f32_e32 v10, v53, v10
	v_exp_f32_e32 v12, v11
	v_sub_f32_e32 v11, v93, v73
	v_add_f32_e32 v10, v48, v10
	v_mul_f32_e32 v11, 0x3fb8aa3b, v11
	v_add_f32_e32 v10, v63, v10
	v_exp_f32_e32 v41, v11
	v_sub_f32_e32 v11, v94, v73
	v_add_f32_e32 v10, v58, v10
	v_mul_f32_e32 v11, 0x3fb8aa3b, v11
	v_add_f32_e32 v10, v70, v10
	v_exp_f32_e32 v35, v11
	v_sub_f32_e32 v11, v95, v73
	v_add_f32_e32 v10, v13, v10
	v_mul_f32_e32 v11, 0x3fb8aa3b, v11
	v_add_f32_e32 v10, v42, v10
	v_exp_f32_e32 v51, v11
	v_sub_f32_e32 v11, v96, v73
	v_add_f32_e32 v10, v36, v10
	v_mul_f32_e32 v11, 0x3fb8aa3b, v11
	v_add_f32_e32 v10, v52, v10
	v_exp_f32_e32 v45, v11
	v_sub_f32_e32 v11, v97, v73
	v_add_f32_e32 v10, v47, v10
	v_mul_f32_e32 v11, 0x3fb8aa3b, v11
	v_add_f32_e32 v10, v61, v10
	v_exp_f32_e32 v59, v11
	v_sub_f32_e32 v11, v98, v73
	v_add_f32_e32 v10, v57, v10
	v_mul_f32_e32 v11, 0x3fb8aa3b, v11
	v_add_f32_e32 v10, v69, v10
	v_exp_f32_e32 v56, v11
	v_sub_f32_e32 v11, v99, v73
	v_add_f32_e32 v10, v12, v10
	v_mul_f32_e32 v11, 0x3fb8aa3b, v11
	v_add_f32_e32 v10, v41, v10
	v_exp_f32_e32 v68, v11
	v_sub_f32_e32 v11, v22, v73
	v_sub_f32_e32 v22, v23, v73
	v_add_f32_e32 v10, v35, v10
	v_mul_f32_e32 v22, 0x3fb8aa3b, v22
	v_add_f32_e32 v10, v51, v10
	v_mul_f32_e32 v11, 0x3fb8aa3b, v11
	v_exp_f32_e32 v40, v22
	v_sub_f32_e32 v22, v24, v73
	v_add_f32_e32 v10, v45, v10
	v_exp_f32_e32 v11, v11
	v_mul_f32_e32 v22, 0x3fb8aa3b, v22
	v_add_f32_e32 v10, v59, v10
	v_exp_f32_e32 v23, v22
	v_sub_f32_e32 v22, v25, v73
	v_sub_f32_e32 v19, v19, v73
	v_add_f32_e32 v10, v56, v10
	v_mul_f32_e32 v22, 0x3fb8aa3b, v22
	v_sub_f32_e32 v18, v18, v73
	v_mul_f32_e32 v19, 0x3fb8aa3b, v19
	v_add_f32_e32 v10, v68, v10
	v_exp_f32_e32 v24, v22
	v_mul_f32_e32 v18, 0x3fb8aa3b, v18
	v_exp_f32_e32 v25, v19
	v_sub_f32_e32 v19, v20, v73
	v_add_f32_e32 v10, v11, v10
	v_exp_f32_e32 v18, v18
	v_mul_f32_e32 v19, 0x3fb8aa3b, v19
	v_add_f32_e32 v10, v40, v10
	v_exp_f32_e32 v20, v19
	v_sub_f32_e32 v19, v21, v73
	v_add_f32_e32 v10, v23, v10
	v_mul_f32_e32 v19, 0x3fb8aa3b, v19
	v_add_f32_e32 v10, v24, v10
	v_exp_f32_e32 v67, v19
	v_add_f32_e32 v10, v18, v10
	v_add_f32_e32 v10, v25, v10
	v_add_f32_e32 v10, v20, v10
	v_add_f32_e32 v19, v67, v10
	v_sub_f32_e32 v10, v14, v73
	v_mul_f32_e32 v10, 0x3fb8aa3b, v10
	v_sub_f32_e32 v15, v15, v73
	v_exp_f32_e32 v10, v10
	v_mul_f32_e32 v15, 0x3fb8aa3b, v15
	v_exp_f32_e32 v15, v15
	v_sub_f32_e32 v17, v17, v73
	v_add_f32_e32 v14, v10, v19
	v_mul_f32_e32 v17, 0x3fb8aa3b, v17
	v_add_f32_e32 v19, v15, v14
	v_sub_f32_e32 v14, v16, v73
	v_mul_f32_e32 v14, 0x3fb8aa3b, v14
	v_exp_f32_e32 v14, v14
	v_exp_f32_e32 v17, v17
	v_sub_f32_e32 v6, v6, v73
	v_mul_f32_e32 v6, 0x3fb8aa3b, v6
	v_add_f32_e32 v16, v14, v19
	v_add_f32_e32 v19, v17, v16
	v_exp_f32_e32 v16, v6
	v_sub_f32_e32 v7, v7, v73
	v_mul_f32_e32 v7, 0x3fb8aa3b, v7
	v_exp_f32_e32 v21, v7
	v_sub_f32_e32 v7, v8, v73
	v_mul_f32_e32 v7, 0x3fb8aa3b, v7
	v_add_f32_e32 v6, v16, v19
	v_exp_f32_e32 v19, v7
	v_sub_f32_e32 v7, v9, v73
	v_mul_f32_e32 v7, 0x3fb8aa3b, v7
	v_exp_f32_e32 v66, v7
	v_add_f32_e32 v6, v21, v6
	v_add_f32_e32 v6, v19, v6
	v_bfe_u32 v8, v102, 16, 1
	v_add_f32_e32 v6, v66, v6
	ds_bpermute_b32 v7, v109, v6
	v_bfe_u32 v9, v100, 16, 1
	v_add3_u32 v73, v100, v9, s91
	v_add3_u32 v74, v102, v8, s91
	v_bfe_u32 v8, v79, 16, 1
	s_waitcnt lgkmcnt(0)
	v_add_f32_e32 v6, v6, v7
	ds_bpermute_b32 v7, v110, v6
	v_bfe_u32 v9, v101, 16, 1
	v_bfe_u32 v75, v103, 16, 1
	v_bfe_u32 v76, v105, 16, 1
	v_add3_u32 v75, v103, v75, s91
	s_waitcnt lgkmcnt(0)
	v_add_f32_e32 v22, v6, v7
	v_bfe_u32 v7, v104, 16, 1
	v_add3_u32 v9, v101, v9, s91
	v_add3_u32 v8, v79, v8, s91
	v_bfe_u32 v6, v111, 16, 1
	v_add3_u32 v7, v104, v7, s91
	v_add3_u32 v76, v105, v76, s91
	v_lshrrev_b32_e32 v77, 16, v8
	v_lshrrev_b32_e32 v79, 16, v9
	v_lshrrev_b32_e32 v8, 16, v75
	v_add3_u32 v6, v111, v6, s91
	v_lshrrev_b32_e32 v9, 16, v76
	v_and_or_b32 v8, v7, s33, v8
	v_and_or_b32 v7, v74, s33, v79
	v_add_u32_e32 v79, 0x9000, v32
	v_add_u32_e32 v96, 0xb000, v32
	v_add_u32_e32 v97, 0xd000, v32
	v_add_u32_e32 v98, 0xf000, v32
	v_and_or_b32 v9, v6, s33, v9
	v_and_or_b32 v6, v73, s33, v77
	ds_read2_b64 v[74:77], v79 offset1:4
	ds_read2_b64 v[80:83], v96 offset0:32 offset1:36
	ds_read2_b64 v[84:87], v97 offset0:64 offset1:68
	ds_read2_b64 v[88:91], v98 offset0:96 offset1:100
	ds_read2_b64 v[92:95], v79 offset0:8 offset1:12
	s_waitcnt lgkmcnt(4)
	v_mfma_f32_16x16x32_bf16 v[74:77], v[74:77], v[6:9], 0
	v_bfe_u32 v73, v72, 16, 1
	v_add3_u32 v72, v72, v73, s91
	v_bfe_u32 v73, v34, 16, 1
	s_waitcnt lgkmcnt(3)
	v_mfma_f32_16x16x32_bf16 v[80:83], v[80:83], v[6:9], 0
	v_add3_u32 v34, v34, v73, s91
	v_lshrrev_b32_e32 v34, 16, v34
	s_waitcnt lgkmcnt(2)
	v_mfma_f32_16x16x32_bf16 v[84:87], v[84:87], v[6:9], 0
	s_waitcnt lgkmcnt(1)
	v_mfma_f32_16x16x32_bf16 v[6:9], v[88:91], v[6:9], 0
	v_bfe_u32 v88, v65, 16, 1
	v_bfe_u32 v89, v55, 16, 1
	v_bfe_u32 v90, v46, 16, 1
	v_add3_u32 v46, v46, v90, s91
	v_add3_u32 v55, v55, v89, s91
	v_add3_u32 v65, v65, v88, s91
	v_bfe_u32 v88, v39, 16, 1
	v_bfe_u32 v89, v50, 16, 1
	v_bfe_u32 v90, v62, 16, 1
	v_add3_u32 v62, v62, v90, s91
	v_add3_u32 v50, v50, v89, s91
	v_add3_u32 v39, v39, v88, s91
	v_lshrrev_b32_e32 v39, 16, v39
	v_lshrrev_b32_e32 v50, 16, v50
	v_lshrrev_b32_e32 v62, 16, v62
	v_and_or_b32 v91, v72, s33, v62
	v_and_or_b32 v90, v65, s33, v50
	v_and_or_b32 v89, v55, s33, v39
	v_and_or_b32 v88, v46, s33, v34
	v_bfe_u32 v46, v54, 16, 1
	v_bfe_u32 v50, v44, 16, 1
	s_waitcnt lgkmcnt(0)
	v_mfma_f32_16x16x32_bf16 v[72:75], v[92:95], v[88:91], v[74:77]
	ds_read2_b64 v[92:95], v96 offset0:40 offset1:44
	v_add3_u32 v44, v44, v50, s91
	v_add3_u32 v46, v54, v46, s91
	s_waitcnt lgkmcnt(0)
	v_mfma_f32_16x16x32_bf16 v[80:83], v[92:95], v[88:91], v[80:83]
	ds_read2_b64 v[92:95], v97 offset0:72 offset1:76
	v_bfe_u32 v50, v33, 16, 1
	v_bfe_u32 v54, v38, 16, 1
	s_waitcnt lgkmcnt(0)
	v_mfma_f32_16x16x32_bf16 v[84:87], v[92:95], v[88:91], v[84:87]
	ds_read2_b64 v[92:95], v98 offset0:104 offset1:108
	v_bfe_u32 v55, v49, 16, 1
	s_waitcnt lgkmcnt(0)
	v_mfma_f32_16x16x32_bf16 v[6:9], v[92:95], v[88:91], v[6:9]
	ds_read2_b64 v[92:95], v79 offset0:16 offset1:20
	v_bfe_u32 v62, v60, 16, 1
	v_bfe_u32 v34, v71, 16, 1
	v_bfe_u32 v39, v64, 16, 1
	v_add3_u32 v60, v60, v62, s91
	v_add3_u32 v49, v49, v55, s91
	v_add3_u32 v38, v38, v54, s91
	v_add3_u32 v33, v33, v50, s91
	v_add3_u32 v39, v64, v39, s91
	v_add3_u32 v34, v71, v34, s91
	v_lshrrev_b32_e32 v33, 16, v33
	v_lshrrev_b32_e32 v38, 16, v38
	v_lshrrev_b32_e32 v49, 16, v49
	v_lshrrev_b32_e32 v50, 16, v60
	v_and_or_b32 v91, v34, s33, v50
	v_and_or_b32 v90, v39, s33, v49
	v_and_or_b32 v89, v46, s33, v38
	v_and_or_b32 v88, v44, s33, v33
	v_bfe_u32 v39, v43, 16, 1
	v_add3_u32 v39, v43, v39, s91
	s_waitcnt lgkmcnt(0)
	v_mfma_f32_16x16x32_bf16 v[72:75], v[92:95], v[88:91], v[72:75]
	ds_read2_b64 v[92:95], v96 offset0:48 offset1:52
	v_bfe_u32 v43, v27, 16, 1
	v_bfe_u32 v44, v37, 16, 1
	s_waitcnt lgkmcnt(0)
	v_mfma_f32_16x16x32_bf16 v[80:83], v[92:95], v[88:91], v[80:83]
	ds_read2_b64 v[92:95], v97 offset0:80 offset1:84
	v_bfe_u32 v46, v48, 16, 1
	v_bfe_u32 v49, v58, 16, 1
	s_waitcnt lgkmcnt(0)
	v_mfma_f32_16x16x32_bf16 v[84:87], v[92:95], v[88:91], v[84:87]
	ds_read2_b64 v[92:95], v98 offset0:112 offset1:116
	v_bfe_u32 v33, v70, 16, 1
	s_waitcnt lgkmcnt(0)
	v_mfma_f32_16x16x32_bf16 v[6:9], v[92:95], v[88:91], v[6:9]
	ds_read2_b64 v[88:91], v79 offset0:24 offset1:28
	v_bfe_u32 v34, v63, 16, 1
	v_bfe_u32 v38, v53, 16, 1
	v_add3_u32 v49, v58, v49, s91
	v_add3_u32 v46, v48, v46, s91
	v_add3_u32 v37, v37, v44, s91
	v_add3_u32 v27, v27, v43, s91
	v_add3_u32 v38, v53, v38, s91
	v_add3_u32 v34, v63, v34, s91
	v_add3_u32 v33, v70, v33, s91
	v_lshrrev_b32_e32 v27, 16, v27
	v_lshrrev_b32_e32 v37, 16, v37
	v_lshrrev_b32_e32 v43, 16, v46
	v_lshrrev_b32_e32 v44, 16, v49
	v_and_or_b32 v65, v33, s33, v44
	v_and_or_b32 v64, v34, s33, v43
	v_and_or_b32 v63, v38, s33, v37
	v_and_or_b32 v62, v39, s33, v27
	v_bfe_u32 v39, v47, 16, 1
	v_add3_u32 v39, v47, v39, s91
	s_waitcnt lgkmcnt(0)
	v_mfma_f32_16x16x32_bf16 v[70:73], v[88:91], v[62:65], v[72:75]
	v_bfe_u32 v37, v42, 16, 1
	v_add3_u32 v42, v42, v37, s91
	v_bfe_u32 v37, v13, 16, 1
	ds_read2_b64 v[74:77], v96 offset0:56 offset1:60
	s_waitcnt lgkmcnt(0)
	v_mfma_f32_16x16x32_bf16 v[74:77], v[74:77], v[62:65], v[80:83]
	s_nop 2
	ds_read2_b64 v[80:83], v97 offset0:88 offset1:92
	v_bfe_u32 v38, v36, 16, 1
	v_bfe_u32 v43, v57, 16, 1
	s_waitcnt lgkmcnt(0)
	v_mfma_f32_16x16x32_bf16 v[80:83], v[80:83], v[62:65], v[84:87]
	s_nop 2
	ds_read2_b64 v[84:87], v98 offset0:120 offset1:124
	ds_read2_b64 v[46:49], v79 offset0:32 offset1:36
	v_bfe_u32 v27, v69, 16, 1
	v_bfe_u32 v33, v61, 16, 1
	v_bfe_u32 v34, v52, 16, 1
	v_add3_u32 v43, v57, v43, s91
	v_add3_u32 v36, v36, v38, s91
	v_add3_u32 v13, v13, v37, s91
	v_add3_u32 v34, v52, v34, s91
	v_add3_u32 v33, v61, v33, s91
	v_add3_u32 v27, v69, v27, s91
	v_lshrrev_b32_e32 v13, 16, v13
	v_lshrrev_b32_e32 v36, 16, v36
	v_lshrrev_b32_e32 v37, 16, v39
	v_lshrrev_b32_e32 v38, 16, v43
	v_and_or_b32 v39, v27, s33, v38
	v_and_or_b32 v38, v33, s33, v37
	v_and_or_b32 v37, v34, s33, v36
	v_and_or_b32 v36, v42, s33, v13
	s_waitcnt lgkmcnt(1)
	v_mfma_f32_16x16x32_bf16 v[6:9], v[84:87], v[62:65], v[6:9]
	ds_read2_b64 v[52:55], v96 offset0:64 offset1:68
	ds_read2_b64 v[60:63], v97 offset0:96 offset1:100
	v_bfe_u32 v13, v68, 16, 1
	s_waitcnt lgkmcnt(2)
	v_mfma_f32_16x16x32_bf16 v[46:49], v[46:49], v[36:39], v[70:73]
	v_bfe_u32 v27, v59, 16, 1
	v_bfe_u32 v33, v51, 16, 1
	v_bfe_u32 v34, v41, 16, 1
	ds_read2_b64 v[70:73], v98 offset0:128 offset1:132
	s_waitcnt lgkmcnt(2)
	v_mfma_f32_16x16x32_bf16 v[52:55], v[52:55], v[36:39], v[74:77]
	v_add3_u32 v34, v41, v34, s91
	v_add3_u32 v33, v51, v33, s91
	s_waitcnt lgkmcnt(1)
	v_mfma_f32_16x16x32_bf16 v[60:63], v[60:63], v[36:39], v[80:83]
	v_add3_u32 v27, v59, v27, s91
	v_add3_u32 v13, v68, v13, s91
	s_waitcnt lgkmcnt(0)
	v_mfma_f32_16x16x32_bf16 v[6:9], v[70:73], v[36:39], v[6:9]
	v_bfe_u32 v38, v45, 16, 1
	v_add3_u32 v38, v45, v38, s91
	ds_read2_b64 v[42:45], v79 offset0:40 offset1:44
	v_bfe_u32 v36, v12, 16, 1
	v_bfe_u32 v37, v35, 16, 1
	v_bfe_u32 v39, v56, 16, 1
	v_add3_u32 v39, v56, v39, s91
	v_add3_u32 v35, v35, v37, s91
	v_add3_u32 v12, v12, v36, s91
	v_lshrrev_b32_e32 v12, 16, v12
	v_lshrrev_b32_e32 v35, 16, v35
	v_lshrrev_b32_e32 v36, 16, v38
	v_lshrrev_b32_e32 v37, 16, v39
	v_and_or_b32 v37, v13, s33, v37
	v_and_or_b32 v36, v27, s33, v36
	v_and_or_b32 v35, v33, s33, v35
	v_and_or_b32 v34, v34, s33, v12
	v_bfe_u32 v33, v40, 16, 1
	v_add3_u32 v33, v40, v33, s91
	s_waitcnt lgkmcnt(0)
	v_mfma_f32_16x16x32_bf16 v[42:45], v[42:45], v[34:37], v[46:49]
	v_bfe_u32 v13, v25, 16, 1
	v_bfe_u32 v27, v24, 16, 1
	v_add3_u32 v24, v24, v27, s91
	ds_read2_b64 v[46:49], v96 offset0:72 offset1:76
	s_waitcnt lgkmcnt(0)
	v_mfma_f32_16x16x32_bf16 v[46:49], v[46:49], v[34:37], v[52:55]
	s_nop 2
	ds_read2_b64 v[50:53], v97 offset0:104 offset1:108
	ds_read2_b64 v[54:57], v98 offset0:136 offset1:140
	ds_read2_b64 v[38:41], v79 offset0:48 offset1:52
	s_waitcnt lgkmcnt(2)
	v_mfma_f32_16x16x32_bf16 v[50:53], v[50:53], v[34:37], v[60:63]
	v_add3_u32 v13, v25, v13, s91
	v_bfe_u32 v25, v11, 16, 1
	v_bfe_u32 v27, v23, 16, 1
	s_waitcnt lgkmcnt(1)
	v_mfma_f32_16x16x32_bf16 v[6:9], v[54:57], v[34:37], v[6:9]
	v_bfe_u32 v34, v18, 16, 1
	v_bfe_u32 v35, v20, 16, 1
	v_bfe_u32 v12, v67, 16, 1
	v_add3_u32 v20, v20, v35, s91
	v_add3_u32 v18, v18, v34, s91
	v_add3_u32 v23, v23, v27, s91
	v_add3_u32 v11, v11, v25, s91
	v_add3_u32 v12, v67, v12, s91
	v_lshrrev_b32_e32 v11, 16, v11
	v_lshrrev_b32_e32 v23, 16, v23
	v_lshrrev_b32_e32 v18, 16, v18
	v_lshrrev_b32_e32 v20, 16, v20
	v_and_or_b32 v37, v12, s33, v20
	v_and_or_b32 v36, v13, s33, v18
	v_and_or_b32 v35, v24, s33, v23
	v_and_or_b32 v34, v33, s33, v11
	v_bfe_u32 v12, v21, 16, 1
	v_bfe_u32 v13, v17, 16, 1
	s_waitcnt lgkmcnt(0)
	v_mfma_f32_16x16x32_bf16 v[38:41], v[38:41], v[34:37], v[42:45]
	v_bfe_u32 v18, v15, 16, 1
	v_add3_u32 v15, v15, v18, s91
	v_add3_u32 v13, v17, v13, s91
	ds_read2_b64 v[42:45], v96 offset0:80 offset1:84
	s_waitcnt lgkmcnt(0)
	v_mfma_f32_16x16x32_bf16 v[42:45], v[42:45], v[34:37], v[46:49]
	s_nop 2
	ds_read2_b64 v[46:49], v97 offset0:112 offset1:116
	v_add3_u32 v12, v21, v12, s91
	v_bfe_u32 v17, v10, 16, 1
	s_waitcnt lgkmcnt(0)
	v_mfma_f32_16x16x32_bf16 v[46:49], v[46:49], v[34:37], v[50:53]
	s_nop 2
	ds_read2_b64 v[50:53], v98 offset0:144 offset1:148
	v_bfe_u32 v18, v14, 16, 1
	v_bfe_u32 v20, v16, 16, 1
	v_bfe_u32 v21, v19, 16, 1
	v_bfe_u32 v11, v66, 16, 1
	v_add3_u32 v19, v19, v21, s91
	v_add3_u32 v16, v16, v20, s91
	v_add3_u32 v14, v14, v18, s91
	v_add3_u32 v10, v10, v17, s91
	v_add3_u32 v11, v66, v11, s91
	v_lshrrev_b32_e32 v10, 16, v10
	v_lshrrev_b32_e32 v14, 16, v14
	v_lshrrev_b32_e32 v16, 16, v16
	v_lshrrev_b32_e32 v17, 16, v19
	s_waitcnt lgkmcnt(0)
	v_mfma_f32_16x16x32_bf16 v[6:9], v[50:53], v[34:37], v[6:9]
	v_and_or_b32 v37, v11, s33, v17
	v_and_or_b32 v36, v12, s33, v16
	v_and_or_b32 v35, v13, s33, v14
	v_and_or_b32 v34, v15, s33, v10
	ds_read2_b64 v[10:13], v79 offset0:56 offset1:60
	v_div_scale_f32 v23, s[4:5], v22, v22, 1.0
	s_waitcnt lgkmcnt(0)
	v_mfma_f32_16x16x32_bf16 v[18:21], v[10:13], v[34:37], v[38:41]
	ds_read2_b64 v[10:13], v96 offset0:88 offset1:92
	v_rcp_f32_e32 v27, v23
	s_nop 0
	ds_read2_b64 v[38:41], v98 offset0:152 offset1:156
	s_waitcnt lgkmcnt(1)
	v_mfma_f32_16x16x32_bf16 v[14:17], v[10:13], v[34:37], v[42:45]
	ds_read2_b64 v[10:13], v97 offset0:120 offset1:124
	v_lshlrev_b64 v[24:25], 11, v[28:29]
	v_fma_f32 v28, -v23, v27, 1.0
	v_fmac_f32_e32 v27, v28, v27
	v_div_scale_f32 v28, vcc, 1.0, v22, 1.0
	v_mul_f32_e32 v29, v28, v27
	v_fma_f32 v33, -v23, v29, v28
	v_fmac_f32_e32 v29, v33, v27
	v_fma_f32 v23, -v23, v29, v28
	v_div_fmas_f32 v23, v23, v27, v29
	s_waitcnt lgkmcnt(0)
	v_mfma_f32_16x16x32_bf16 v[10:13], v[10:13], v[34:37], v[46:49]
	v_div_fixup_f32 v22, v23, v22, 1.0
	v_lshl_add_u64 v[24:25], s[0:1], 0, v[24:25]
	v_lshl_add_u64 v[24:25], v[24:25], 0, s[94:95]
	v_mfma_f32_16x16x32_bf16 v[6:9], v[38:41], v[34:37], v[6:9]
	v_mov_b32_e32 v35, v20
	v_mov_b32_e32 v20, v19
	v_mov_b32_e32 v34, v18
	v_pk_mul_f32 v[18:19], v[22:23], v[20:21] op_sel_hi:[0,1]
	v_mov_b32_e32 v27, v1
	v_pk_mul_f32 v[34:35], v[22:23], v[34:35] op_sel_hi:[0,1]
	v_and_b32_sdwa v23, v19, v218 dst_sel:DWORD dst_unused:UNUSED_PAD src0_sel:WORD_1 src1_sel:DWORD
	v_lshl_add_u64 v[24:25], v[24:25], 0, v[26:27]
	v_and_b32_sdwa v20, v35, v218 dst_sel:DWORD dst_unused:UNUSED_PAD src0_sel:WORD_1 src1_sel:DWORD
	v_and_b32_sdwa v27, v18, v218 dst_sel:DWORD dst_unused:UNUSED_PAD src0_sel:WORD_1 src1_sel:DWORD
	v_add3_u32 v19, v19, v23, s91
	v_and_b32_sdwa v21, v34, v218 dst_sel:DWORD dst_unused:UNUSED_PAD src0_sel:WORD_1 src1_sel:DWORD
	v_add3_u32 v20, v35, v20, s91
	v_add3_u32 v18, v18, v27, s91
	v_and_b32_e32 v19, 0xffff0000, v19
	v_add3_u32 v21, v34, v21, s91
	v_and_b32_e32 v18, 0xffff0000, v18
	v_or_b32_sdwa v19, v19, v20 dst_sel:DWORD dst_unused:UNUSED_PAD src0_sel:DWORD src1_sel:WORD_1
	v_add_co_u32_e32 v20, vcc, s8, v24
	v_or_b32_sdwa v18, v18, v21 dst_sel:DWORD dst_unused:UNUSED_PAD src0_sel:DWORD src1_sel:WORD_1
	s_nop 0
	v_addc_co_u32_e32 v21, vcc, 0, v25, vcc
	flat_store_dwordx2 v[20:21], v[18:19] offset:1536
	v_mov_b32_e32 v18, v14
	v_mov_b32_e32 v19, v16
	v_pk_mul_f32 v[18:19], v[22:23], v[18:19] op_sel_hi:[0,1]
	v_mov_b32_e32 v16, v15
	v_pk_mul_f32 v[14:15], v[22:23], v[16:17] op_sel_hi:[0,1]
	v_and_b32_sdwa v16, v19, v218 dst_sel:DWORD dst_unused:UNUSED_PAD src0_sel:WORD_1 src1_sel:DWORD
	v_and_b32_sdwa v17, v18, v218 dst_sel:DWORD dst_unused:UNUSED_PAD src0_sel:WORD_1 src1_sel:DWORD
	v_add3_u32 v17, v18, v17, s91
	v_add3_u32 v16, v19, v16, s91
	v_and_b32_sdwa v18, v15, v218 dst_sel:DWORD dst_unused:UNUSED_PAD src0_sel:WORD_1 src1_sel:DWORD
	v_and_b32_sdwa v19, v14, v218 dst_sel:DWORD dst_unused:UNUSED_PAD src0_sel:WORD_1 src1_sel:DWORD
	v_add3_u32 v15, v15, v18, s91
	v_add3_u32 v14, v14, v19, s91
	v_and_b32_e32 v15, 0xffff0000, v15
	v_and_b32_e32 v14, 0xffff0000, v14
	v_lshl_add_u64 v[28:29], v[24:25], 0, s[10:11]
	v_or_b32_sdwa v15, v15, v16 dst_sel:DWORD dst_unused:UNUSED_PAD src0_sel:DWORD src1_sel:WORD_1
	v_or_b32_sdwa v14, v14, v17 dst_sel:DWORD dst_unused:UNUSED_PAD src0_sel:DWORD src1_sel:WORD_1
	flat_store_dwordx2 v[28:29], v[14:15] offset:32
	v_mov_b32_e32 v14, v10
	v_mov_b32_e32 v15, v12
	v_pk_mul_f32 v[14:15], v[22:23], v[14:15] op_sel_hi:[0,1]
	v_mov_b32_e32 v12, v11
	v_pk_mul_f32 v[10:11], v[22:23], v[12:13] op_sel_hi:[0,1]
	v_and_b32_sdwa v12, v15, v218 dst_sel:DWORD dst_unused:UNUSED_PAD src0_sel:WORD_1 src1_sel:DWORD
	v_and_b32_sdwa v13, v14, v218 dst_sel:DWORD dst_unused:UNUSED_PAD src0_sel:WORD_1 src1_sel:DWORD
	v_add3_u32 v13, v14, v13, s91
	v_add3_u32 v12, v15, v12, s91
	v_and_b32_sdwa v14, v11, v218 dst_sel:DWORD dst_unused:UNUSED_PAD src0_sel:WORD_1 src1_sel:DWORD
	v_and_b32_sdwa v15, v10, v218 dst_sel:DWORD dst_unused:UNUSED_PAD src0_sel:WORD_1 src1_sel:DWORD
	v_add3_u32 v11, v11, v14, s91
	v_add3_u32 v10, v10, v15, s91
	v_and_b32_e32 v11, 0xffff0000, v11
	v_and_b32_e32 v10, 0xffff0000, v10
	v_or_b32_sdwa v11, v11, v12 dst_sel:DWORD dst_unused:UNUSED_PAD src0_sel:DWORD src1_sel:WORD_1
	v_or_b32_sdwa v10, v10, v13 dst_sel:DWORD dst_unused:UNUSED_PAD src0_sel:DWORD src1_sel:WORD_1
	flat_store_dwordx2 v[28:29], v[10:11] offset:64
	v_mov_b32_e32 v10, v6
	v_mov_b32_e32 v11, v8
	v_pk_mul_f32 v[10:11], v[22:23], v[10:11] op_sel_hi:[0,1]
	v_mov_b32_e32 v8, v7
	v_pk_mul_f32 v[6:7], v[22:23], v[8:9] op_sel_hi:[0,1]
	v_and_b32_sdwa v8, v11, v218 dst_sel:DWORD dst_unused:UNUSED_PAD src0_sel:WORD_1 src1_sel:DWORD
	v_and_b32_sdwa v9, v10, v218 dst_sel:DWORD dst_unused:UNUSED_PAD src0_sel:WORD_1 src1_sel:DWORD
	v_add3_u32 v9, v10, v9, s91
	v_add3_u32 v8, v11, v8, s91
	v_and_b32_sdwa v10, v7, v218 dst_sel:DWORD dst_unused:UNUSED_PAD src0_sel:WORD_1 src1_sel:DWORD
	v_and_b32_sdwa v11, v6, v218 dst_sel:DWORD dst_unused:UNUSED_PAD src0_sel:WORD_1 src1_sel:DWORD
	v_add3_u32 v7, v7, v10, s91
	v_add3_u32 v6, v6, v11, s91
	v_and_b32_e32 v7, 0xffff0000, v7
	v_and_b32_e32 v6, 0xffff0000, v6
	v_or_b32_sdwa v7, v7, v8 dst_sel:DWORD dst_unused:UNUSED_PAD src0_sel:DWORD src1_sel:WORD_1
	v_or_b32_sdwa v6, v6, v9 dst_sel:DWORD dst_unused:UNUSED_PAD src0_sel:DWORD src1_sel:WORD_1
	s_movk_i32 s4, 0x80
	s_and_b64 vcc, exec, s[2:3]
	s_mov_b64 s[2:3], 0
	flat_store_dwordx2 v[28:29], v[6:7] offset:96
	s_cbranch_vccnz .LBB0_459
	s_waitcnt lgkmcnt(0)
	s_barrier

.LBB0_465:
	s_or_b64 exec, exec, s[4:5]
	v_pk_mul_f32 v[56:57], v[50:51], v[50:51]
	v_pk_mul_f32 v[60:61], v[52:53], v[52:53]
	v_pk_fma_f32 v[56:57], v[46:47], v[46:47], v[56:57]
	v_pk_fma_f32 v[60:61], v[48:49], v[48:49], v[60:61]
	v_add_f32_e32 v0, v57, v56
	v_pk_mul_f32 v[62:63], v[58:59], v[58:59]
	v_add_f32_e32 v0, v60, v0
	v_pk_fma_f32 v[62:63], v[64:65], v[64:65], v[62:63]
	v_add_f32_e32 v0, v61, v0
	v_pk_mul_f32 v[66:67], v[72:73], v[72:73]
	v_add_f32_e32 v0, v62, v0
	v_pk_fma_f32 v[66:67], v[70:71], v[70:71], v[66:67]
	v_add_f32_e32 v0, v63, v0
	v_add_f32_e32 v0, v66, v0
	v_add_f32_e32 v0, v67, v0
	ds_bpermute_b32 v55, v5, v0
	s_cmp_eq_u32 s13, 31
	v_readlane_b32 s6, v254, 49
	s_cselect_b64 s[4:5], -1, 0
	v_readlane_b32 s7, v254, 50
	s_waitcnt lgkmcnt(0)
	v_add_f32_e32 v0, v0, v55
	ds_bpermute_b32 v55, v106, v0
	s_and_b64 s[6:7], s[6:7], s[4:5]
	v_max_i32_e32 v54, 0, v54
	s_nop 1
	v_lshl_or_b32 v175, v54, 5, v3
	v_or_b32_e32 v180, 4, v175
	v_ashrrev_i32_e32 v181, 31, v180
	v_lshlrev_b64 v[180:181], 2, v[180:181]
	v_lshl_add_u64 v[182:183], s[10:11], 0, v[180:181]
	global_load_dwordx4 v[184:187], v[182:183], off
	s_nop 1
	v_lshl_or_b32 v174, v54, 5, v3
	v_or_b32_e32 v170, 4, v174
	v_ashrrev_i32_e32 v171, 31, v170
	v_lshlrev_b64 v[170:171], 2, v[170:171]
	v_lshl_add_u64 v[172:173], s[8:9], 0, v[170:171]
	global_load_dwordx4 v[176:179], v[172:173], off
	s_nop 1
	v_lshl_or_b32 v146, v54, 5, v3
	v_ashrrev_i32_e32 v147, 31, v146
	v_lshlrev_b64 v[142:143], 2, v[146:147]
	v_lshl_add_u64 v[144:145], s[8:9], 0, v[142:143]
	global_load_dwordx4 v[148:151], v[144:145], off
	s_nop 1
	v_lshl_or_b32 v134, v54, 5, v3
	v_ashrrev_i32_e32 v135, 31, v134
	v_lshlrev_b64 v[132:133], 2, v[134:135]
	v_lshl_add_u64 v[136:137], s[10:11], 0, v[132:133]
	global_load_dwordx4 v[138:141], v[136:137], off
	v_lshl_or_b32 v76, v54, 5, v3
	v_ashrrev_i32_e32 v77, 31, v76
	s_waitcnt lgkmcnt(0)
	v_add_f32_e32 v0, v0, v55
	v_fmamk_f32 v0, v0, 0x3c800000, v219
	v_cmp_gt_f32_e32 vcc, s85, v0
	v_mul_f32_e32 v55, 0x4f800000, v0
	s_and_b32 s20, s20, 0xffffff80
	v_cndmask_b32_e32 v0, v0, v55, vcc
	v_sqrt_f32_e32 v55, v0
	s_addk_i32 s20, 0xff80
	v_add_u32_e32 v56, -1, v55
	v_fma_f32 v57, -v56, v55, v0
	v_cmp_ge_f32_e64 s[4:5], 0, v57
	v_add_u32_e32 v57, 1, v55
	s_nop 0
	v_cndmask_b32_e64 v56, v55, v56, s[4:5]
	v_fma_f32 v55, -v57, v55, v0
	v_cmp_lt_f32_e64 s[4:5], 0, v55
	s_nop 1
	v_cndmask_b32_e64 v55, v56, v57, s[4:5]
	v_mul_f32_e32 v56, 0x37800000, v55
	v_cndmask_b32_e32 v55, v55, v56, vcc
	v_cmp_class_f32_e32 vcc, v0, v221
	s_nop 1
	v_cndmask_b32_e32 v0, v55, v0, vcc
	v_div_scale_f32 v55, s[4:5], v0, v0, 1.0
	v_rcp_f32_e32 v56, v55
	v_readlane_b32 s4, v254, 15
	v_fma_f32 v57, -v55, v56, 1.0
	v_fmac_f32_e32 v56, v57, v56
	v_div_scale_f32 v57, vcc, 1.0, v0, 1.0
	v_mul_f32_e32 v60, v57, v56
	v_fma_f32 v61, -v55, v60, v57
	v_fmac_f32_e32 v60, v61, v56
	v_fma_f32 v55, -v55, v60, v57
	v_div_fmas_f32 v55, v55, v56, v60
	v_div_fixup_f32 v74, v55, v0, 1.0
	v_mov_b32_e32 v0, s4
	ds_read_b64 v[56:57], v0
	v_lshlrev_b32_e32 v0, 2, v3
	v_lshlrev_b64 v[54:55], 2, v[76:77]
	v_lshl_add_u64 v[80:81], s[10:11], 0, v[54:55]
	s_waitcnt vmcnt(0)
	s_nop 0
	v_mov_b32_e32 v84, v138
	v_mov_b32_e32 v85, v139
	v_mov_b32_e32 v86, v140
	v_mov_b32_e32 v87, v141
	s_nop 1
	s_waitcnt lgkmcnt(0)
	v_readfirstlane_b32 s4, v56
	v_readfirstlane_b32 s5, v57
	s_nop 1
	v_lshl_add_u64 v[188:189], s[4:5], 0, v[0:1]
	global_load_dwordx4 v[190:193], v[188:189], off offset:16
	s_nop 1
	v_lshl_add_u64 v[164:165], s[4:5], 0, v[0:1]
	global_load_dwordx4 v[166:169], v[164:165], off offset:144
	s_nop 1
	v_lshl_add_u64 v[158:159], s[4:5], 0, v[0:1]
	global_load_dwordx4 v[160:163], v[158:159], off
	s_nop 1
	v_lshl_add_u64 v[152:153], s[4:5], 0, v[0:1]
	global_load_dwordx4 v[154:157], v[152:153], off offset:128
	v_lshl_add_u64 v[56:57], s[8:9], 0, v[54:55]
	s_waitcnt vmcnt(0)
	s_nop 0
	v_mov_b32_e32 v54, v148
	v_mov_b32_e32 v55, v149
	v_mov_b32_e32 v56, v150
	v_mov_b32_e32 v57, v151
	s_nop 1
	v_lshl_add_u64 v[66:67], s[4:5], 0, v[0:1]
	s_waitcnt vmcnt(0)
	s_nop 0
	v_mov_b32_e32 v60, v154
	v_mov_b32_e32 v61, v155
	v_mov_b32_e32 v62, v156
	v_mov_b32_e32 v63, v157
	s_nop 1
	s_waitcnt vmcnt(0)
	s_nop 0
	v_mov_b32_e32 v88, v160
	v_mov_b32_e32 v89, v161
	v_mov_b32_e32 v90, v162
	v_mov_b32_e32 v91, v163
	s_nop 1
	v_pk_mul_f32 v[50:51], v[50:51], v[74:75] op_sel_hi:[1,0]
	v_pk_mul_f32 v[46:47], v[46:47], v[74:75] op_sel_hi:[1,0]
	v_pk_mul_f32 v[52:53], v[52:53], v[74:75] op_sel_hi:[1,0]
	v_pk_mul_f32 v[48:49], v[48:49], v[74:75] op_sel_hi:[1,0]
	v_pk_mul_f32 v[58:59], v[58:59], v[74:75] op_sel_hi:[1,0]
	s_movk_i32 s4, 0x7f
	v_cmp_lt_i32_e32 vcc, s4, v82
	s_and_b64 s[22:23], s[6:7], vcc
	s_waitcnt vmcnt(0) lgkmcnt(0)
	v_pk_mul_f32 v[60:61], v[60:61], v[50:51]
	v_pk_mul_f32 v[46:47], v[88:89], v[46:47]
	v_pk_mul_f32 v[50:51], v[84:85], v[60:61]
	v_pk_mul_f32 v[48:49], v[48:49], v[90:91]
	v_pk_fma_f32 v[50:51], v[54:55], v[46:47], v[50:51] neg_lo:[0,0,1] neg_hi:[0,0,1]
	v_pk_mul_f32 v[54:55], v[54:55], v[60:61]
	v_bfe_u32 v69, v50, 16, 1
	v_pk_fma_f32 v[46:47], v[84:85], v[46:47], v[54:55]
	v_pk_mul_f32 v[54:55], v[52:53], v[62:63]
	s_waitcnt vmcnt(0)
	s_nop 0
	v_mov_b32_e32 v60, v166
	v_mov_b32_e32 v61, v167
	v_mov_b32_e32 v62, v168
	v_mov_b32_e32 v63, v169
	s_nop 1
	v_pk_mul_f32 v[52:53], v[86:87], v[54:55]
	v_pk_mul_f32 v[54:55], v[56:57], v[54:55]
	v_pk_fma_f32 v[52:53], v[56:57], v[48:49], v[52:53] neg_lo:[0,0,1] neg_hi:[0,0,1]
	v_pk_fma_f32 v[48:49], v[86:87], v[48:49], v[54:55]
	v_or_b32_e32 v54, 4, v76
	v_ashrrev_i32_e32 v55, 31, v54
	v_lshlrev_b64 v[54:55], 2, v[54:55]
	v_lshl_add_u64 v[80:81], s[10:11], 0, v[54:55]
	v_lshl_add_u64 v[56:57], s[8:9], 0, v[54:55]
	s_waitcnt vmcnt(0)
	s_nop 0
	v_mov_b32_e32 v54, v176
	v_mov_b32_e32 v55, v177
	v_mov_b32_e32 v56, v178
	v_mov_b32_e32 v57, v179
	s_nop 1
	v_add3_u32 v69, v50, v69, s91
	v_lshrrev_b32_e32 v69, 16, v69
	s_waitcnt vmcnt(0) lgkmcnt(0)
	v_pk_mul_f32 v[76:77], v[58:59], v[60:61]
	s_waitcnt vmcnt(0)
	s_nop 0
	v_mov_b32_e32 v58, v184
	v_mov_b32_e32 v59, v185
	v_mov_b32_e32 v60, v186
	v_mov_b32_e32 v61, v187
	s_nop 1
	v_pk_mul_f32 v[80:81], v[64:65], v[74:75] op_sel_hi:[1,0]
	s_waitcnt vmcnt(0)
	s_nop 0
	v_mov_b32_e32 v64, v190
	v_mov_b32_e32 v65, v191
	v_mov_b32_e32 v66, v192
	v_mov_b32_e32 v67, v193
	s_nop 1
	s_waitcnt vmcnt(0) lgkmcnt(0)
	v_pk_mul_f32 v[80:81], v[80:81], v[64:65]
	v_pk_mul_f32 v[64:65], v[58:59], v[76:77]
	s_nop 0
	v_pk_fma_f32 v[64:65], v[54:55], v[80:81], v[64:65] neg_lo:[0,0,1] neg_hi:[0,0,1]
	v_pk_mul_f32 v[54:55], v[54:55], v[76:77]
	s_nop 0
	v_pk_fma_f32 v[54:55], v[58:59], v[80:81], v[54:55]
	v_pk_mul_f32 v[58:59], v[72:73], v[74:75] op_sel_hi:[1,0]
	s_nop 0
	v_pk_mul_f32 v[58:59], v[58:59], v[62:63]
	v_pk_mul_f32 v[62:63], v[70:71], v[74:75] op_sel_hi:[1,0]
	v_bfe_u32 v70, v64, 16, 1
	v_pk_mul_f32 v[62:63], v[62:63], v[66:67]
	v_pk_mul_f32 v[66:67], v[60:61], v[58:59]
	v_add3_u32 v70, v64, v70, s91
	v_pk_fma_f32 v[66:67], v[56:57], v[62:63], v[66:67] neg_lo:[0,0,1] neg_hi:[0,0,1]
	v_pk_mul_f32 v[56:57], v[56:57], v[58:59]
	v_bfe_u32 v58, v65, 16, 1
	v_pk_fma_f32 v[56:57], v[60:61], v[62:63], v[56:57]
	v_bfe_u32 v60, v67, 16, 1
	v_bfe_u32 v61, v53, 16, 1
	v_add3_u32 v62, v53, v61, s91
	v_add3_u32 v61, v67, v60, s91
	v_bfe_u32 v60, v52, 16, 1
	v_bfe_u32 v59, v51, 16, 1
	v_bfe_u32 v63, v66, 16, 1
	v_add3_u32 v60, v52, v60, s91
	v_add3_u32 v59, v51, v59, s91
	v_add3_u32 v58, v65, v58, s91
	v_add3_u32 v63, v66, v63, s91
	v_lshrrev_b32_e32 v71, 16, v60
	v_lshrrev_b32_e32 v60, 16, v70
	v_lshrrev_b32_e32 v63, 16, v63
	v_and_or_b32 v60, v58, s33, v60
	v_and_or_b32 v58, v59, s33, v69
	v_and_or_b32 v59, v62, s33, v71
	v_mul_lo_u32 v62, v82, s88
	v_and_or_b32 v61, v61, s33, v63
	v_add3_u32 v62, 0, v62, v68
	ds_write_b128 v62, v[58:61]
	v_bfe_u32 v60, v57, 16, 1
	v_bfe_u32 v61, v49, 16, 1
	v_add3_u32 v63, v49, v61, s91
	v_add3_u32 v61, v57, v60, s91
	v_bfe_u32 v60, v48, 16, 1
	v_bfe_u32 v69, v56, 16, 1
	v_bfe_u32 v70, v46, 16, 1
	v_bfe_u32 v71, v54, 16, 1
	v_bfe_u32 v58, v55, 16, 1
	v_bfe_u32 v59, v47, 16, 1
	v_add3_u32 v71, v54, v71, s91
	v_add3_u32 v70, v46, v70, s91
	v_add3_u32 v69, v56, v69, s91
	v_add3_u32 v60, v48, v60, s91
	v_add3_u32 v59, v47, v59, s91
	v_add3_u32 v58, v55, v58, s91
	v_lshrrev_b32_e32 v72, 16, v60
	v_lshrrev_b32_e32 v69, 16, v69
	v_lshrrev_b32_e32 v70, 16, v70
	v_lshrrev_b32_e32 v60, 16, v71
	v_and_or_b32 v60, v58, s33, v60
	v_and_or_b32 v58, v59, s33, v70
	v_and_or_b32 v61, v61, s33, v69
	v_and_or_b32 v59, v63, s33, v72
	ds_write_b128 v62, v[58:61] offset:64
	s_and_saveexec_b64 s[4:5], s[22:23]
	s_cbranch_execz .LBB0_467
	v_readlane_b32 s21, v254, 8
	s_lshl_b32 s94, s15, 2
	s_nop 0
	v_mov_b32_e32 v58, s21
	ds_read_b64 v[58:59], v58
	s_mov_b32 s21, 0x4158000
	s_waitcnt lgkmcnt(0)
	v_readfirstlane_b32 s22, v58
	v_add_u32_e32 v58, s20, v82
	v_readfirstlane_b32 s23, v59
	v_ashrrev_i32_e32 v59, 31, v58
	v_lshlrev_b64 v[58:59], 10, v[58:59]
	v_lshl_add_u64 v[58:59], s[22:23], 0, v[58:59]
	v_lshl_add_u64 v[58:59], v[58:59], 0, s[94:95]
	v_lshl_add_u64 v[58:59], v[58:59], 0, v[0:1]
	s_mov_b64 s[22:23], 0x4158000
	v_lshl_add_u64 v[60:61], v[58:59], 0, s[22:23]
	v_add_co_u32_e32 v58, vcc, s21, v58
	s_nop 1
	v_addc_co_u32_e32 v59, vcc, 0, v59, vcc
	flat_store_dwordx4 v[58:59], v[50:53]
	flat_store_dwordx4 v[60:61], v[64:67] offset:16
	flat_store_dwordx4 v[60:61], v[46:49] offset:128
	flat_store_dwordx4 v[60:61], v[54:57] offset:144

.LBB0_469:
	s_or_b64 exec, exec, s[4:5]
	v_pk_mul_f32 v[56:57], v[50:51], v[50:51]
	v_pk_mul_f32 v[60:61], v[52:53], v[52:53]
	v_pk_fma_f32 v[56:57], v[46:47], v[46:47], v[56:57]
	v_pk_fma_f32 v[60:61], v[48:49], v[48:49], v[60:61]
	v_add_f32_e32 v55, v57, v56
	v_pk_mul_f32 v[62:63], v[58:59], v[58:59]
	v_add_f32_e32 v55, v60, v55
	v_pk_fma_f32 v[62:63], v[64:65], v[64:65], v[62:63]
	v_add_f32_e32 v55, v61, v55
	v_pk_mul_f32 v[66:67], v[72:73], v[72:73]
	v_add_f32_e32 v55, v62, v55
	v_pk_fma_f32 v[66:67], v[70:71], v[70:71], v[66:67]
	v_add_f32_e32 v55, v63, v55
	v_add_f32_e32 v55, v66, v55
	v_add_f32_e32 v55, v67, v55
	ds_bpermute_b32 v56, v5, v55
	v_max_i32_e32 v54, 0, v54
	s_nop 1
	v_lshl_or_b32 v175, v54, 5, v3
	v_or_b32_e32 v180, 4, v175
	v_ashrrev_i32_e32 v181, 31, v180
	v_lshlrev_b64 v[180:181], 2, v[180:181]
	v_lshl_add_u64 v[182:183], s[10:11], 0, v[180:181]
	global_load_dwordx4 v[184:187], v[182:183], off
	s_nop 1
	v_lshl_or_b32 v174, v54, 5, v3
	v_or_b32_e32 v170, 4, v174
	v_ashrrev_i32_e32 v171, 31, v170
	v_lshlrev_b64 v[170:171], 2, v[170:171]
	v_lshl_add_u64 v[172:173], s[8:9], 0, v[170:171]
	global_load_dwordx4 v[176:179], v[172:173], off
	s_nop 1
	v_lshl_or_b32 v146, v54, 5, v3
	v_ashrrev_i32_e32 v147, 31, v146
	v_lshlrev_b64 v[142:143], 2, v[146:147]
	v_lshl_add_u64 v[144:145], s[8:9], 0, v[142:143]
	global_load_dwordx4 v[148:151], v[144:145], off
	s_nop 1
	v_lshl_or_b32 v134, v54, 5, v3
	v_ashrrev_i32_e32 v135, 31, v134
	v_lshlrev_b64 v[132:133], 2, v[134:135]
	v_lshl_add_u64 v[136:137], s[10:11], 0, v[132:133]
	global_load_dwordx4 v[138:141], v[136:137], off
	v_lshl_or_b32 v76, v54, 5, v3
	v_ashrrev_i32_e32 v77, 31, v76
	s_waitcnt lgkmcnt(0)
	v_add_f32_e32 v55, v55, v56
	ds_bpermute_b32 v56, v106, v55
	s_waitcnt lgkmcnt(0)
	v_add_f32_e32 v55, v55, v56
	v_fmamk_f32 v55, v55, 0x3c800000, v219
	v_cmp_gt_f32_e32 vcc, s85, v55
	v_mul_f32_e32 v56, 0x4f800000, v55
	s_nop 0
	v_cndmask_b32_e32 v55, v55, v56, vcc
	v_sqrt_f32_e32 v56, v55
	s_nop 0
	v_add_u32_e32 v57, -1, v56
	v_fma_f32 v60, -v57, v56, v55
	v_cmp_ge_f32_e64 s[4:5], 0, v60
	v_add_u32_e32 v60, 1, v56
	s_nop 0
	v_cndmask_b32_e64 v57, v56, v57, s[4:5]
	v_fma_f32 v56, -v60, v56, v55
	v_cmp_lt_f32_e64 s[4:5], 0, v56
	s_nop 1
	v_cndmask_b32_e64 v56, v57, v60, s[4:5]
	v_mul_f32_e32 v57, 0x37800000, v56
	v_cndmask_b32_e32 v56, v56, v57, vcc
	v_cmp_class_f32_e32 vcc, v55, v221
	s_nop 1
	v_cndmask_b32_e32 v55, v56, v55, vcc
	v_div_scale_f32 v56, s[4:5], v55, v55, 1.0
	v_rcp_f32_e32 v57, v56
	v_readlane_b32 s4, v254, 15
	v_fma_f32 v60, -v56, v57, 1.0
	v_fmac_f32_e32 v57, v60, v57
	v_div_scale_f32 v60, vcc, 1.0, v55, 1.0
	v_mul_f32_e32 v61, v60, v57
	v_fma_f32 v62, -v56, v61, v60
	v_fmac_f32_e32 v61, v62, v57
	v_fma_f32 v56, -v56, v61, v60
	v_div_fmas_f32 v56, v56, v57, v61
	v_div_fixup_f32 v74, v56, v55, 1.0
	v_mov_b32_e32 v55, s4
	ds_read_b64 v[56:57], v55
	v_lshlrev_b64 v[54:55], 2, v[76:77]
	v_lshl_add_u64 v[80:81], s[10:11], 0, v[54:55]
	s_waitcnt vmcnt(0)
	s_nop 0
	v_mov_b32_e32 v84, v138
	v_mov_b32_e32 v85, v139
	v_mov_b32_e32 v86, v140
	v_mov_b32_e32 v87, v141
	s_nop 1
	v_pk_mul_f32 v[50:51], v[50:51], v[74:75] op_sel_hi:[1,0]
	s_waitcnt lgkmcnt(0)
	v_readfirstlane_b32 s4, v56
	v_readfirstlane_b32 s5, v57
	s_nop 1
	v_lshl_add_u64 v[188:189], s[4:5], 0, v[0:1]
	global_load_dwordx4 v[190:193], v[188:189], off offset:16
	s_nop 1
	v_lshl_add_u64 v[164:165], s[4:5], 0, v[0:1]
	global_load_dwordx4 v[166:169], v[164:165], off offset:144
	s_nop 1
	v_lshl_add_u64 v[158:159], s[4:5], 0, v[0:1]
	global_load_dwordx4 v[160:163], v[158:159], off
	s_nop 1
	v_lshl_add_u64 v[152:153], s[4:5], 0, v[0:1]
	global_load_dwordx4 v[154:157], v[152:153], off offset:128
	v_lshl_add_u64 v[56:57], s[8:9], 0, v[54:55]
	s_waitcnt vmcnt(0)
	s_nop 0
	v_mov_b32_e32 v54, v148
	v_mov_b32_e32 v55, v149
	v_mov_b32_e32 v56, v150
	v_mov_b32_e32 v57, v151
	s_nop 1
	v_lshl_add_u64 v[66:67], s[4:5], 0, v[0:1]
	s_waitcnt vmcnt(0)
	s_nop 0
	v_mov_b32_e32 v60, v154
	v_mov_b32_e32 v61, v155
	v_mov_b32_e32 v62, v156
	v_mov_b32_e32 v63, v157
	s_nop 1
	s_waitcnt vmcnt(0)
	s_nop 0
	v_mov_b32_e32 v88, v160
	v_mov_b32_e32 v89, v161
	v_mov_b32_e32 v90, v162
	v_mov_b32_e32 v91, v163
	s_nop 1
	v_pk_mul_f32 v[46:47], v[46:47], v[74:75] op_sel_hi:[1,0]
	v_pk_mul_f32 v[52:53], v[52:53], v[74:75] op_sel_hi:[1,0]
	v_pk_mul_f32 v[48:49], v[48:49], v[74:75] op_sel_hi:[1,0]
	v_pk_mul_f32 v[58:59], v[58:59], v[74:75] op_sel_hi:[1,0]
	s_movk_i32 s4, 0x7f
	v_cmp_lt_i32_e32 vcc, s4, v82
	s_waitcnt vmcnt(0) lgkmcnt(0)
	v_pk_mul_f32 v[60:61], v[60:61], v[50:51]
	v_pk_mul_f32 v[46:47], v[88:89], v[46:47]
	v_pk_mul_f32 v[50:51], v[84:85], v[60:61]
	v_pk_mul_f32 v[48:49], v[48:49], v[90:91]
	v_pk_fma_f32 v[50:51], v[54:55], v[46:47], v[50:51] neg_lo:[0,0,1] neg_hi:[0,0,1]
	v_pk_mul_f32 v[54:55], v[54:55], v[60:61]
	s_nop 0
	v_pk_fma_f32 v[46:47], v[84:85], v[46:47], v[54:55]
	v_pk_mul_f32 v[54:55], v[52:53], v[62:63]
	s_waitcnt vmcnt(0)
	s_nop 0
	v_mov_b32_e32 v60, v166
	v_mov_b32_e32 v61, v167
	v_mov_b32_e32 v62, v168
	v_mov_b32_e32 v63, v169
	s_nop 1
	v_pk_mul_f32 v[52:53], v[86:87], v[54:55]
	v_pk_mul_f32 v[54:55], v[56:57], v[54:55]
	v_pk_fma_f32 v[52:53], v[56:57], v[48:49], v[52:53] neg_lo:[0,0,1] neg_hi:[0,0,1]
	v_pk_fma_f32 v[48:49], v[86:87], v[48:49], v[54:55]
	v_or_b32_e32 v54, 4, v76
	v_ashrrev_i32_e32 v55, 31, v54
	v_lshlrev_b64 v[54:55], 2, v[54:55]
	v_lshl_add_u64 v[80:81], s[10:11], 0, v[54:55]
	v_lshl_add_u64 v[56:57], s[8:9], 0, v[54:55]
	s_waitcnt vmcnt(0)
	s_nop 0
	v_mov_b32_e32 v54, v176
	v_mov_b32_e32 v55, v177
	v_mov_b32_e32 v56, v178
	v_mov_b32_e32 v57, v179
	s_nop 1
	s_and_b64 s[8:9], s[6:7], vcc
	s_waitcnt vmcnt(0) lgkmcnt(0)
	v_pk_mul_f32 v[76:77], v[58:59], v[60:61]
	s_waitcnt vmcnt(0)
	s_nop 0
	v_mov_b32_e32 v58, v184
	v_mov_b32_e32 v59, v185
	v_mov_b32_e32 v60, v186
	v_mov_b32_e32 v61, v187
	s_nop 1
	v_pk_mul_f32 v[80:81], v[64:65], v[74:75] op_sel_hi:[1,0]
	s_waitcnt vmcnt(0)
	s_nop 0
	v_mov_b32_e32 v64, v190
	v_mov_b32_e32 v65, v191
	v_mov_b32_e32 v66, v192
	v_mov_b32_e32 v67, v193
	s_nop 1
	s_waitcnt vmcnt(0) lgkmcnt(0)
	v_pk_mul_f32 v[80:81], v[80:81], v[64:65]
	v_pk_mul_f32 v[64:65], v[58:59], v[76:77]
	s_nop 0
	v_pk_fma_f32 v[64:65], v[54:55], v[80:81], v[64:65] neg_lo:[0,0,1] neg_hi:[0,0,1]
	v_pk_mul_f32 v[54:55], v[54:55], v[76:77]
	v_bfe_u32 v69, v64, 16, 1
	v_pk_fma_f32 v[54:55], v[58:59], v[80:81], v[54:55]
	v_pk_mul_f32 v[58:59], v[72:73], v[74:75] op_sel_hi:[1,0]
	v_bfe_u32 v3, v65, 16, 1
	v_pk_mul_f32 v[58:59], v[58:59], v[62:63]
	v_pk_mul_f32 v[62:63], v[70:71], v[74:75] op_sel_hi:[1,0]
	v_add3_u32 v69, v64, v69, s91
	v_pk_mul_f32 v[62:63], v[62:63], v[66:67]
	v_pk_mul_f32 v[66:67], v[60:61], v[58:59]
	v_add3_u32 v3, v65, v3, s91
	v_pk_fma_f32 v[66:67], v[56:57], v[62:63], v[66:67] neg_lo:[0,0,1] neg_hi:[0,0,1]
	v_pk_mul_f32 v[56:57], v[56:57], v[58:59]
	v_bfe_u32 v58, v51, 16, 1
	v_pk_fma_f32 v[56:57], v[60:61], v[62:63], v[56:57]
	v_bfe_u32 v60, v53, 16, 1
	v_add3_u32 v62, v53, v60, s91
	v_bfe_u32 v60, v52, 16, 1
	v_bfe_u32 v61, v66, 16, 1
	v_bfe_u32 v63, v50, 16, 1
	v_add3_u32 v60, v52, v60, s91
	v_bfe_u32 v59, v67, 16, 1
	v_add3_u32 v63, v50, v63, s91
	v_add3_u32 v61, v66, v61, s91
	v_lshrrev_b32_e32 v70, 16, v60
	v_lshrrev_b32_e32 v60, 16, v69
	v_add3_u32 v59, v67, v59, s91
	v_add3_u32 v58, v51, v58, s91
	v_lshrrev_b32_e32 v61, 16, v61
	v_lshrrev_b32_e32 v63, 16, v63
	v_and_or_b32 v60, v3, s33, v60
	v_mul_lo_u32 v3, v82, s88
	v_and_or_b32 v58, v58, s33, v63
	v_and_or_b32 v61, v59, s33, v61
	v_and_or_b32 v59, v62, s33, v70
	v_add3_u32 v3, 0, v3, v68
	ds_write_b128 v3, v[58:61]
	v_bfe_u32 v60, v57, 16, 1
	v_bfe_u32 v61, v49, 16, 1
	v_add3_u32 v62, v49, v61, s91
	v_add3_u32 v61, v57, v60, s91
	v_bfe_u32 v60, v48, 16, 1
	v_bfe_u32 v63, v56, 16, 1
	v_bfe_u32 v68, v46, 16, 1
	v_bfe_u32 v69, v54, 16, 1
	v_bfe_u32 v58, v55, 16, 1
	v_bfe_u32 v59, v47, 16, 1
	v_add3_u32 v69, v54, v69, s91
	v_add3_u32 v68, v46, v68, s91
	v_add3_u32 v63, v56, v63, s91
	v_add3_u32 v60, v48, v60, s91
	v_add3_u32 v59, v47, v59, s91
	v_add3_u32 v58, v55, v58, s91
	v_lshrrev_b32_e32 v70, 16, v60
	v_lshrrev_b32_e32 v63, 16, v63
	v_lshrrev_b32_e32 v68, 16, v68
	v_lshrrev_b32_e32 v60, 16, v69
	v_and_or_b32 v60, v58, s33, v60
	v_and_or_b32 v58, v59, s33, v68
	v_and_or_b32 v61, v61, s33, v63
	v_and_or_b32 v59, v62, s33, v70
	ds_write_b128 v3, v[58:61] offset:64
	s_and_saveexec_b64 s[4:5], s[8:9]
	s_cbranch_execz .LBB0_471
	v_readlane_b32 s8, v254, 8
	s_lshl_b32 s94, s15, 2
	s_nop 0
	v_mov_b32_e32 v3, s8
	ds_read_b64 v[58:59], v3
	s_waitcnt lgkmcnt(0)
	v_readfirstlane_b32 s8, v58
	v_add_u32_e32 v58, s20, v82
	v_readfirstlane_b32 s9, v59
	v_ashrrev_i32_e32 v59, 31, v58
	v_lshlrev_b64 v[58:59], 10, v[58:59]
	v_lshl_add_u64 v[58:59], s[8:9], 0, v[58:59]
	v_lshl_add_u64 v[58:59], v[58:59], 0, s[94:95]
	v_lshl_add_u64 v[58:59], v[58:59], 0, v[0:1]
	s_mov_b64 s[8:9], 0x4158000
	v_lshl_add_u64 v[60:61], v[58:59], 0, s[8:9]
	s_mov_b32 s8, 0x4158000
	v_add_co_u32_e32 v58, vcc, s8, v58
	s_nop 1
	v_addc_co_u32_e32 v59, vcc, 0, v59, vcc
	flat_store_dwordx4 v[58:59], v[50:53]
	flat_store_dwordx4 v[60:61], v[64:67] offset:16
	flat_store_dwordx4 v[60:61], v[46:49] offset:128
	flat_store_dwordx4 v[60:61], v[54:57] offset:144

.LBB0_497:
	ds_read_b32 v12, v9
	v_add_u32_e32 v8, 64, v8
	v_max_f32_e32 v11, v11, v11
	v_cmp_lt_u32_e32 vcc, 64, v8
	v_add_u32_e32 v9, 0x100, v9
	s_waitcnt lgkmcnt(0)
	v_max_f32_e32 v12, v12, v12
	s_or_b64 s[6:7], vcc, s[6:7]
	v_max_f32_e32 v11, v11, v12
	s_andn2_b64 exec, exec, s[6:7]
	s_cbranch_execnz .LBB0_497
	s_or_b64 exec, exec, s[6:7]
	ds_bpermute_b32 v8, v5, v11
	v_max_f32_e32 v9, v11, v11
	v_readfirstlane_b32 s6, v6
	v_readfirstlane_b32 s7, v7
	s_nop 1
	v_add_u32_e32 v134, s40, v2
	v_ashrrev_i32_e32 v135, 31, v134
	v_mov_b32_e32 v132, s6
	v_mov_b32_e32 v133, s7
	v_lshl_add_u64 v[132:133], v[134:135], 2, v[132:133]
	global_load_dword v136, v[132:133], off
	v_add_u32_e32 v12, s40, v2
	s_waitcnt lgkmcnt(0)
	v_max_f32_e32 v8, v8, v8
	v_max_f32_e32 v8, v9, v8
	ds_bpermute_b32 v9, v106, v8
	v_ashrrev_i32_e32 v13, 31, v12
	s_mov_b32 s8, 0
	s_waitcnt lgkmcnt(0)
	v_max_f32_e32 v9, v9, v9
	v_max_f32_e32 v8, v8, v9
	ds_bpermute_b32 v9, v107, v8
	s_waitcnt lgkmcnt(0)
	v_max_f32_e32 v9, v9, v9
	v_max_f32_e32 v8, v8, v9
	ds_bpermute_b32 v9, v108, v8
	s_waitcnt lgkmcnt(0)
	v_max_f32_e32 v9, v9, v9
	v_max_f32_e32 v8, v8, v9
	ds_bpermute_b32 v9, v109, v8
	s_waitcnt lgkmcnt(0)
	v_max_f32_e32 v9, v9, v9
	v_max_f32_e32 v11, v8, v9
	v_mov_b32_e32 v8, s6
	v_mov_b32_e32 v9, s7
	v_lshl_add_u64 v[8:9], v[12:13], 2, v[8:9]
	s_waitcnt vmcnt(0)
	s_nop 0
	v_mov_b32_e32 v8, v136
	s_nop 1
	ds_bpermute_b32 v14, v110, v11
	s_mov_b64 s[6:7], 0
	v_mov_b32_e32 v12, v3
	s_waitcnt vmcnt(0) lgkmcnt(0)
	v_max3_f32 v9, v11, v14, v8
	v_mov_b32_e32 v11, 0

.LBB0_536:
	v_add_u32_e32 v28, s4, v5
	v_mad_i64_i32 v[6:7], s[4:5], s11, v28, 0
	v_lshl_add_u64 v[10:11], v[6:7], 1, v[2:3]
	v_mov_b32_e32 v14, s9
	flat_load_dwordx4 v[6:9], v[10:11] nt
	s_nop 0
	flat_load_dwordx4 v[10:13], v[10:11] offset:64 nt
	ds_read_b64 v[14:15], v14
	v_ashrrev_i32_e32 v29, 31, v28
	s_waitcnt lgkmcnt(0)
	v_readfirstlane_b32 s4, v14
	v_readfirstlane_b32 s5, v15
	s_add_u32 s4, s4, s6
	s_addc_u32 s5, s5, s7
	s_nop 1
	v_lshl_add_u64 v[126:127], s[4:5], 0, v[0:1]
	global_load_dwordx4 v[128:131], v[126:127], off offset:144
	s_nop 1
	v_lshl_add_u64 v[120:121], s[4:5], 0, v[0:1]
	global_load_dwordx4 v[122:125], v[120:121], off offset:16
	s_nop 1
	v_lshl_add_u64 v[114:115], s[4:5], 0, v[0:1]
	global_load_dwordx4 v[116:119], v[114:115], off
	v_lshl_add_u64 v[18:19], s[4:5], 0, v[0:1]
	flat_load_dwordx4 v[14:17], v[18:19] offset:128
	s_waitcnt vmcnt(0)
	v_lshlrev_b32_e32 v35, 16, v7
	v_lshlrev_b32_e32 v21, 16, v11
	v_lshlrev_b32_e32 v20, 16, v10
	v_and_b32_e32 v23, 0xffff0000, v11
	v_and_b32_e32 v22, 0xffff0000, v10
	v_and_b32_e32 v33, 0xffff0000, v13
	v_and_b32_e32 v32, 0xffff0000, v12
	v_lshlrev_b32_e32 v34, 16, v6
	v_and_b32_e32 v37, 0xffff0000, v7
	v_and_b32_e32 v36, 0xffff0000, v6
	v_mov_b32_e32 v6, v23
	v_mov_b32_e32 v7, v21
	s_waitcnt lgkmcnt(0)
	v_mov_b32_e32 v24, v14
	v_mov_b32_e32 v25, v16
	v_mov_b32_e32 v16, v15
	v_lshlrev_b32_e32 v15, 16, v13
	v_lshlrev_b32_e32 v14, 16, v12
	s_waitcnt vmcnt(0)
	s_nop 0
	v_mov_b32_e32 v10, v116
	v_mov_b32_e32 v11, v117
	v_mov_b32_e32 v12, v118
	v_mov_b32_e32 v13, v119
	s_nop 1
	v_pk_mul_f32 v[6:7], v[6:7], v[6:7]
	v_mov_b32_e32 v38, v37
	v_mov_b32_e32 v39, v35
	v_pk_fma_f32 v[38:39], v[38:39], v[38:39], v[6:7]
	v_and_b32_e32 v43, 0xffff0000, v9
	v_and_b32_e32 v42, 0xffff0000, v8
	v_mov_b32_e32 v44, v32
	v_mov_b32_e32 v45, v14
	v_pk_mul_f32 v[44:45], v[44:45], v[44:45]
	v_mov_b32_e32 v46, v42
	v_mov_b32_e32 v48, v43
	v_mul_f32_e32 v27, v36, v36
	v_fmac_f32_e32 v27, v22, v22
	s_waitcnt vmcnt(0) lgkmcnt(0)
	v_mov_b32_e32 v40, v10
	v_mov_b32_e32 v41, v12
	v_mov_b32_e32 v12, v11
	v_lshlrev_b32_e32 v11, 16, v9
	v_lshlrev_b32_e32 v10, 16, v8
	s_waitcnt vmcnt(0)
	s_nop 0
	v_mov_b32_e32 v6, v122
	v_mov_b32_e32 v7, v123
	v_mov_b32_e32 v8, v124
	v_mov_b32_e32 v9, v125
	s_nop 1
	v_mov_b32_e32 v47, v10
	v_pk_fma_f32 v[44:45], v[46:47], v[46:47], v[44:45]
	v_mov_b32_e32 v46, v33
	v_mov_b32_e32 v47, v15
	v_pk_mul_f32 v[46:47], v[46:47], v[46:47]
	v_mov_b32_e32 v49, v11
	v_pk_fma_f32 v[46:47], v[48:49], v[48:49], v[46:47]
	v_mul_f32_e32 v48, v34, v34
	v_fmac_f32_e32 v48, v20, v20
	v_add_f32_e32 v27, v48, v27
	v_add_f32_e32 v27, v39, v27
	v_add_f32_e32 v27, v38, v27
	v_add_f32_e32 v27, v45, v27
	v_add_f32_e32 v27, v44, v27
	v_add_f32_e32 v27, v47, v27
	v_add_f32_e32 v27, v46, v27
	ds_bpermute_b32 v38, v98, v27
	s_waitcnt lgkmcnt(0)
	v_add_f32_e32 v27, v27, v38
	ds_bpermute_b32 v38, v99, v27
	s_waitcnt lgkmcnt(0)
	v_add_f32_e32 v27, v27, v38
	v_fmamk_f32 v27, v27, 0x3c800000, v219
	v_cmp_gt_f32_e32 vcc, s85, v27
	v_mul_f32_e32 v38, 0x4f800000, v27
	s_nop 0
	v_cndmask_b32_e32 v27, v27, v38, vcc
	v_sqrt_f32_e32 v38, v27
	s_nop 0
	v_add_u32_e32 v39, -1, v38
	v_fma_f32 v44, -v39, v38, v27
	v_cmp_ge_f32_e64 s[4:5], 0, v44
	v_add_u32_e32 v44, 1, v38
	s_nop 0
	v_cndmask_b32_e64 v39, v38, v39, s[4:5]
	v_fma_f32 v38, -v44, v38, v27
	v_cmp_lt_f32_e64 s[4:5], 0, v38
	s_nop 1
	v_cndmask_b32_e64 v38, v39, v44, s[4:5]
	v_mul_f32_e32 v39, 0x37800000, v38
	v_cndmask_b32_e32 v38, v38, v39, vcc
	v_cmp_class_f32_e32 vcc, v27, v221
	s_nop 1
	v_cndmask_b32_e32 v27, v38, v27, vcc
	v_div_scale_f32 v38, s[4:5], v27, v27, s86
	v_rcp_f32_e32 v39, v38
	s_nop 0
	v_fma_f32 v44, -v38, v39, 1.0
	v_fmac_f32_e32 v39, v44, v39
	v_div_scale_f32 v44, vcc, s86, v27, s86
	v_mul_f32_e32 v45, v44, v39
	v_fma_f32 v46, -v38, v45, v44
	v_fmac_f32_e32 v45, v46, v39
	v_fma_f32 v38, -v38, v45, v44
	v_div_fmas_f32 v38, v38, v39, v45
	v_div_fixup_f32 v38, v38, v27, s86
	v_pk_mul_f32 v[36:37], v[38:39], v[36:37] op_sel_hi:[0,1]
	v_pk_mul_f32 v[12:13], v[12:13], v[36:37]
	v_pk_mul_f32 v[10:11], v[38:39], v[10:11] op_sel_hi:[0,1]
	v_pk_mul_f32 v[34:35], v[38:39], v[34:35] op_sel_hi:[0,1]
	v_pk_mul_f32 v[34:35], v[40:41], v[34:35]
	v_bfe_u32 v27, v13, 16, 1
	v_add3_u32 v13, v13, v27, s91
	v_pk_mul_f32 v[14:15], v[38:39], v[14:15] op_sel_hi:[0,1]
	s_waitcnt vmcnt(0)
	v_mov_b32_e32 v36, v6
	v_mov_b32_e32 v37, v8
	v_pk_mul_f32 v[10:11], v[36:37], v[10:11]
	v_pk_mul_f32 v[36:37], v[38:39], v[42:43] op_sel_hi:[0,1]
	v_mov_b32_e32 v8, v7
	v_pk_mul_f32 v[6:7], v[8:9], v[36:37]
	v_bfe_u32 v36, v12, 16, 1
	v_bfe_u32 v8, v7, 16, 1
	v_bfe_u32 v9, v6, 16, 1
	v_add3_u32 v12, v12, v36, s91
	v_add3_u32 v6, v6, v9, s91
	v_add3_u32 v7, v7, v8, s91
	v_bfe_u32 v8, v34, 16, 1
	v_bfe_u32 v9, v35, 16, 1
	v_bfe_u32 v27, v10, 16, 1
	v_bfe_u32 v36, v11, 16, 1
	v_add3_u32 v11, v11, v36, s91
	v_add3_u32 v10, v10, v27, s91
	v_add3_u32 v9, v35, v9, s91
	v_add3_u32 v8, v34, v8, s91
	v_lshrrev_b32_e32 v27, 16, v8
	v_lshrrev_b32_e32 v34, 16, v9
	v_lshrrev_b32_e32 v8, 16, v10
	v_lshrrev_b32_e32 v9, 16, v11
	v_pk_mul_f32 v[10:11], v[38:39], v[20:21] op_sel_hi:[0,1]
	v_pk_mul_f32 v[20:21], v[24:25], v[10:11]
	v_pk_mul_f32 v[10:11], v[38:39], v[22:23] op_sel_hi:[0,1]
	v_and_or_b32 v9, v7, s33, v9
	v_and_or_b32 v8, v6, s33, v8
	v_and_or_b32 v7, v13, s33, v34
	v_and_or_b32 v6, v12, s33, v27
	v_pk_mul_f32 v[16:17], v[16:17], v[10:11]
	s_waitcnt vmcnt(0)
	s_nop 0
	v_mov_b32_e32 v10, v128
	v_mov_b32_e32 v11, v129
	v_mov_b32_e32 v12, v130
	v_mov_b32_e32 v13, v131
	s_nop 1
	s_waitcnt vmcnt(0) lgkmcnt(0)
	v_mov_b32_e32 v18, v10
	v_mov_b32_e32 v19, v12
	v_pk_mul_f32 v[14:15], v[18:19], v[14:15]
	v_pk_mul_f32 v[18:19], v[38:39], v[32:33] op_sel_hi:[0,1]
	v_mov_b32_e32 v12, v11
	v_pk_mul_f32 v[10:11], v[18:19], v[12:13]
	v_bfe_u32 v18, v17, 16, 1
	v_bfe_u32 v12, v11, 16, 1
	v_bfe_u32 v13, v10, 16, 1
	v_bfe_u32 v19, v16, 16, 1
	v_add3_u32 v16, v16, v19, s91
	v_add3_u32 v17, v17, v18, s91
	v_add3_u32 v10, v10, v13, s91
	v_add3_u32 v11, v11, v12, s91
	v_bfe_u32 v12, v20, 16, 1
	v_bfe_u32 v13, v21, 16, 1
	v_bfe_u32 v18, v14, 16, 1
	v_bfe_u32 v19, v15, 16, 1
	v_add3_u32 v15, v15, v19, s91
	v_add3_u32 v14, v14, v18, s91
	v_add3_u32 v13, v21, v13, s91
	v_add3_u32 v12, v20, v12, s91
	v_lshrrev_b32_e32 v18, 16, v12
	v_lshrrev_b32_e32 v19, 16, v13
	v_lshrrev_b32_e32 v12, 16, v14
	v_lshrrev_b32_e32 v13, 16, v15
	v_and_or_b32 v13, v11, s33, v13
	v_and_or_b32 v12, v10, s33, v12
	v_and_or_b32 v11, v17, s33, v19
	v_and_or_b32 v10, v16, s33, v18
	ds_read_b128 v[14:17], v30
	ds_read_b128 v[18:21], v30 offset:64
	s_waitcnt lgkmcnt(1)
	v_mfma_f32_16x16x32_bf16 v[14:17], v[14:17], v[6:9], 0
	s_waitcnt lgkmcnt(0)
	v_mfma_f32_16x16x32_bf16 v[32:35], v[18:21], v[10:13], v[14:17]
	ds_read_b128 v[18:21], v30 offset:2368
	s_nop 4
	ds_read_b128 v[14:17], v30 offset:2304
	s_waitcnt lgkmcnt(0)
	v_mfma_f32_16x16x32_bf16 v[14:17], v[14:17], v[6:9], 0
	v_mfma_f32_16x16x32_bf16 v[36:39], v[18:21], v[10:13], v[14:17]
	ds_read_b128 v[18:21], v30 offset:4672
	s_nop 5
	ds_read_b128 v[14:17], v30 offset:4608
	s_waitcnt lgkmcnt(0)
	v_mfma_f32_16x16x32_bf16 v[14:17], v[14:17], v[6:9], 0
	v_mfma_f32_16x16x32_bf16 v[40:43], v[18:21], v[10:13], v[14:17]
	ds_read_b128 v[18:21], v30 offset:6976
	s_nop 5
	ds_read_b128 v[14:17], v30 offset:6912
	s_waitcnt lgkmcnt(0)
	v_mfma_f32_16x16x32_bf16 v[14:17], v[14:17], v[6:9], 0
	v_mfma_f32_16x16x32_bf16 v[50:53], v[18:21], v[10:13], v[14:17]
	ds_read_b128 v[18:21], v30 offset:9280
	s_nop 5
	ds_read_b128 v[14:17], v30 offset:9216
	s_waitcnt lgkmcnt(0)
	v_mfma_f32_16x16x32_bf16 v[14:17], v[14:17], v[6:9], 0
	v_mfma_f32_16x16x32_bf16 v[56:59], v[18:21], v[10:13], v[14:17]
	ds_read_b128 v[18:21], v30 offset:11584
	s_nop 5
	ds_read_b128 v[14:17], v30 offset:11520
	s_waitcnt lgkmcnt(0)
	v_mfma_f32_16x16x32_bf16 v[14:17], v[14:17], v[6:9], 0
	v_mfma_f32_16x16x32_bf16 v[66:69], v[18:21], v[10:13], v[14:17]
	ds_read_b128 v[18:21], v30 offset:13888
	s_nop 5
	ds_read_b128 v[14:17], v30 offset:13824
	s_waitcnt lgkmcnt(0)
	v_mfma_f32_16x16x32_bf16 v[14:17], v[14:17], v[6:9], 0
	v_mfma_f32_16x16x32_bf16 v[72:75], v[18:21], v[10:13], v[14:17]
	ds_read_b128 v[18:21], v30 offset:16192
	s_nop 5
	ds_read_b128 v[14:17], v30 offset:16128
	s_waitcnt lgkmcnt(0)
	v_mfma_f32_16x16x32_bf16 v[14:17], v[14:17], v[6:9], 0
	v_mfma_f32_16x16x32_bf16 v[76:79], v[18:21], v[10:13], v[14:17]
	ds_read_b128 v[18:21], v30 offset:18496
	s_nop 5
	ds_read_b128 v[14:17], v30 offset:18432
	s_waitcnt lgkmcnt(0)
	v_mfma_f32_16x16x32_bf16 v[14:17], v[14:17], v[6:9], 0
	v_mfma_f32_16x16x32_bf16 v[84:87], v[18:21], v[10:13], v[14:17]
	ds_read_b128 v[18:21], v30 offset:20800
	s_nop 5
	ds_read_b128 v[14:17], v30 offset:20736
	s_waitcnt lgkmcnt(0)
	v_mfma_f32_16x16x32_bf16 v[14:17], v[14:17], v[6:9], 0
	v_mfma_f32_16x16x32_bf16 v[88:91], v[18:21], v[10:13], v[14:17]
	ds_read_b128 v[18:21], v30 offset:23104
	s_nop 5
	ds_read_b128 v[14:17], v30 offset:23040
	s_waitcnt lgkmcnt(0)
	v_mfma_f32_16x16x32_bf16 v[14:17], v[14:17], v[6:9], 0
	v_mfma_f32_16x16x32_bf16 v[92:95], v[18:21], v[10:13], v[14:17]
	ds_read_b128 v[18:21], v30 offset:25408
	s_nop 5
	ds_read_b128 v[14:17], v30 offset:25344
	s_waitcnt lgkmcnt(0)
	v_mfma_f32_16x16x32_bf16 v[14:17], v[14:17], v[6:9], 0
	v_mfma_f32_16x16x32_bf16 v[102:105], v[18:21], v[10:13], v[14:17]
	ds_read_b128 v[18:21], v30 offset:27712
	s_nop 5
	ds_read_b128 v[14:17], v30 offset:27648
	s_waitcnt lgkmcnt(0)
	v_mfma_f32_16x16x32_bf16 v[14:17], v[14:17], v[6:9], 0
	v_mfma_f32_16x16x32_bf16 v[22:25], v[18:21], v[10:13], v[14:17]
	ds_read_b128 v[18:21], v30 offset:30016
	s_nop 5
	ds_read_b128 v[14:17], v30 offset:29952
	s_waitcnt lgkmcnt(0)
	v_mfma_f32_16x16x32_bf16 v[14:17], v[14:17], v[6:9], 0
	ds_read_b128 v[44:47], v30 offset:32320
	v_mfma_f32_16x16x32_bf16 v[18:21], v[18:21], v[10:13], v[14:17]
	s_nop 5
	ds_read_b128 v[14:17], v30 offset:32256
	s_waitcnt lgkmcnt(0)
	v_mfma_f32_16x16x32_bf16 v[14:17], v[14:17], v[6:9], 0
	v_mfma_f32_16x16x32_bf16 v[14:17], v[44:47], v[10:13], v[14:17]
	ds_read_b128 v[44:47], v30 offset:34560
	s_waitcnt lgkmcnt(0)
	v_mfma_f32_16x16x32_bf16 v[6:9], v[44:47], v[6:9], 0
	ds_read_b128 v[44:47], v30 offset:34624
	s_waitcnt lgkmcnt(0)
	v_mfma_f32_16x16x32_bf16 v[6:9], v[44:47], v[10:13], v[6:9]
	v_max3_f32 v10, v32, s89, v33
	v_max3_f32 v10, v10, v34, v35
	v_max3_f32 v10, v10, v36, v37
	v_max3_f32 v10, v10, v38, v39
	v_max3_f32 v10, v10, v40, v41
	v_max3_f32 v10, v10, v42, v43
	v_max3_f32 v10, v10, v50, v51
	v_max3_f32 v10, v10, v52, v53
	v_max3_f32 v10, v10, v56, v57
	v_max3_f32 v10, v10, v58, v59
	v_max3_f32 v10, v10, v66, v67
	v_max3_f32 v10, v10, v68, v69
	v_max3_f32 v10, v10, v72, v73
	v_max3_f32 v10, v10, v74, v75
	v_max3_f32 v10, v10, v76, v77
	v_max3_f32 v10, v10, v78, v79
	v_max3_f32 v10, v10, v84, v85
	v_max3_f32 v10, v10, v86, v87
	v_max3_f32 v10, v10, v88, v89
	v_max3_f32 v10, v10, v90, v91
	v_max3_f32 v10, v10, v92, v93
	v_max3_f32 v10, v10, v94, v95
	v_max3_f32 v10, v10, v102, v103
	v_max3_f32 v10, v10, v104, v105
	v_max3_f32 v10, v10, v22, v23
	v_max3_f32 v10, v10, v24, v25
	v_max3_f32 v10, v10, v18, v19
	v_max3_f32 v10, v10, v20, v21
	v_max3_f32 v10, v10, v14, v15
	v_max3_f32 v10, v10, v16, v17
	v_max3_f32 v10, v10, v6, v7
	v_max3_f32 v10, v10, v8, v9
	ds_bpermute_b32 v11, v98, v10
	s_waitcnt lgkmcnt(0)
	v_max_f32_e32 v11, v11, v11
	v_max_f32_e32 v10, v10, v11
	ds_bpermute_b32 v11, v99, v10
	s_waitcnt lgkmcnt(0)
	v_max_f32_e32 v11, v11, v11
	v_max_f32_e32 v65, v10, v11
	v_sub_f32_e32 v11, v33, v65
	v_mul_f32_e32 v11, 0x3fb8aa3b, v11
	v_exp_f32_e32 v81, v11
	v_sub_f32_e32 v11, v34, v65
	v_mul_f32_e32 v11, 0x3fb8aa3b, v11
	v_exp_f32_e32 v82, v11
	v_sub_f32_e32 v11, v35, v65
	v_mul_f32_e32 v11, 0x3fb8aa3b, v11
	v_exp_f32_e32 v96, v11
	v_sub_f32_e32 v11, v36, v65
	v_mul_f32_e32 v11, 0x3fb8aa3b, v11
	v_exp_f32_e32 v97, v11
	v_sub_f32_e32 v11, v37, v65
	v_mul_f32_e32 v11, 0x3fb8aa3b, v11
	v_exp_f32_e32 v101, v11
	v_sub_f32_e32 v11, v38, v65
	v_mul_f32_e32 v11, 0x3fb8aa3b, v11
	v_exp_f32_e32 v106, v11
	v_sub_f32_e32 v11, v39, v65
	v_mul_f32_e32 v11, 0x3fb8aa3b, v11
	v_exp_f32_e32 v107, v11
	v_sub_f32_e32 v11, v40, v65
	v_mul_f32_e32 v11, 0x3fb8aa3b, v11
	v_exp_f32_e32 v33, v11
	v_sub_f32_e32 v11, v41, v65
	v_mul_f32_e32 v11, 0x3fb8aa3b, v11
	v_exp_f32_e32 v45, v11
	v_sub_f32_e32 v11, v42, v65
	v_mul_f32_e32 v11, 0x3fb8aa3b, v11
	v_exp_f32_e32 v38, v11
	v_sub_f32_e32 v11, v43, v65
	v_mul_f32_e32 v11, 0x3fb8aa3b, v11
	v_exp_f32_e32 v54, v11
	v_sub_f32_e32 v11, v50, v65
	v_mul_f32_e32 v11, 0x3fb8aa3b, v11
	v_exp_f32_e32 v49, v11
	v_sub_f32_e32 v11, v51, v65
	v_mul_f32_e32 v11, 0x3fb8aa3b, v11
	v_exp_f32_e32 v64, v11
	v_sub_f32_e32 v11, v52, v65
	v_mul_f32_e32 v11, 0x3fb8aa3b, v11
	v_exp_f32_e32 v61, v11
	v_sub_f32_e32 v11, v53, v65
	v_mul_f32_e32 v11, 0x3fb8aa3b, v11
	v_exp_f32_e32 v71, v11
	v_sub_f32_e32 v11, v56, v65
	v_mul_f32_e32 v11, 0x3fb8aa3b, v11
	v_sub_f32_e32 v10, v32, v65
	v_exp_f32_e32 v32, v11
	v_sub_f32_e32 v11, v57, v65
	v_mul_f32_e32 v11, 0x3fb8aa3b, v11
	v_exp_f32_e32 v43, v11
	v_sub_f32_e32 v11, v58, v65
	v_mul_f32_e32 v11, 0x3fb8aa3b, v11
	v_exp_f32_e32 v37, v11
	v_sub_f32_e32 v11, v59, v65
	v_mul_f32_e32 v11, 0x3fb8aa3b, v11
	v_exp_f32_e32 v53, v11
	v_sub_f32_e32 v11, v66, v65
	v_mul_f32_e32 v11, 0x3fb8aa3b, v11
	v_exp_f32_e32 v48, v11
	v_sub_f32_e32 v11, v67, v65
	v_mul_f32_e32 v11, 0x3fb8aa3b, v11
	v_exp_f32_e32 v63, v11
	v_sub_f32_e32 v11, v68, v65
	v_mul_f32_e32 v11, 0x3fb8aa3b, v11
	v_exp_f32_e32 v59, v11
	v_sub_f32_e32 v11, v69, v65
	v_mul_f32_e32 v11, 0x3fb8aa3b, v11
	v_exp_f32_e32 v70, v11
	v_sub_f32_e32 v11, v72, v65
	v_mul_f32_e32 v11, 0x3fb8aa3b, v11
	v_mul_f32_e32 v10, 0x3fb8aa3b, v10
	v_exp_f32_e32 v27, v11
	v_sub_f32_e32 v11, v73, v65
	v_exp_f32_e32 v80, v10
	v_mul_f32_e32 v11, 0x3fb8aa3b, v11
	v_exp_f32_e32 v42, v11
	v_sub_f32_e32 v11, v74, v65
	v_mul_f32_e32 v11, 0x3fb8aa3b, v11
	v_exp_f32_e32 v36, v11
	v_sub_f32_e32 v11, v75, v65
	v_add_f32_e32 v10, 0, v80
	v_mul_f32_e32 v11, 0x3fb8aa3b, v11
	v_add_f32_e32 v10, v81, v10
	v_exp_f32_e32 v52, v11
	v_sub_f32_e32 v11, v76, v65
	v_add_f32_e32 v10, v82, v10
	v_mul_f32_e32 v11, 0x3fb8aa3b, v11
	v_add_f32_e32 v10, v96, v10
	v_exp_f32_e32 v47, v11
	v_sub_f32_e32 v11, v77, v65
	v_add_f32_e32 v10, v97, v10
	v_mul_f32_e32 v11, 0x3fb8aa3b, v11
	v_add_f32_e32 v10, v101, v10
	v_exp_f32_e32 v62, v11
	v_sub_f32_e32 v11, v78, v65
	v_add_f32_e32 v10, v106, v10
	v_mul_f32_e32 v11, 0x3fb8aa3b, v11
	v_add_f32_e32 v10, v107, v10
	v_exp_f32_e32 v57, v11
	v_sub_f32_e32 v11, v79, v65
	v_add_f32_e32 v10, v33, v10
	v_mul_f32_e32 v11, 0x3fb8aa3b, v11
	v_add_f32_e32 v10, v45, v10
	v_exp_f32_e32 v69, v11
	v_sub_f32_e32 v11, v84, v65
	v_add_f32_e32 v10, v38, v10
	v_mul_f32_e32 v11, 0x3fb8aa3b, v11
	v_add_f32_e32 v10, v54, v10
	v_exp_f32_e32 v13, v11
	v_sub_f32_e32 v11, v85, v65
	v_add_f32_e32 v10, v49, v10
	v_mul_f32_e32 v11, 0x3fb8aa3b, v11
	v_add_f32_e32 v10, v64, v10
	v_exp_f32_e32 v41, v11
	v_sub_f32_e32 v11, v86, v65
	v_add_f32_e32 v10, v61, v10
	v_mul_f32_e32 v11, 0x3fb8aa3b, v11
	v_add_f32_e32 v10, v71, v10
	v_exp_f32_e32 v35, v11
	v_sub_f32_e32 v11, v87, v65
	v_add_f32_e32 v10, v32, v10
	v_mul_f32_e32 v11, 0x3fb8aa3b, v11
	v_add_f32_e32 v10, v43, v10
	v_exp_f32_e32 v51, v11
	v_sub_f32_e32 v11, v88, v65
	v_add_f32_e32 v10, v37, v10
	v_mul_f32_e32 v11, 0x3fb8aa3b, v11
	v_add_f32_e32 v10, v53, v10
	v_exp_f32_e32 v46, v11
	v_sub_f32_e32 v11, v89, v65
	v_add_f32_e32 v10, v48, v10
	v_mul_f32_e32 v11, 0x3fb8aa3b, v11
	v_add_f32_e32 v10, v63, v10
	v_exp_f32_e32 v60, v11
	v_sub_f32_e32 v11, v90, v65
	v_add_f32_e32 v10, v59, v10
	v_mul_f32_e32 v11, 0x3fb8aa3b, v11
	v_add_f32_e32 v10, v70, v10
	v_exp_f32_e32 v56, v11
	v_sub_f32_e32 v11, v91, v65
	v_add_f32_e32 v10, v27, v10
	v_mul_f32_e32 v11, 0x3fb8aa3b, v11
	v_add_f32_e32 v10, v42, v10
	v_exp_f32_e32 v68, v11
	v_sub_f32_e32 v11, v92, v65
	v_add_f32_e32 v10, v36, v10
	v_mul_f32_e32 v11, 0x3fb8aa3b, v11
	v_add_f32_e32 v10, v52, v10
	v_exp_f32_e32 v12, v11
	v_sub_f32_e32 v11, v93, v65
	v_add_f32_e32 v10, v47, v10
	v_mul_f32_e32 v11, 0x3fb8aa3b, v11
	v_add_f32_e32 v10, v62, v10
	v_exp_f32_e32 v40, v11
	v_sub_f32_e32 v11, v94, v65
	v_add_f32_e32 v10, v57, v10
	v_mul_f32_e32 v11, 0x3fb8aa3b, v11
	v_add_f32_e32 v10, v69, v10
	v_exp_f32_e32 v34, v11
	v_sub_f32_e32 v11, v95, v65
	v_add_f32_e32 v10, v13, v10
	v_mul_f32_e32 v11, 0x3fb8aa3b, v11
	v_add_f32_e32 v10, v41, v10
	v_exp_f32_e32 v50, v11
	v_sub_f32_e32 v11, v102, v65
	v_add_f32_e32 v10, v35, v10
	v_mul_f32_e32 v11, 0x3fb8aa3b, v11
	v_add_f32_e32 v10, v51, v10
	v_exp_f32_e32 v44, v11
	v_sub_f32_e32 v11, v103, v65
	v_add_f32_e32 v10, v46, v10
	v_mul_f32_e32 v11, 0x3fb8aa3b, v11
	v_add_f32_e32 v10, v60, v10
	v_exp_f32_e32 v58, v11
	v_sub_f32_e32 v11, v104, v65
	v_add_f32_e32 v10, v56, v10
	v_mul_f32_e32 v11, 0x3fb8aa3b, v11
	v_add_f32_e32 v10, v68, v10
	v_exp_f32_e32 v55, v11
	v_sub_f32_e32 v11, v105, v65
	v_add_f32_e32 v10, v12, v10
	v_mul_f32_e32 v11, 0x3fb8aa3b, v11
	v_add_f32_e32 v10, v40, v10
	v_exp_f32_e32 v67, v11
	v_sub_f32_e32 v11, v22, v65
	v_sub_f32_e32 v22, v23, v65
	v_add_f32_e32 v10, v34, v10
	v_mul_f32_e32 v22, 0x3fb8aa3b, v22
	v_add_f32_e32 v10, v50, v10
	v_mul_f32_e32 v11, 0x3fb8aa3b, v11
	v_exp_f32_e32 v39, v22
	v_sub_f32_e32 v22, v24, v65
	v_add_f32_e32 v10, v44, v10
	v_exp_f32_e32 v11, v11
	v_mul_f32_e32 v22, 0x3fb8aa3b, v22
	v_add_f32_e32 v10, v58, v10
	v_exp_f32_e32 v23, v22
	v_sub_f32_e32 v22, v25, v65
	v_sub_f32_e32 v19, v19, v65
	v_add_f32_e32 v10, v55, v10
	v_mul_f32_e32 v22, 0x3fb8aa3b, v22
	v_sub_f32_e32 v18, v18, v65
	v_mul_f32_e32 v19, 0x3fb8aa3b, v19
	v_add_f32_e32 v10, v67, v10
	v_exp_f32_e32 v24, v22
	v_mul_f32_e32 v18, 0x3fb8aa3b, v18
	v_exp_f32_e32 v25, v19
	v_sub_f32_e32 v19, v20, v65
	v_add_f32_e32 v10, v11, v10
	v_exp_f32_e32 v18, v18
	v_mul_f32_e32 v19, 0x3fb8aa3b, v19
	v_add_f32_e32 v10, v39, v10
	v_exp_f32_e32 v20, v19
	v_sub_f32_e32 v19, v21, v65
	v_add_f32_e32 v10, v23, v10
	v_mul_f32_e32 v19, 0x3fb8aa3b, v19
	v_add_f32_e32 v10, v24, v10
	v_exp_f32_e32 v66, v19
	v_add_f32_e32 v10, v18, v10
	v_add_f32_e32 v10, v25, v10
	v_add_f32_e32 v10, v20, v10
	v_add_f32_e32 v19, v66, v10
	v_sub_f32_e32 v10, v14, v65
	v_mul_f32_e32 v10, 0x3fb8aa3b, v10
	v_sub_f32_e32 v15, v15, v65
	v_exp_f32_e32 v10, v10
	v_mul_f32_e32 v15, 0x3fb8aa3b, v15
	v_exp_f32_e32 v15, v15
	v_sub_f32_e32 v17, v17, v65
	v_add_f32_e32 v14, v10, v19
	v_mul_f32_e32 v17, 0x3fb8aa3b, v17
	v_add_f32_e32 v19, v15, v14
	v_sub_f32_e32 v14, v16, v65
	v_mul_f32_e32 v14, 0x3fb8aa3b, v14
	v_exp_f32_e32 v14, v14
	v_exp_f32_e32 v17, v17
	v_sub_f32_e32 v6, v6, v65
	v_mul_f32_e32 v6, 0x3fb8aa3b, v6
	v_add_f32_e32 v16, v14, v19
	v_add_f32_e32 v19, v17, v16
	v_exp_f32_e32 v16, v6
	v_sub_f32_e32 v7, v7, v65
	v_mul_f32_e32 v7, 0x3fb8aa3b, v7
	v_exp_f32_e32 v21, v7
	v_sub_f32_e32 v7, v8, v65
	v_mul_f32_e32 v7, 0x3fb8aa3b, v7
	v_add_f32_e32 v6, v16, v19
	v_exp_f32_e32 v19, v7
	v_sub_f32_e32 v7, v9, v65
	v_mul_f32_e32 v7, 0x3fb8aa3b, v7
	v_exp_f32_e32 v65, v7
	v_add_f32_e32 v6, v21, v6
	v_add_f32_e32 v6, v19, v6
	v_bfe_u32 v8, v96, 16, 1
	v_add_f32_e32 v6, v65, v6
	ds_bpermute_b32 v7, v98, v6
	v_bfe_u32 v9, v81, 16, 1
	v_add3_u32 v72, v81, v9, s91
	v_add3_u32 v73, v96, v8, s91
	v_bfe_u32 v8, v80, 16, 1
	s_waitcnt lgkmcnt(0)
	v_add_f32_e32 v6, v6, v7
	ds_bpermute_b32 v7, v99, v6
	v_bfe_u32 v9, v82, 16, 1
	v_bfe_u32 v74, v97, 16, 1
	v_bfe_u32 v75, v106, 16, 1
	v_add3_u32 v75, v106, v75, s91
	s_waitcnt lgkmcnt(0)
	v_add_f32_e32 v22, v6, v7
	v_bfe_u32 v6, v107, 16, 1
	v_bfe_u32 v7, v101, 16, 1
	v_add3_u32 v74, v97, v74, s91
	v_add3_u32 v9, v82, v9, s91
	v_add3_u32 v8, v80, v8, s91
	v_add3_u32 v7, v101, v7, s91
	v_add3_u32 v6, v107, v6, s91
	v_lshrrev_b32_e32 v76, 16, v8
	v_lshrrev_b32_e32 v77, 16, v9
	v_lshrrev_b32_e32 v8, 16, v74
	v_lshrrev_b32_e32 v9, 16, v75
	v_add_u32_e32 v82, 0x9000, v31
	v_add_u32_e32 v96, 0xb000, v31
	v_add_u32_e32 v97, 0xd000, v31
	v_add_u32_e32 v101, 0xf000, v31
	v_and_or_b32 v9, v6, s33, v9
	v_and_or_b32 v8, v7, s33, v8
	v_and_or_b32 v7, v73, s33, v77
	v_and_or_b32 v6, v72, s33, v76
	ds_read2_b64 v[72:75], v82 offset1:4
	ds_read2_b64 v[76:79], v96 offset0:32 offset1:36
	ds_read2_b64 v[84:87], v97 offset0:64 offset1:68
	ds_read2_b64 v[88:91], v101 offset0:96 offset1:100
	ds_read2_b64 v[92:95], v82 offset0:8 offset1:12
	s_waitcnt lgkmcnt(4)
	v_mfma_f32_16x16x32_bf16 v[72:75], v[72:75], v[6:9], 0
	v_bfe_u32 v80, v71, 16, 1
	v_bfe_u32 v81, v64, 16, 1
	v_add3_u32 v64, v64, v81, s91
	s_waitcnt lgkmcnt(3)
	v_mfma_f32_16x16x32_bf16 v[76:79], v[76:79], v[6:9], 0
	v_add3_u32 v71, v71, v80, s91
	v_bfe_u32 v80, v33, 16, 1
	v_bfe_u32 v81, v38, 16, 1
	s_waitcnt lgkmcnt(2)
	v_mfma_f32_16x16x32_bf16 v[84:87], v[84:87], v[6:9], 0
	v_add3_u32 v38, v38, v81, s91
	v_add3_u32 v33, v33, v80, s91
	v_lshrrev_b32_e32 v33, 16, v33
	s_waitcnt lgkmcnt(1)
	v_mfma_f32_16x16x32_bf16 v[6:9], v[88:91], v[6:9], 0
	v_bfe_u32 v88, v54, 16, 1
	v_bfe_u32 v89, v45, 16, 1
	v_add3_u32 v45, v45, v89, s91
	v_add3_u32 v54, v54, v88, s91
	v_bfe_u32 v88, v49, 16, 1
	v_bfe_u32 v89, v61, 16, 1
	v_add3_u32 v61, v61, v89, s91
	v_add3_u32 v49, v49, v88, s91
	v_lshrrev_b32_e32 v38, 16, v38
	v_lshrrev_b32_e32 v49, 16, v49
	v_lshrrev_b32_e32 v61, 16, v61
	v_and_or_b32 v91, v71, s33, v61
	v_and_or_b32 v90, v64, s33, v49
	v_and_or_b32 v89, v54, s33, v38
	v_and_or_b32 v88, v45, s33, v33
	v_bfe_u32 v45, v53, 16, 1
	v_bfe_u32 v49, v43, 16, 1
	s_waitcnt lgkmcnt(0)
	v_mfma_f32_16x16x32_bf16 v[72:75], v[92:95], v[88:91], v[72:75]
	ds_read2_b64 v[92:95], v96 offset0:40 offset1:44
	v_add3_u32 v43, v43, v49, s91
	v_add3_u32 v45, v53, v45, s91
	s_waitcnt lgkmcnt(0)
	v_mfma_f32_16x16x32_bf16 v[76:79], v[92:95], v[88:91], v[76:79]
	ds_read2_b64 v[92:95], v97 offset0:72 offset1:76
	v_bfe_u32 v49, v32, 16, 1
	v_bfe_u32 v53, v37, 16, 1
	s_waitcnt lgkmcnt(0)
	v_mfma_f32_16x16x32_bf16 v[84:87], v[92:95], v[88:91], v[84:87]
	ds_read2_b64 v[92:95], v101 offset0:104 offset1:108
	v_bfe_u32 v54, v48, 16, 1
	s_waitcnt lgkmcnt(0)
	v_mfma_f32_16x16x32_bf16 v[6:9], v[92:95], v[88:91], v[6:9]
	ds_read2_b64 v[92:95], v82 offset0:16 offset1:20
	v_bfe_u32 v61, v59, 16, 1
	v_bfe_u32 v33, v70, 16, 1
	v_bfe_u32 v38, v63, 16, 1
	v_add3_u32 v59, v59, v61, s91
	v_add3_u32 v48, v48, v54, s91
	v_add3_u32 v37, v37, v53, s91
	v_add3_u32 v32, v32, v49, s91
	v_add3_u32 v38, v63, v38, s91
	v_add3_u32 v33, v70, v33, s91
	v_lshrrev_b32_e32 v32, 16, v32
	v_lshrrev_b32_e32 v37, 16, v37
	v_lshrrev_b32_e32 v48, 16, v48
	v_lshrrev_b32_e32 v49, 16, v59
	v_and_or_b32 v91, v33, s33, v49
	v_and_or_b32 v90, v38, s33, v48
	v_and_or_b32 v89, v45, s33, v37
	v_and_or_b32 v88, v43, s33, v32
	v_bfe_u32 v38, v42, 16, 1
	v_add3_u32 v38, v42, v38, s91
	s_waitcnt lgkmcnt(0)
	v_mfma_f32_16x16x32_bf16 v[70:73], v[92:95], v[88:91], v[72:75]
	ds_read2_b64 v[92:95], v96 offset0:48 offset1:52
	v_bfe_u32 v42, v27, 16, 1
	v_bfe_u32 v43, v36, 16, 1
	s_waitcnt lgkmcnt(0)
	v_mfma_f32_16x16x32_bf16 v[74:77], v[92:95], v[88:91], v[76:79]
	s_nop 2
	ds_read2_b64 v[78:81], v97 offset0:80 offset1:84
	v_bfe_u32 v45, v47, 16, 1
	v_bfe_u32 v48, v57, 16, 1
	s_waitcnt lgkmcnt(0)
	v_mfma_f32_16x16x32_bf16 v[78:81], v[78:81], v[88:91], v[84:87]
	s_nop 2
	ds_read2_b64 v[84:87], v101 offset0:112 offset1:116
	v_bfe_u32 v32, v69, 16, 1
	s_waitcnt lgkmcnt(0)
	v_mfma_f32_16x16x32_bf16 v[6:9], v[84:87], v[88:91], v[6:9]
	ds_read2_b64 v[88:91], v82 offset0:24 offset1:28
	v_bfe_u32 v33, v62, 16, 1
	v_bfe_u32 v37, v52, 16, 1
	v_add3_u32 v48, v57, v48, s91
	v_add3_u32 v45, v47, v45, s91
	v_add3_u32 v36, v36, v43, s91
	v_add3_u32 v27, v27, v42, s91
	v_add3_u32 v37, v52, v37, s91
	v_add3_u32 v33, v62, v33, s91
	v_add3_u32 v32, v69, v32, s91
	v_lshrrev_b32_e32 v27, 16, v27
	v_lshrrev_b32_e32 v36, 16, v36
	v_lshrrev_b32_e32 v42, 16, v45
	v_lshrrev_b32_e32 v43, 16, v48
	v_and_or_b32 v87, v32, s33, v43
	v_and_or_b32 v86, v33, s33, v42
	v_and_or_b32 v85, v37, s33, v36
	v_and_or_b32 v84, v38, s33, v27
	v_bfe_u32 v32, v60, 16, 1
	v_add3_u32 v32, v60, v32, s91
	s_waitcnt lgkmcnt(0)
	v_mfma_f32_16x16x32_bf16 v[70:73], v[88:91], v[84:87], v[70:73]
	ds_read2_b64 v[88:91], v96 offset0:56 offset1:60
	v_bfe_u32 v36, v41, 16, 1
	v_add3_u32 v36, v41, v36, s91
	s_waitcnt lgkmcnt(0)
	v_mfma_f32_16x16x32_bf16 v[74:77], v[88:91], v[84:87], v[74:77]
	ds_read2_b64 v[88:91], v97 offset0:88 offset1:92
	v_bfe_u32 v37, v13, 16, 1
	v_bfe_u32 v38, v35, 16, 1
	s_waitcnt lgkmcnt(0)
	v_mfma_f32_16x16x32_bf16 v[78:81], v[88:91], v[84:87], v[78:81]
	ds_read2_b64 v[88:91], v101 offset0:120 offset1:124
	ds_read2_b64 v[60:63], v82 offset0:32 offset1:36
	v_bfe_u32 v41, v46, 16, 1
	v_bfe_u32 v42, v56, 16, 1
	v_bfe_u32 v27, v68, 16, 1
	v_bfe_u32 v33, v51, 16, 1
	v_add3_u32 v42, v56, v42, s91
	v_add3_u32 v41, v46, v41, s91
	v_add3_u32 v35, v35, v38, s91
	v_add3_u32 v13, v13, v37, s91
	v_add3_u32 v33, v51, v33, s91
	v_add3_u32 v27, v68, v27, s91
	v_lshrrev_b32_e32 v13, 16, v13
	v_lshrrev_b32_e32 v35, 16, v35
	v_lshrrev_b32_e32 v37, 16, v41
	v_lshrrev_b32_e32 v38, 16, v42
	v_and_or_b32 v49, v27, s33, v38
	v_and_or_b32 v48, v32, s33, v37
	v_and_or_b32 v47, v33, s33, v35
	v_and_or_b32 v46, v36, s33, v13
	s_waitcnt lgkmcnt(1)
	v_mfma_f32_16x16x32_bf16 v[6:9], v[88:91], v[84:87], v[6:9]
	v_bfe_u32 v32, v50, 16, 1
	v_bfe_u32 v33, v40, 16, 1
	v_bfe_u32 v37, v44, 16, 1
	s_waitcnt lgkmcnt(0)
	v_mfma_f32_16x16x32_bf16 v[60:63], v[60:63], v[46:49], v[70:73]
	v_bfe_u32 v38, v55, 16, 1
	v_add3_u32 v36, v40, v33, s91
	v_add3_u32 v32, v50, v32, s91
	ds_read2_b64 v[68:71], v96 offset0:64 offset1:68
	s_waitcnt lgkmcnt(0)
	v_mfma_f32_16x16x32_bf16 v[68:71], v[68:71], v[46:49], v[74:77]
	s_nop 2
	ds_read2_b64 v[72:75], v97 offset0:96 offset1:100
	v_add3_u32 v38, v55, v38, s91
	v_add3_u32 v37, v44, v37, s91
	s_waitcnt lgkmcnt(0)
	v_mfma_f32_16x16x32_bf16 v[72:75], v[72:75], v[46:49], v[78:81]
	s_nop 2
	ds_read2_b64 v[76:79], v101 offset0:128 offset1:132
	ds_read2_b64 v[40:43], v82 offset0:40 offset1:44
	s_waitcnt lgkmcnt(1)
	v_mfma_f32_16x16x32_bf16 v[6:9], v[76:79], v[46:49], v[6:9]
	ds_read2_b64 v[44:47], v96 offset0:72 offset1:76
	ds_read2_b64 v[48:51], v97 offset0:104 offset1:108
	ds_read2_b64 v[52:55], v101 offset0:136 offset1:140
	v_bfe_u32 v33, v12, 16, 1
	v_bfe_u32 v35, v34, 16, 1
	v_bfe_u32 v13, v67, 16, 1
	v_bfe_u32 v27, v58, 16, 1
	v_add3_u32 v34, v34, v35, s91
	v_add3_u32 v12, v12, v33, s91
	v_add3_u32 v27, v58, v27, s91
	v_add3_u32 v13, v67, v13, s91
	v_lshrrev_b32_e32 v12, 16, v12
	v_lshrrev_b32_e32 v33, 16, v34
	v_lshrrev_b32_e32 v34, 16, v37
	v_lshrrev_b32_e32 v35, 16, v38
	v_and_or_b32 v35, v13, s33, v35
	v_and_or_b32 v34, v27, s33, v34
	v_and_or_b32 v33, v32, s33, v33
	v_and_or_b32 v32, v36, s33, v12
	v_bfe_u32 v13, v25, 16, 1
	v_bfe_u32 v27, v24, 16, 1
	s_waitcnt lgkmcnt(3)
	v_mfma_f32_16x16x32_bf16 v[40:43], v[40:43], v[32:35], v[60:63]
	v_add3_u32 v24, v24, v27, s91
	v_add3_u32 v13, v25, v13, s91
	v_bfe_u32 v25, v11, 16, 1
	s_waitcnt lgkmcnt(2)
	v_mfma_f32_16x16x32_bf16 v[44:47], v[44:47], v[32:35], v[68:71]
	v_bfe_u32 v27, v23, 16, 1
	v_bfe_u32 v12, v66, 16, 1
	v_add3_u32 v23, v23, v27, s91
	s_waitcnt lgkmcnt(1)
	v_mfma_f32_16x16x32_bf16 v[48:51], v[48:51], v[32:35], v[72:75]
	v_add3_u32 v11, v11, v25, s91
	v_add3_u32 v12, v66, v12, s91
	v_lshrrev_b32_e32 v11, 16, v11
	s_waitcnt lgkmcnt(0)
	v_mfma_f32_16x16x32_bf16 v[6:9], v[52:55], v[32:35], v[6:9]
	v_bfe_u32 v32, v39, 16, 1
	v_add3_u32 v32, v39, v32, s91
	ds_read2_b64 v[36:39], v82 offset0:48 offset1:52
	v_bfe_u32 v33, v18, 16, 1
	v_bfe_u32 v34, v20, 16, 1
	v_add3_u32 v20, v20, v34, s91
	v_add3_u32 v18, v18, v33, s91
	v_lshrrev_b32_e32 v23, 16, v23
	v_lshrrev_b32_e32 v18, 16, v18
	v_lshrrev_b32_e32 v20, 16, v20
	v_and_or_b32 v35, v12, s33, v20
	v_and_or_b32 v34, v13, s33, v18
	v_and_or_b32 v33, v24, s33, v23
	v_and_or_b32 v32, v32, s33, v11
	v_bfe_u32 v12, v21, 16, 1
	v_bfe_u32 v13, v17, 16, 1
	s_waitcnt lgkmcnt(0)
	v_mfma_f32_16x16x32_bf16 v[36:39], v[36:39], v[32:35], v[40:43]
	v_bfe_u32 v18, v15, 16, 1
	v_add3_u32 v15, v15, v18, s91
	v_add3_u32 v13, v17, v13, s91
	ds_read2_b64 v[40:43], v96 offset0:80 offset1:84
	s_waitcnt lgkmcnt(0)
	v_mfma_f32_16x16x32_bf16 v[40:43], v[40:43], v[32:35], v[44:47]
	s_nop 2
	ds_read2_b64 v[44:47], v97 offset0:112 offset1:116
	v_add3_u32 v12, v21, v12, s91
	v_bfe_u32 v17, v10, 16, 1
	s_waitcnt lgkmcnt(0)
	v_mfma_f32_16x16x32_bf16 v[44:47], v[44:47], v[32:35], v[48:51]
	s_nop 2
	ds_read2_b64 v[48:51], v101 offset0:144 offset1:148
	v_bfe_u32 v18, v14, 16, 1
	v_bfe_u32 v20, v16, 16, 1
	v_bfe_u32 v21, v19, 16, 1
	v_bfe_u32 v11, v65, 16, 1
	v_add3_u32 v19, v19, v21, s91
	v_add3_u32 v16, v16, v20, s91
	v_add3_u32 v14, v14, v18, s91
	v_add3_u32 v10, v10, v17, s91
	v_add3_u32 v11, v65, v11, s91
	v_lshrrev_b32_e32 v10, 16, v10
	v_lshrrev_b32_e32 v14, 16, v14
	v_lshrrev_b32_e32 v16, 16, v16
	v_lshrrev_b32_e32 v17, 16, v19
	s_waitcnt lgkmcnt(0)
	v_mfma_f32_16x16x32_bf16 v[6:9], v[48:51], v[32:35], v[6:9]
	v_and_or_b32 v35, v11, s33, v17
	v_and_or_b32 v34, v12, s33, v16
	v_and_or_b32 v33, v13, s33, v14
	v_and_or_b32 v32, v15, s33, v10
	ds_read2_b64 v[10:13], v82 offset0:56 offset1:60
	v_div_scale_f32 v23, s[4:5], v22, v22, 1.0
	s_waitcnt lgkmcnt(0)
	v_mfma_f32_16x16x32_bf16 v[18:21], v[10:13], v[32:35], v[36:39]
	ds_read2_b64 v[10:13], v96 offset0:88 offset1:92
	s_nop 1
	ds_read2_b64 v[36:39], v101 offset0:152 offset1:156
	v_rcp_f32_e32 v27, v23
	s_waitcnt lgkmcnt(1)
	v_mfma_f32_16x16x32_bf16 v[14:17], v[10:13], v[32:35], v[40:43]
	ds_read2_b64 v[10:13], v97 offset0:120 offset1:124
	v_lshlrev_b64 v[24:25], 11, v[28:29]
	v_fma_f32 v28, -v23, v27, 1.0
	v_fmac_f32_e32 v27, v28, v27
	v_div_scale_f32 v28, vcc, 1.0, v22, 1.0
	v_mul_f32_e32 v29, v28, v27
	s_waitcnt lgkmcnt(0)
	v_mfma_f32_16x16x32_bf16 v[10:13], v[10:13], v[32:35], v[44:47]
	v_lshl_add_u64 v[24:25], s[0:1], 0, v[24:25]
	v_lshl_add_u64 v[24:25], v[24:25], 0, s[94:95]
	v_mfma_f32_16x16x32_bf16 v[6:9], v[36:39], v[32:35], v[6:9]
	v_fma_f32 v32, -v23, v29, v28
	v_fmac_f32_e32 v29, v32, v27
	v_fma_f32 v23, -v23, v29, v28
	v_div_fmas_f32 v23, v23, v27, v29
	v_div_fixup_f32 v22, v23, v22, 1.0
	v_mov_b32_e32 v33, v20
	v_mov_b32_e32 v20, v19
	v_mov_b32_e32 v32, v18
	v_pk_mul_f32 v[18:19], v[22:23], v[20:21] op_sel_hi:[0,1]
	v_mov_b32_e32 v27, v1
	v_pk_mul_f32 v[32:33], v[22:23], v[32:33] op_sel_hi:[0,1]
	v_and_b32_sdwa v23, v19, v218 dst_sel:DWORD dst_unused:UNUSED_PAD src0_sel:WORD_1 src1_sel:DWORD
	v_lshl_add_u64 v[24:25], v[24:25], 0, v[26:27]
	v_and_b32_sdwa v20, v33, v218 dst_sel:DWORD dst_unused:UNUSED_PAD src0_sel:WORD_1 src1_sel:DWORD
	v_and_b32_sdwa v27, v18, v218 dst_sel:DWORD dst_unused:UNUSED_PAD src0_sel:WORD_1 src1_sel:DWORD
	v_add3_u32 v19, v19, v23, s91
	v_and_b32_sdwa v21, v32, v218 dst_sel:DWORD dst_unused:UNUSED_PAD src0_sel:WORD_1 src1_sel:DWORD
	v_add3_u32 v20, v33, v20, s91
	v_add3_u32 v18, v18, v27, s91
	v_and_b32_e32 v19, 0xffff0000, v19
	v_add3_u32 v21, v32, v21, s91
	v_and_b32_e32 v18, 0xffff0000, v18
	v_or_b32_sdwa v19, v19, v20 dst_sel:DWORD dst_unused:UNUSED_PAD src0_sel:DWORD src1_sel:WORD_1
	v_add_co_u32_e32 v20, vcc, s8, v24
	v_or_b32_sdwa v18, v18, v21 dst_sel:DWORD dst_unused:UNUSED_PAD src0_sel:DWORD src1_sel:WORD_1
	s_nop 0
	v_addc_co_u32_e32 v21, vcc, 0, v25, vcc
	flat_store_dwordx2 v[20:21], v[18:19] offset:1536
	v_mov_b32_e32 v18, v14
	v_mov_b32_e32 v19, v16
	v_pk_mul_f32 v[18:19], v[22:23], v[18:19] op_sel_hi:[0,1]
	v_mov_b32_e32 v16, v15
	v_pk_mul_f32 v[14:15], v[22:23], v[16:17] op_sel_hi:[0,1]
	v_and_b32_sdwa v16, v19, v218 dst_sel:DWORD dst_unused:UNUSED_PAD src0_sel:WORD_1 src1_sel:DWORD
	v_and_b32_sdwa v17, v18, v218 dst_sel:DWORD dst_unused:UNUSED_PAD src0_sel:WORD_1 src1_sel:DWORD
	v_add3_u32 v17, v18, v17, s91
	v_add3_u32 v16, v19, v16, s91
	v_and_b32_sdwa v18, v15, v218 dst_sel:DWORD dst_unused:UNUSED_PAD src0_sel:WORD_1 src1_sel:DWORD
	v_and_b32_sdwa v19, v14, v218 dst_sel:DWORD dst_unused:UNUSED_PAD src0_sel:WORD_1 src1_sel:DWORD
	v_add3_u32 v15, v15, v18, s91
	v_add3_u32 v14, v14, v19, s91
	v_and_b32_e32 v15, 0xffff0000, v15
	v_and_b32_e32 v14, 0xffff0000, v14
	v_lshl_add_u64 v[28:29], v[24:25], 0, s[16:17]
	v_or_b32_sdwa v15, v15, v16 dst_sel:DWORD dst_unused:UNUSED_PAD src0_sel:DWORD src1_sel:WORD_1
	v_or_b32_sdwa v14, v14, v17 dst_sel:DWORD dst_unused:UNUSED_PAD src0_sel:DWORD src1_sel:WORD_1
	flat_store_dwordx2 v[28:29], v[14:15] offset:32
	v_mov_b32_e32 v14, v10
	v_mov_b32_e32 v15, v12
	v_pk_mul_f32 v[14:15], v[22:23], v[14:15] op_sel_hi:[0,1]
	v_mov_b32_e32 v12, v11
	v_pk_mul_f32 v[10:11], v[22:23], v[12:13] op_sel_hi:[0,1]
	v_and_b32_sdwa v12, v15, v218 dst_sel:DWORD dst_unused:UNUSED_PAD src0_sel:WORD_1 src1_sel:DWORD
	v_and_b32_sdwa v13, v14, v218 dst_sel:DWORD dst_unused:UNUSED_PAD src0_sel:WORD_1 src1_sel:DWORD
	v_add3_u32 v13, v14, v13, s91
	v_add3_u32 v12, v15, v12, s91
	v_and_b32_sdwa v14, v11, v218 dst_sel:DWORD dst_unused:UNUSED_PAD src0_sel:WORD_1 src1_sel:DWORD
	v_and_b32_sdwa v15, v10, v218 dst_sel:DWORD dst_unused:UNUSED_PAD src0_sel:WORD_1 src1_sel:DWORD
	v_add3_u32 v11, v11, v14, s91
	v_add3_u32 v10, v10, v15, s91
	v_and_b32_e32 v11, 0xffff0000, v11
	v_and_b32_e32 v10, 0xffff0000, v10
	v_or_b32_sdwa v11, v11, v12 dst_sel:DWORD dst_unused:UNUSED_PAD src0_sel:DWORD src1_sel:WORD_1
	v_or_b32_sdwa v10, v10, v13 dst_sel:DWORD dst_unused:UNUSED_PAD src0_sel:DWORD src1_sel:WORD_1
	flat_store_dwordx2 v[28:29], v[10:11] offset:64
	v_mov_b32_e32 v10, v6
	v_mov_b32_e32 v11, v8
	v_pk_mul_f32 v[10:11], v[22:23], v[10:11] op_sel_hi:[0,1]
	v_mov_b32_e32 v8, v7
	v_pk_mul_f32 v[6:7], v[22:23], v[8:9] op_sel_hi:[0,1]
	v_and_b32_sdwa v8, v11, v218 dst_sel:DWORD dst_unused:UNUSED_PAD src0_sel:WORD_1 src1_sel:DWORD
	v_and_b32_sdwa v9, v10, v218 dst_sel:DWORD dst_unused:UNUSED_PAD src0_sel:WORD_1 src1_sel:DWORD
	v_add3_u32 v9, v10, v9, s91
	v_add3_u32 v8, v11, v8, s91
	v_and_b32_sdwa v10, v7, v218 dst_sel:DWORD dst_unused:UNUSED_PAD src0_sel:WORD_1 src1_sel:DWORD
	v_and_b32_sdwa v11, v6, v218 dst_sel:DWORD dst_unused:UNUSED_PAD src0_sel:WORD_1 src1_sel:DWORD
	v_add3_u32 v7, v7, v10, s91
	v_add3_u32 v6, v6, v11, s91
	v_and_b32_e32 v7, 0xffff0000, v7
	v_and_b32_e32 v6, 0xffff0000, v6
	v_or_b32_sdwa v7, v7, v8 dst_sel:DWORD dst_unused:UNUSED_PAD src0_sel:DWORD src1_sel:WORD_1
	v_or_b32_sdwa v6, v6, v9 dst_sel:DWORD dst_unused:UNUSED_PAD src0_sel:DWORD src1_sel:WORD_1
	s_movk_i32 s4, 0x80
	s_and_b64 vcc, exec, s[2:3]
	s_mov_b64 s[2:3], 0
	flat_store_dwordx2 v[28:29], v[6:7] offset:96
	s_cbranch_vccnz .LBB0_536
	s_waitcnt lgkmcnt(0)
	s_barrier
	s_branch .LBB0_533

.LBB0_558:
	s_andn2_saveexec_b64 s[14:15], s[6:7]
	s_cbranch_execz .LBB0_555
	s_waitcnt lgkmcnt(0)
	v_add_f32_e32 v14, v23, v25
	v_fmamk_f32 v14, v14, 0x3c800000, v219
	v_cmp_gt_f32_e32 vcc, s85, v14
	v_mul_f32_e32 v15, 0x4f800000, v14
	s_nop 0
	v_cndmask_b32_e32 v14, v14, v15, vcc
	v_sqrt_f32_e32 v15, v14
	s_nop 0
	v_add_u32_e32 v16, -1, v15
	v_fma_f32 v17, -v16, v15, v14
	v_cmp_ge_f32_e64 s[6:7], 0, v17
	v_add_u32_e32 v17, 1, v15
	s_nop 0
	v_cndmask_b32_e64 v16, v15, v16, s[6:7]
	v_fma_f32 v15, -v17, v15, v14
	v_cmp_lt_f32_e64 s[6:7], 0, v15
	s_nop 1
	v_cndmask_b32_e64 v15, v16, v17, s[6:7]
	v_mul_f32_e32 v16, 0x37800000, v15
	v_cndmask_b32_e32 v15, v15, v16, vcc
	v_cmp_class_f32_e32 vcc, v14, v221
	s_nop 1
	v_cndmask_b32_e32 v14, v15, v14, vcc
	v_div_scale_f32 v15, s[6:7], v14, v14, 1.0
	v_rcp_f32_e32 v16, v15
	v_readlane_b32 s6, v254, 18
	v_fma_f32 v17, -v15, v16, 1.0
	v_fmac_f32_e32 v16, v17, v16
	v_div_scale_f32 v17, vcc, 1.0, v14, 1.0
	v_mul_f32_e32 v23, v17, v16
	v_fma_f32 v25, -v15, v23, v17
	v_fmac_f32_e32 v23, v25, v16
	v_fma_f32 v15, -v15, v23, v17
	v_div_fmas_f32 v15, v15, v16, v23
	v_div_fixup_f32 v30, v15, v14, 1.0
	v_mov_b32_e32 v14, s6
	ds_read_b64 v[14:15], v14
	s_lshl_b32 s6, s9, 6
	s_ashr_i32 s7, s6, 31
	s_lshl_b64 s[6:7], s[6:7], 2
	v_pk_mul_f32 v[6:7], v[30:31], v[6:7] op_sel_hi:[0,1]
	s_waitcnt lgkmcnt(0)
	v_readfirstlane_b32 s16, v14
	v_readfirstlane_b32 s17, v15
	s_add_u32 s6, s16, s6
	s_addc_u32 s7, s17, s7
	s_nop 1
	v_lshl_add_u64 v[102:103], s[6:7], 0, v[0:1]
	global_load_dwordx4 v[104:107], v[102:103], off offset:16
	v_lshl_add_u64 v[32:33], s[6:7], 0, v[0:1]
	flat_load_dwordx4 v[14:17], v[32:33]
	v_pk_mul_f32 v[8:9], v[30:31], v[8:9] op_sel_hi:[0,1]
	v_pk_mul_f32 v[10:11], v[30:31], v[10:11] op_sel_hi:[0,1]
	v_readlane_b32 s6, v254, 8
	v_mov_b32_e32 v25, v1
	v_pk_mul_f32 v[12:13], v[30:31], v[12:13] op_sel_hi:[0,1]
	s_waitcnt vmcnt(0) lgkmcnt(0)
	v_pk_mul_f32 v[6:7], v[6:7], v[14:15]
	v_pk_mul_f32 v[8:9], v[8:9], v[16:17]
	s_waitcnt vmcnt(0)
	s_nop 0
	v_mov_b32_e32 v14, v104
	v_mov_b32_e32 v15, v105
	v_mov_b32_e32 v16, v106
	v_mov_b32_e32 v17, v107
	s_nop 1
	s_waitcnt vmcnt(0) lgkmcnt(0)
	v_pk_mul_f32 v[10:11], v[10:11], v[14:15]
	v_mov_b32_e32 v14, s6
	ds_read_b64 v[14:15], v14
	s_lshl_b32 s6, s9, 2
	s_or_b32 s6, s6, s3
	s_ashr_i32 s7, s6, 31
	s_lshl_b64 s[16:17], s[6:7], 18
	s_waitcnt lgkmcnt(0)
	v_readfirstlane_b32 s18, v14
	v_readfirstlane_b32 s19, v15
	s_add_u32 s3, s18, s16
	s_addc_u32 s7, s19, s17
	s_lshl_b32 s9, s1, 10
	s_add_u32 s16, s3, s9
	s_addc_u32 s17, s7, 0
	v_lshl_add_u64 v[14:15], s[16:17], 0, v[24:25]
	v_lshl_add_u64 v[14:15], v[14:15], 0, v[0:1]
	s_mov_b64 s[16:17], 0x4258000
	s_mov_b32 s3, 0x4258000
	v_pk_mul_f32 v[12:13], v[12:13], v[16:17]
	v_lshl_add_u64 v[16:17], v[14:15], 0, s[16:17]
	v_add_co_u32_e32 v14, vcc, s3, v14
	v_bfe_u32 v0, v11, 16, 1
	s_nop 0
	v_addc_co_u32_e32 v15, vcc, 0, v15, vcc
	flat_store_dwordx4 v[14:15], v[6:9]
	flat_store_dwordx4 v[16:17], v[10:13] offset:16
	v_bfe_u32 v14, v7, 16, 1
	v_bfe_u32 v15, v13, 16, 1
	v_bfe_u32 v16, v9, 16, 1
	v_add3_u32 v16, v9, v16, s91
	v_add3_u32 v9, v13, v15, s91
	v_add3_u32 v7, v7, v14, s91
	v_add3_u32 v0, v11, v0, s91
	v_bfe_u32 v11, v8, 16, 1
	v_bfe_u32 v14, v6, 16, 1
	v_bfe_u32 v15, v10, 16, 1
	v_add3_u32 v10, v10, v15, s91
	v_add3_u32 v6, v6, v14, s91
	v_add3_u32 v8, v8, v11, s91
	v_lshrrev_b32_e32 v11, 16, v8
	v_lshrrev_b32_e32 v6, 16, v6
	v_lshrrev_b32_e32 v8, 16, v10
	v_lshl_or_b32 v10, s6, 2, v27
	v_and_or_b32 v6, v7, s33, v6
	v_and_or_b32 v7, v16, s33, v11
	v_ashrrev_i32_e32 v11, 31, v10
	v_bfe_u32 v13, v12, 16, 1
	v_lshlrev_b64 v[10:11], 15, v[10:11]
	v_add3_u32 v12, v12, v13, s91
	v_lshl_add_u64 v[10:11], s[10:11], 0, v[10:11]
	s_lshl_b32 s94, s1, 7
	v_lshrrev_b32_e32 v12, 16, v12
	v_and_or_b32 v8, v0, s33, v8
	v_lshl_add_u64 v[10:11], v[10:11], 0, s[94:95]
	v_lshlrev_b32_e32 v0, 1, v2
	v_and_or_b32 v9, v9, s33, v12
	v_lshl_add_u64 v[10:11], v[10:11], 0, v[0:1]
	flat_store_dwordx4 v[10:11], v[6:9]
	s_branch .LBB0_555

.LBB0_568:
	s_nop 1
	global_load_dword v102, v[8:9], off
	v_ashrrev_i32_e32 v11, 31, v10
	v_lshl_add_u64 v[14:15], v[10:11], 2, s[2:3]
	flat_load_dword v11, v[14:15]
	v_add_u32_e32 v7, 8, v7
	v_add_u32_e32 v10, 0x200, v10
	s_waitcnt vmcnt(0) lgkmcnt(0)
	v_mul_f32_e32 v14, v11, v11
	ds_bpermute_b32 v14, v5, v14
	s_waitcnt lgkmcnt(0)
	v_fmac_f32_e32 v14, v11, v11
	ds_bpermute_b32 v15, v88, v14
	s_waitcnt lgkmcnt(0)
	v_add_f32_e32 v14, v14, v15
	ds_bpermute_b32 v15, v89, v14
	s_waitcnt lgkmcnt(0)
	v_add_f32_e32 v14, v14, v15
	ds_bpermute_b32 v15, v90, v14
	s_waitcnt lgkmcnt(0)
	v_add_f32_e32 v14, v14, v15
	ds_bpermute_b32 v15, v91, v14
	s_waitcnt lgkmcnt(0)
	v_add_f32_e32 v14, v14, v15
	ds_bpermute_b32 v15, v92, v14
	s_waitcnt lgkmcnt(0)
	v_add_f32_e32 v14, v14, v15
	v_fmamk_f32 v14, v14, 0x3c800000, v219
	v_cmp_gt_f32_e32 vcc, s85, v14
	v_mul_f32_e32 v15, 0x4f800000, v14
	s_nop 0
	v_cndmask_b32_e32 v14, v14, v15, vcc
	v_sqrt_f32_e32 v15, v14
	s_nop 0
	v_add_u32_e32 v16, -1, v15
	v_fma_f32 v17, -v16, v15, v14
	v_cmp_ge_f32_e64 s[6:7], 0, v17
	v_add_u32_e32 v17, 1, v15
	s_nop 0
	v_cndmask_b32_e64 v16, v15, v16, s[6:7]
	v_fma_f32 v15, -v17, v15, v14
	v_cmp_lt_f32_e64 s[6:7], 0, v15
	s_nop 1
	v_cndmask_b32_e64 v15, v16, v17, s[6:7]
	v_mul_f32_e32 v16, 0x37800000, v15
	v_cndmask_b32_e32 v15, v15, v16, vcc
	v_cmp_class_f32_e32 vcc, v14, v221
	s_nop 1
	v_cndmask_b32_e32 v14, v15, v14, vcc
	v_div_scale_f32 v15, s[6:7], v14, v14, 1.0
	v_rcp_f32_e32 v16, v15
	s_nop 0
	v_fma_f32 v17, -v15, v16, 1.0
	v_fmac_f32_e32 v16, v17, v16
	v_div_scale_f32 v17, vcc, 1.0, v14, 1.0
	v_mul_f32_e32 v18, v17, v16
	v_fma_f32 v19, -v15, v18, v17
	v_fmac_f32_e32 v18, v19, v16
	v_fma_f32 v15, -v15, v18, v17
	v_div_fmas_f32 v15, v15, v16, v18
	v_div_fixup_f32 v14, v15, v14, 1.0
	v_mul_f32_e32 v11, v11, v14
	s_waitcnt vmcnt(0)
	s_nop 0
	v_mov_b32_e32 v14, v102
	s_nop 1
	v_cmp_lt_i32_e32 vcc, -5, v7
	s_or_b64 s[20:21], vcc, s[20:21]
	s_waitcnt vmcnt(0) lgkmcnt(0)
	v_mul_f32_e32 v11, v14, v11
	v_mul_f32_e32 v11, 0x3e000000, v11
	ds_write_b32 v13, v11
	v_add_u32_e32 v13, 0x800, v13
	s_andn2_b64 exec, exec, s[20:21]
	s_cbranch_execnz .LBB0_568

.LBB0_602:
	s_and_b64 vcc, exec, s[0:1]
	s_cbranch_vccz .LBB0_633
	v_readlane_b32 s0, v254, 4
	v_readlane_b32 s1, v254, 19
	v_bfe_u32 v3, v2, 3, 6
	v_mov_b32_e32 v0, s0
	ds_read_b64 v[10:11], v0
	s_add_i32 s0, s28, 0xfffffa00
	s_lshl_b32 s94, s0, 6
	s_add_i32 s0, s0, s24
	v_mov_b32_e32 v0, s1
	s_ashr_i32 s1, s0, 31
	s_waitcnt lgkmcnt(0)
	v_readfirstlane_b32 s15, v10
	s_lshl_b64 s[0:1], s[0:1], 14
	v_readfirstlane_b32 s17, v11
	s_add_u32 s0, s15, s0
	ds_read2_b64 v[6:9], v0 offset1:1
	s_addc_u32 s1, s17, s1
	v_lshlrev_b32_e32 v0, 7, v3
	v_lshl_add_u64 v[10:11], s[0:1], 0, v[0:1]
	v_lshlrev_b32_e32 v0, 4, v2
	v_and_b32_e32 v0, 0x70, v0
	v_lshl_add_u64 v[10:11], v[10:11], 0, v[0:1]
	s_mov_b64 s[0:1], 0x9d00000
	s_nop 1
	v_lshl_add_u64 v[102:103], v[10:11], 0, s[0:1]
	v_add_u32_e32 v104, 0x200, v2
	v_ashrrev_i32_e32 v106, 9, v104
	v_lshlrev_b32_e32 v104, 12, v106
	v_ashrrev_i32_e32 v105, 31, v104
	v_lshl_add_u64 v[102:103], v[104:105], 1, v[102:103]
	global_load_dwordx4 v[108:111], v[102:103], off
	v_ashrrev_i32_e32 v18, 9, v2
	v_lshl_add_u64 v[14:15], v[10:11], 0, s[0:1]
	v_lshlrev_b32_e32 v10, 12, v18
	v_ashrrev_i32_e32 v11, 31, v10
	v_lshl_add_u64 v[10:11], v[10:11], 1, v[14:15]
	flat_load_dwordx4 v[10:13], v[10:11]
	v_add_u32_e32 v16, 0x200, v2
	v_mul_u32_u24_e32 v3, 0x90, v3
	v_ashrrev_i32_e32 v19, 9, v16
	v_readlane_b32 s0, v254, 20
	v_lshlrev_b32_e32 v16, 12, v19
	v_ashrrev_i32_e32 v17, 31, v16
	v_add3_u32 v0, s0, v3, v0
	s_movk_i32 s0, 0x2400
	v_mad_i32_i24 v3, v18, s0, v0
	v_lshl_add_u64 v[14:15], v[16:17], 1, v[14:15]
	s_waitcnt lgkmcnt(0)
	v_readfirstlane_b32 s2, v6
	v_readfirstlane_b32 s3, v7
	v_readfirstlane_b32 s6, v8
	v_readfirstlane_b32 s7, v9
	v_mad_i32_i24 v0, v19, s0, v0
	v_cmp_gt_i32_e32 vcc, 64, v2
	s_waitcnt vmcnt(0)
	ds_write_b128 v3, v[10:13]
	s_waitcnt vmcnt(0)
	s_nop 0
	v_mov_b32_e32 v10, v108
	v_mov_b32_e32 v11, v109
	v_mov_b32_e32 v12, v110
	v_mov_b32_e32 v13, v111
	s_nop 1
	s_waitcnt vmcnt(0) lgkmcnt(0)
	ds_write_b128 v0, v[10:13]
	s_and_saveexec_b64 s[0:1], vcc
	s_cbranch_execz .LBB0_605
	v_readlane_b32 s4, v254, 21
	s_add_i32 s20, s94, s10
	s_nop 0
	v_mov_b32_e32 v0, s4
	ds_read_b128 v[6:9], v0
	s_waitcnt lgkmcnt(0)
	v_readfirstlane_b32 s4, v8
	v_add_u32_e32 v8, s20, v2
	v_readfirstlane_b32 s5, v9
	v_ashrrev_i32_e32 v9, 31, v8
	v_lshlrev_b64 v[8:9], 2, v[8:9]
	v_lshl_add_u64 v[10:11], s[4:5], 0, v[8:9]
	flat_load_dword v0, v[10:11]
	s_mov_b32 s4, 0xbfb8aa3b
	s_waitcnt vmcnt(0) lgkmcnt(0)
	v_mul_f32_e32 v3, 0xbfb8aa3b, v0
	v_fma_f32 v10, v0, s4, -v3
	v_rndne_f32_e32 v11, v3
	v_fmac_f32_e32 v10, 0xb2a5705f, v0
	v_sub_f32_e32 v3, v3, v11
	v_add_f32_e32 v3, v3, v10
	v_exp_f32_e32 v3, v3
	v_cvt_i32_f32_e32 v10, v11
	s_mov_b32 s4, 0x42ce8ed0
	v_cmp_nlt_f32_e32 vcc, s4, v0
	s_mov_b32 s4, 0xc2b17218
	v_ldexp_f32 v3, v3, v10
	v_cndmask_b32_e32 v3, 0, v3, vcc
	v_cmp_ngt_f32_e32 vcc, s4, v0
	s_mov_b32 s4, 0x3f2aaaab
	s_nop 0
	v_cndmask_b32_e32 v0, v228, v3, vcc
	v_add_f32_e32 v3, 1.0, v0
	v_add_f32_e32 v10, -1.0, v3
	v_sub_f32_e32 v11, v10, v3
	v_add_f32_e32 v11, 1.0, v11
	v_sub_f32_e32 v10, v0, v10
	v_add_f32_e32 v12, v10, v11
	v_frexp_mant_f32_e32 v10, v3
	v_cmp_gt_f32_e32 vcc, s4, v10
	v_cvt_f64_f32_e32 v[10:11], v3
	v_frexp_exp_i32_f64_e32 v10, v[10:11]
	v_subbrev_co_u32_e32 v10, vcc, 0, v10, vcc
	v_sub_u32_e32 v11, 0, v10
	v_ldexp_f32 v3, v3, v11
	v_ldexp_f32 v11, v12, v11
	v_add_f32_e32 v12, -1.0, v3
	v_add_f32_e32 v13, 1.0, v12
	v_sub_f32_e32 v13, v3, v13
	v_add_f32_e32 v13, v11, v13
	v_add_f32_e32 v14, v12, v13
	v_sub_f32_e32 v12, v12, v14
	v_add_f32_e32 v12, v13, v12
	v_add_f32_e32 v13, 1.0, v3
	v_add_f32_e32 v15, -1.0, v13
	v_sub_f32_e32 v3, v3, v15
	v_add_f32_e32 v3, v11, v3
	v_add_f32_e32 v11, v13, v3
	v_sub_f32_e32 v13, v13, v11
	v_add_f32_e32 v3, v3, v13
	v_rcp_f32_e32 v13, v11
	v_cvt_f32_i32_e32 v10, v10
	s_mov_b32 s4, 0x3f317218
	v_mul_f32_e32 v15, v14, v13
	v_mul_f32_e32 v16, v11, v15
	v_fma_f32 v17, v15, v11, -v16
	v_fmac_f32_e32 v17, v15, v3
	v_add_f32_e32 v18, v16, v17
	v_sub_f32_e32 v19, v14, v18
	v_sub_f32_e32 v14, v14, v19
	v_sub_f32_e32 v16, v18, v16
	v_sub_f32_e32 v14, v14, v18
	v_add_f32_e32 v12, v12, v14
	v_sub_f32_e32 v14, v16, v17
	v_add_f32_e32 v12, v14, v12
	v_add_f32_e32 v14, v19, v12
	v_mul_f32_e32 v16, v13, v14
	v_mul_f32_e32 v17, v11, v16
	v_fma_f32 v11, v16, v11, -v17
	v_fmac_f32_e32 v11, v16, v3
	v_sub_f32_e32 v3, v19, v14
	v_add_f32_e32 v3, v12, v3
	v_add_f32_e32 v12, v17, v11
	v_sub_f32_e32 v18, v14, v12
	v_sub_f32_e32 v14, v14, v18
	v_sub_f32_e32 v17, v12, v17
	v_sub_f32_e32 v12, v14, v12
	v_add_f32_e32 v3, v3, v12
	v_sub_f32_e32 v11, v17, v11
	v_add_f32_e32 v3, v11, v3
	v_add_f32_e32 v11, v15, v16
	v_add_f32_e32 v3, v18, v3
	v_sub_f32_e32 v12, v11, v15
	v_mul_f32_e32 v3, v13, v3
	v_sub_f32_e32 v12, v16, v12
	v_add_f32_e32 v3, v12, v3
	v_mul_f32_e32 v15, 0x3f317218, v10
	v_add_f32_e32 v12, v11, v3
	v_fma_f32 v16, v10, s4, -v15
	v_mul_f32_e32 v13, v12, v12
	v_fmac_f32_e32 v16, 0xb102e308, v10
	v_sub_f32_e32 v10, v12, v11
	v_fmamk_f32 v14, v13, 0x3e9b6dac, v222
	v_sub_f32_e32 v3, v3, v10
	v_add_f32_e32 v10, v15, v16
	v_fmaak_f32 v14, v13, v14, 0x3f2aaada
	v_sub_f32_e32 v11, v10, v15
	v_ldexp_f32 v15, v12, 1
	v_mul_f32_e32 v12, v12, v13
	v_mul_f32_e32 v12, v12, v14
	v_add_f32_e32 v13, v15, v12
	v_sub_f32_e32 v14, v13, v15
	v_ldexp_f32 v3, v3, 1
	v_sub_f32_e32 v12, v12, v14
	v_add_f32_e32 v3, v3, v12
	v_add_f32_e32 v12, v13, v3
	v_sub_f32_e32 v13, v12, v13
	v_sub_f32_e32 v3, v3, v13
	v_add_f32_e32 v13, v10, v12
	v_sub_f32_e32 v14, v13, v10
	v_sub_f32_e32 v15, v13, v14
	v_sub_f32_e32 v11, v16, v11
	v_sub_f32_e32 v10, v10, v15
	v_sub_f32_e32 v12, v12, v14
	v_add_f32_e32 v10, v12, v10
	v_add_f32_e32 v12, v11, v3
	v_sub_f32_e32 v14, v12, v11
	v_sub_f32_e32 v15, v12, v14
	v_sub_f32_e32 v11, v11, v15
	v_sub_f32_e32 v3, v3, v14
	v_add_f32_e32 v10, v12, v10
	v_add_f32_e32 v3, v3, v11
	v_add_f32_e32 v11, v13, v10
	v_sub_f32_e32 v12, v11, v13
	v_sub_f32_e32 v10, v10, v12
	v_add_f32_e32 v3, v3, v10
	s_mov_b32 s4, 0x7f800000
	v_add_f32_e32 v3, v11, v3
	v_cmp_neq_f32_e32 vcc, s4, v0
	s_mov_b32 s4, 0x33800000
	s_nop 0
	v_cndmask_b32_e32 v3, v228, v3, vcc
	v_cmp_lt_f32_e64 vcc, |v0|, s4
	v_readlane_b32 s4, v254, 22
	s_nop 0
	v_cndmask_b32_e32 v0, v3, v0, vcc
	v_xor_b32_e32 v3, 0x80000000, v0
	v_lshl_add_u32 v0, v2, 2, 0
	v_add_u32_e32 v0, 0x22500, v0
	ds_write_b32 v0, v3
	v_mov_b32_e32 v3, s4
	ds_read_b64 v[10:11], v3
	s_waitcnt lgkmcnt(0)
	v_readfirstlane_b32 s4, v10
	v_readfirstlane_b32 s5, v11
	s_nop 1
	v_lshl_add_u64 v[10:11], s[4:5], 0, v[8:9]
	flat_load_dword v3, v[10:11]
	v_readfirstlane_b32 s4, v6
	v_readfirstlane_b32 s5, v7
	s_nop 1
	v_lshl_add_u64 v[102:103], s[4:5], 0, v[8:9]
	global_load_dword v104, v[102:103], off
	s_waitcnt vmcnt(0) lgkmcnt(0)
	ds_write_b32 v0, v3 offset:256
	v_lshl_add_u64 v[6:7], s[4:5], 0, v[8:9]
	s_waitcnt vmcnt(0)
	s_nop 0
	v_mov_b32_e32 v3, v104
	s_nop 1
	s_waitcnt vmcnt(0) lgkmcnt(0)
	ds_write_b32 v0, v3 offset:512

.LBB0_607:
	s_nop 1
	global_load_dword v106, v[16:17], off
	s_nop 1
	global_load_dword v105, v[14:15], off
	s_nop 1
	global_load_dword v104, v[12:13], off offset:3072
	s_nop 1
	global_load_dword v103, v[12:13], off
	s_nop 1
	global_load_dword v102, v[10:11], off
	v_ashrrev_i32_e32 v24, 6, v19
	s_waitcnt lgkmcnt(0)
	v_readfirstlane_b32 s29, v6
	v_readfirstlane_b32 s30, v7
	v_add_u32_e32 v25, s25, v24
	v_mov_b32_e32 v22, s29
	v_mov_b32_e32 v23, s30
	v_mad_i64_i32 v[22:23], s[30:31], v25, s35, v[22:23]
	v_lshl_add_u64 v[22:23], v[22:23], 0, s[2:3]
	v_lshl_add_u64 v[22:23], v[22:23], 0, v[0:1]
	s_movk_i32 s29, 0x1000
	flat_load_dword v26, v[22:23]
	flat_load_dword v28, v[22:23] offset:3072
	v_add_co_u32_e32 v22, vcc, s29, v22
	s_waitcnt lgkmcnt(0)
	v_readfirstlane_b32 s29, v8
	v_addc_co_u32_e32 v23, vcc, 0, v23, vcc
	flat_load_dword v29, v[22:23] offset:2048
	v_mad_i64_i32 v[22:23], s[30:31], v24, s34, v[20:21]
	flat_load_dword v30, v[22:23] offset:3072
	s_nop 0
	s_waitcnt vmcnt(0)
	s_nop 0
	v_mov_b32_e32 v22, v102
	s_nop 1
	s_waitcnt vmcnt(0)
	s_nop 0
	v_mov_b32_e32 v23, v103
	s_nop 1
	s_waitcnt vmcnt(0) lgkmcnt(0)
	v_fmac_f32_e32 v22, v26, v23
	s_waitcnt vmcnt(0)
	s_nop 0
	v_mov_b32_e32 v23, v104
	s_nop 1
	s_waitcnt vmcnt(0) lgkmcnt(0)
	v_fmac_f32_e32 v22, v28, v23
	s_waitcnt vmcnt(0)
	s_nop 0
	v_mov_b32_e32 v23, v105
	s_nop 1
	s_waitcnt vmcnt(0) lgkmcnt(0)
	v_fmac_f32_e32 v22, v29, v23
	s_waitcnt vmcnt(0)
	s_nop 0
	v_mov_b32_e32 v23, v106
	s_nop 1
	s_waitcnt vmcnt(0) lgkmcnt(0)
	v_fmac_f32_e32 v22, v30, v23
	v_bfe_u32 v23, v22, 16, 1
	ds_write_b32 v3, v22
	v_add3_u32 v26, v22, v23, s91
	v_mad_u64_u32 v[22:23], s[30:31], v24, s88, v[18:19]
	v_readfirstlane_b32 s30, v9
	ds_write_b16_d16_hi v22, v26
	v_mov_b32_e32 v22, s29
	v_mov_b32_e32 v23, s30
	v_mad_i64_i32 v[22:23], s[30:31], v25, s35, v[22:23]
	v_lshl_add_u64 v[22:23], v[22:23], 0, s[2:3]
	v_lshl_add_u64 v[22:23], v[22:23], 0, v[0:1]
	v_add_co_u32_e32 v26, vcc, 0x4b18000, v22
	s_mov_b64 s[30:31], 0x4b18000
	s_nop 0
	v_addc_co_u32_e32 v27, vcc, 0, v23, vcc
	v_lshl_add_u64 v[24:25], v[22:23], 0, s[30:31]
	v_add_co_u32_e32 v22, vcc, 0x4b19000, v22
	flat_store_dword v[26:27], v28
	flat_store_dword v[24:25], v29 offset:3072
	v_addc_co_u32_e32 v23, vcc, 0, v23, vcc
	flat_store_dword v[22:23], v30 offset:2048
	v_add_u32_e32 v22, 0x200, v19
	v_cmp_lt_i32_e32 vcc, s36, v19
	v_add_u32_e32 v3, 0x800, v3
	s_or_b64 s[6:7], vcc, s[6:7]
	v_mov_b32_e32 v19, v22
	s_andn2_b64 exec, exec, s[6:7]
	s_cbranch_execnz .LBB0_607

.LBB0_613:
	v_readlane_b32 s0, v254, 4
	s_mul_hi_i32 s2, s28, 0x2aaaaaab
	s_lshr_b32 s3, s2, 31
	v_mov_b32_e32 v0, s0
	s_ashr_i32 s15, s2, 1
	ds_read_b64 v[10:11], v0
	s_add_i32 s15, s15, s3
	s_mul_i32 s2, s15, 12
	s_sub_i32 s4, s28, s2
	s_lshl_b32 s2, s4, 6
	s_add_i32 s4, s4, s24
	v_readlane_b32 s0, v254, 19
	s_ashr_i32 s5, s4, 31
	s_ashr_i32 s3, s2, 31
	v_mov_b32_e32 v0, s0
	s_waitcnt lgkmcnt(0)
	v_readfirstlane_b32 s0, v10
	s_lshl_b64 s[4:5], s[4:5], 14
	v_readfirstlane_b32 s1, v11
	s_add_u32 s4, s0, s4
	v_bfe_u32 v16, v2, 3, 6
	ds_read2_b64 v[6:9], v0 offset1:1
	s_addc_u32 s5, s1, s5
	v_lshlrev_b32_e32 v0, 7, v16
	v_lshl_add_u64 v[10:11], s[4:5], 0, v[0:1]
	v_lshlrev_b32_e32 v0, 3, v2
	v_and_b32_e32 v3, 56, v0
	v_lshlrev_b32_e32 v62, 1, v3
	v_mov_b32_e32 v63, v1
	v_lshl_add_u64 v[10:11], v[10:11], 0, v[62:63]
	s_mov_b64 s[4:5], 0x9d00000
	s_nop 1
	v_lshl_add_u64 v[102:103], v[10:11], 0, s[4:5]
	v_add_u32_e32 v105, 0x200, v2
	v_ashrrev_i32_e32 v106, 9, v105
	v_lshlrev_b32_e32 v104, 12, v106
	v_ashrrev_i32_e32 v105, 31, v104
	v_lshl_add_u64 v[102:103], v[104:105], 1, v[102:103]
	global_load_dwordx4 v[108:111], v[102:103], off
	v_ashrrev_i32_e32 v0, 9, v2
	v_lshl_add_u64 v[14:15], v[10:11], 0, s[4:5]
	v_lshlrev_b32_e32 v10, 12, v0
	v_ashrrev_i32_e32 v11, 31, v10
	v_lshl_add_u64 v[10:11], v[10:11], 1, v[14:15]
	flat_load_dwordx4 v[10:13], v[10:11]
	v_add_u32_e32 v17, 0x200, v2
	v_mul_u32_u24_e32 v18, 0x90, v16
	v_ashrrev_i32_e32 v19, 9, v17
	v_readlane_b32 s4, v254, 20
	v_lshlrev_b32_e32 v16, 12, v19
	v_ashrrev_i32_e32 v17, 31, v16
	v_add3_u32 v18, s4, v18, v62
	s_movk_i32 s4, 0x2400
	v_mad_i32_i24 v0, v0, s4, v18
	v_lshl_add_u64 v[14:15], v[16:17], 1, v[14:15]
	s_waitcnt lgkmcnt(0)
	v_readfirstlane_b32 s17, v6
	v_readfirstlane_b32 s20, v7
	v_readfirstlane_b32 s21, v8
	v_readfirstlane_b32 s29, v9
	v_cmp_gt_i32_e32 vcc, 64, v2
	s_waitcnt vmcnt(0)
	ds_write_b128 v0, v[10:13]
	s_waitcnt vmcnt(0)
	s_nop 0
	v_mov_b32_e32 v10, v108
	v_mov_b32_e32 v11, v109
	v_mov_b32_e32 v12, v110
	v_mov_b32_e32 v13, v111
	s_nop 1
	v_mad_i32_i24 v0, v19, s4, v18
	s_waitcnt vmcnt(0) lgkmcnt(0)
	ds_write_b128 v0, v[10:13]
	s_and_saveexec_b64 s[4:5], vcc
	s_cbranch_execz .LBB0_615
	v_readlane_b32 s6, v254, 21
	s_add_i32 s30, s2, s10
	s_nop 0
	v_mov_b32_e32 v0, s6
	ds_read_b128 v[6:9], v0
	s_waitcnt lgkmcnt(0)
	v_readfirstlane_b32 s6, v8
	v_add_u32_e32 v8, s30, v2
	v_readfirstlane_b32 s7, v9
	v_ashrrev_i32_e32 v9, 31, v8
	v_lshlrev_b64 v[8:9], 2, v[8:9]
	v_lshl_add_u64 v[10:11], s[6:7], 0, v[8:9]
	flat_load_dword v0, v[10:11]
	s_mov_b32 s6, 0xbfb8aa3b
	s_waitcnt vmcnt(0) lgkmcnt(0)
	v_mul_f32_e32 v10, 0xbfb8aa3b, v0
	v_fma_f32 v11, v0, s6, -v10
	v_rndne_f32_e32 v12, v10
	v_fmac_f32_e32 v11, 0xb2a5705f, v0
	v_sub_f32_e32 v10, v10, v12
	v_add_f32_e32 v10, v10, v11
	v_exp_f32_e32 v10, v10
	v_cvt_i32_f32_e32 v11, v12
	s_mov_b32 s6, 0x42ce8ed0
	v_cmp_nlt_f32_e32 vcc, s6, v0
	s_mov_b32 s6, 0xc2b17218
	v_ldexp_f32 v10, v10, v11
	v_cndmask_b32_e32 v10, 0, v10, vcc
	v_cmp_ngt_f32_e32 vcc, s6, v0
	s_mov_b32 s6, 0x3f2aaaab
	s_nop 0
	v_cndmask_b32_e32 v0, v228, v10, vcc
	v_add_f32_e32 v12, 1.0, v0
	v_add_f32_e32 v10, -1.0, v12
	v_sub_f32_e32 v11, v10, v12
	v_add_f32_e32 v11, 1.0, v11
	v_sub_f32_e32 v10, v0, v10
	v_add_f32_e32 v13, v10, v11
	v_frexp_mant_f32_e32 v10, v12
	v_cmp_gt_f32_e32 vcc, s6, v10
	v_cvt_f64_f32_e32 v[10:11], v12
	v_frexp_exp_i32_f64_e32 v10, v[10:11]
	v_subbrev_co_u32_e32 v10, vcc, 0, v10, vcc
	v_sub_u32_e32 v11, 0, v10
	v_ldexp_f32 v12, v12, v11
	v_ldexp_f32 v11, v13, v11
	v_add_f32_e32 v13, -1.0, v12
	v_add_f32_e32 v14, 1.0, v13
	v_sub_f32_e32 v14, v12, v14
	v_add_f32_e32 v14, v11, v14
	v_add_f32_e32 v15, v13, v14
	v_sub_f32_e32 v13, v13, v15
	v_add_f32_e32 v13, v14, v13
	v_add_f32_e32 v14, 1.0, v12
	v_add_f32_e32 v16, -1.0, v14
	v_sub_f32_e32 v12, v12, v16
	v_add_f32_e32 v11, v11, v12
	v_add_f32_e32 v12, v14, v11
	v_sub_f32_e32 v14, v14, v12
	v_add_f32_e32 v11, v11, v14
	v_rcp_f32_e32 v14, v12
	v_cvt_f32_i32_e32 v10, v10
	s_mov_b32 s6, 0x3f317218
	v_mul_f32_e32 v16, v15, v14
	v_mul_f32_e32 v17, v12, v16
	v_fma_f32 v18, v16, v12, -v17
	v_fmac_f32_e32 v18, v16, v11
	v_add_f32_e32 v19, v17, v18
	v_sub_f32_e32 v20, v15, v19
	v_sub_f32_e32 v15, v15, v20
	v_sub_f32_e32 v17, v19, v17
	v_sub_f32_e32 v15, v15, v19
	v_add_f32_e32 v13, v13, v15
	v_sub_f32_e32 v15, v17, v18
	v_add_f32_e32 v13, v15, v13
	v_add_f32_e32 v15, v20, v13
	v_mul_f32_e32 v17, v14, v15
	v_mul_f32_e32 v18, v12, v17
	v_fma_f32 v12, v17, v12, -v18
	v_fmac_f32_e32 v12, v17, v11
	v_sub_f32_e32 v11, v20, v15
	v_add_f32_e32 v11, v13, v11
	v_add_f32_e32 v13, v18, v12
	v_sub_f32_e32 v19, v15, v13
	v_sub_f32_e32 v15, v15, v19
	v_sub_f32_e32 v18, v13, v18
	v_sub_f32_e32 v13, v15, v13
	v_add_f32_e32 v11, v11, v13
	v_sub_f32_e32 v12, v18, v12
	v_add_f32_e32 v11, v12, v11
	v_add_f32_e32 v12, v16, v17
	v_add_f32_e32 v11, v19, v11
	v_sub_f32_e32 v13, v12, v16
	v_mul_f32_e32 v11, v14, v11
	v_sub_f32_e32 v13, v17, v13
	v_add_f32_e32 v11, v13, v11
	v_mul_f32_e32 v16, 0x3f317218, v10
	v_add_f32_e32 v13, v12, v11
	v_fma_f32 v17, v10, s6, -v16
	v_mul_f32_e32 v14, v13, v13
	v_fmac_f32_e32 v17, 0xb102e308, v10
	v_sub_f32_e32 v10, v13, v12
	v_fmamk_f32 v15, v14, 0x3e9b6dac, v222
	v_sub_f32_e32 v10, v11, v10
	v_add_f32_e32 v11, v16, v17
	v_fmaak_f32 v15, v14, v15, 0x3f2aaada
	v_sub_f32_e32 v12, v11, v16
	v_ldexp_f32 v16, v13, 1
	v_mul_f32_e32 v13, v13, v14
	v_mul_f32_e32 v13, v13, v15
	v_add_f32_e32 v14, v16, v13
	v_sub_f32_e32 v15, v14, v16
	v_ldexp_f32 v10, v10, 1
	v_sub_f32_e32 v13, v13, v15
	v_add_f32_e32 v10, v10, v13
	v_add_f32_e32 v13, v14, v10
	v_sub_f32_e32 v14, v13, v14
	v_sub_f32_e32 v10, v10, v14
	v_add_f32_e32 v14, v11, v13
	v_sub_f32_e32 v15, v14, v11
	v_sub_f32_e32 v16, v14, v15
	v_sub_f32_e32 v12, v17, v12
	v_sub_f32_e32 v11, v11, v16
	v_sub_f32_e32 v13, v13, v15
	v_add_f32_e32 v11, v13, v11
	v_add_f32_e32 v13, v12, v10
	v_sub_f32_e32 v15, v13, v12
	v_sub_f32_e32 v16, v13, v15
	v_sub_f32_e32 v12, v12, v16
	v_sub_f32_e32 v10, v10, v15
	v_add_f32_e32 v11, v13, v11
	v_add_f32_e32 v10, v10, v12
	v_add_f32_e32 v12, v14, v11
	v_sub_f32_e32 v13, v12, v14
	v_sub_f32_e32 v11, v11, v13
	v_add_f32_e32 v10, v10, v11
	s_mov_b32 s6, 0x7f800000
	v_add_f32_e32 v10, v12, v10
	v_cmp_neq_f32_e32 vcc, s6, v0
	s_mov_b32 s6, 0x33800000
	s_nop 0
	v_cndmask_b32_e32 v10, v228, v10, vcc
	v_cmp_lt_f32_e64 vcc, |v0|, s6
	v_readlane_b32 s6, v254, 22
	s_nop 0
	v_cndmask_b32_e32 v0, v10, v0, vcc
	v_xor_b32_e32 v10, 0x80000000, v0
	v_lshl_add_u32 v0, v2, 2, 0
	v_add_u32_e32 v0, 0x22500, v0
	ds_write_b32 v0, v10
	v_mov_b32_e32 v10, s6
	ds_read_b64 v[10:11], v10
	s_waitcnt lgkmcnt(0)
	v_readfirstlane_b32 s6, v10
	v_readfirstlane_b32 s7, v11
	s_nop 1
	v_lshl_add_u64 v[10:11], s[6:7], 0, v[8:9]
	flat_load_dword v10, v[10:11]
	v_readfirstlane_b32 s6, v6
	v_readfirstlane_b32 s7, v7
	s_nop 1
	v_lshl_add_u64 v[102:103], s[6:7], 0, v[8:9]
	global_load_dword v104, v[102:103], off
	s_waitcnt vmcnt(0) lgkmcnt(0)
	ds_write_b32 v0, v10 offset:256
	v_lshl_add_u64 v[6:7], s[6:7], 0, v[8:9]
	s_waitcnt vmcnt(0)
	s_nop 0
	v_mov_b32_e32 v6, v104
	s_nop 1
	s_waitcnt vmcnt(0) lgkmcnt(0)
	ds_write_b32 v0, v6 offset:512
